# v30 + priority 3 around the remaining LDS-DMA issue groups (tile prologues and the unrolled short-K loops of ret_scores / ret_o / gm_spatial / rw_gemm2)
# baseline (speedup 1.0000x reference)
.LBB0_302:
	s_mul_i32 s1, s10, s9
	s_sub_i32 s1, s11, s1
	s_add_i32 s8, s8, s1
	s_lshl_b32 s38, s8, 7
	s_lshl_b32 s40, s10, 7
	s_lshl_b32 s11, s0, 1
	s_add_u32 s8, s86, s11
	s_addc_u32 s9, s87, 0
	s_ashr_i32 s39, s38, 31
	s_lshl_b64 s[0:1], s[38:39], 11
	s_add_u32 s8, s8, s0
	s_addc_u32 s9, s9, s1
	v_lshl_add_u64 v[0:1], v[72:73], 1, s[8:9]
	v_readfirstlane_b32 s8, v84
	v_add_u32_e32 v6, 0x1000, v84
	v_lshl_add_u64 v[0:1], v[0:1], 0, v[68:69]
	s_mov_b32 m0, s8
	s_mov_b64 s[18:19], 0x10000
	v_readfirstlane_b32 s8, v6
	v_add_u32_e32 v6, 0x2000, v84
	s_setprio 3
	global_load_lds_dwordx4 v[0:1], off
	v_lshl_add_u64 v[4:5], v[0:1], 0, s[18:19]
	s_mov_b32 m0, s8
	v_readfirstlane_b32 s8, v6
	global_load_lds_dwordx4 v[4:5], off
	v_lshl_add_u64 v[4:5], v[0:1], 0, s[28:29]
	s_mov_b32 m0, s8
	s_mov_b64 s[22:23], 0x30000
	global_load_lds_dwordx4 v[4:5], off
	v_add_u32_e32 v4, 0x3000, v84
	v_lshl_add_u64 v[0:1], v[0:1], 0, s[22:23]
	v_readfirstlane_b32 s8, v4
	s_mov_b32 m0, s8
	s_ashr_i32 s41, s40, 31
	global_load_lds_dwordx4 v[0:1], off
	v_add_u32_e32 v0, 0x8000, v84
	s_lshl_b64 s[12:13], s[40:41], 11
	v_readfirstlane_b32 s8, v0
	v_add_u32_e32 v4, 0x9000, v84
	v_lshl_add_u64 v[2:3], v[74:75], 0, s[12:13]
	s_mov_b32 m0, s8
	v_readfirstlane_b32 s8, v4
	v_add_u32_e32 v4, 0xa000, v84
	global_load_lds_dwordx4 v[2:3], off
	v_lshl_add_u64 v[0:1], v[2:3], 0, s[18:19]
	s_mov_b32 m0, s8
	v_readfirstlane_b32 s8, v4
	global_load_lds_dwordx4 v[0:1], off
	v_lshl_add_u64 v[0:1], v[2:3], 0, s[28:29]
	s_mov_b32 m0, s8
	s_add_u32 s0, s0, s11
	global_load_lds_dwordx4 v[0:1], off
	v_lshl_add_u64 v[0:1], v[2:3], 0, s[22:23]
	v_add_u32_e32 v2, 0xb000, v84
	s_addc_u32 s1, s1, 0
	v_readfirstlane_b32 s8, v2
	s_mov_b32 m0, s8
	v_lshl_add_u64 v[78:79], v[76:77], 0, s[0:1]
	global_load_lds_dwordx4 v[0:1], off
	s_setprio 0
	s_waitcnt vmcnt(0)
	v_mov_b32_e32 v0, 0
	v_lshl_add_u64 v[80:81], v[76:77], 0, s[12:13]
	s_mov_b32 s0, 0
	v_mov_b32_e32 v1, v0
	v_mov_b32_e32 v2, v0
	v_mov_b32_e32 v3, v0
	v_mov_b32_e32 v4, v0
	v_mov_b32_e32 v5, v0
	v_mov_b32_e32 v6, v0
	v_mov_b32_e32 v7, v0
	v_mov_b32_e32 v8, v0
	v_mov_b32_e32 v9, v0
	v_mov_b32_e32 v10, v0
	v_mov_b32_e32 v11, v0
	v_mov_b32_e32 v12, v0
	v_mov_b32_e32 v13, v0
	v_mov_b32_e32 v14, v0
	v_mov_b32_e32 v15, v0
	v_mov_b32_e32 v16, v0
	v_mov_b32_e32 v17, v0
	v_mov_b32_e32 v18, v0
	v_mov_b32_e32 v19, v0
	v_mov_b32_e32 v20, v0
	v_mov_b32_e32 v21, v0
	v_mov_b32_e32 v22, v0
	v_mov_b32_e32 v23, v0
	v_mov_b32_e32 v24, v0
	v_mov_b32_e32 v25, v0
	v_mov_b32_e32 v26, v0
	v_mov_b32_e32 v27, v0
	v_mov_b32_e32 v28, v0
	v_mov_b32_e32 v29, v0
	v_mov_b32_e32 v30, v0
	v_mov_b32_e32 v31, v0
	v_mov_b32_e32 v32, v0
	v_mov_b32_e32 v33, v0
	v_mov_b32_e32 v34, v0
	v_mov_b32_e32 v35, v0
	v_mov_b32_e32 v36, v0
	v_mov_b32_e32 v37, v0
	v_mov_b32_e32 v38, v0
	v_mov_b32_e32 v39, v0
	v_mov_b32_e32 v40, v0
	v_mov_b32_e32 v41, v0
	v_mov_b32_e32 v42, v0
	v_mov_b32_e32 v43, v0
	v_mov_b32_e32 v44, v0
	v_mov_b32_e32 v45, v0
	v_mov_b32_e32 v46, v0
	v_mov_b32_e32 v47, v0
	v_mov_b32_e32 v48, v0
	v_mov_b32_e32 v49, v0
	v_mov_b32_e32 v50, v0
	v_mov_b32_e32 v51, v0
	v_mov_b32_e32 v52, v0
	v_mov_b32_e32 v53, v0
	v_mov_b32_e32 v54, v0
	v_mov_b32_e32 v55, v0
	v_mov_b32_e32 v56, v0
	v_mov_b32_e32 v57, v0
	v_mov_b32_e32 v58, v0
	v_mov_b32_e32 v59, v0
	v_mov_b32_e32 v60, v0
	v_mov_b32_e32 v61, v0
	v_mov_b32_e32 v62, v0
	v_mov_b32_e32 v63, v0
	v_lshl_add_u64 v[82:83], v[78:79], 0, s[20:21]
	s_mov_b64 s[8:9], 0xf500080
	v_lshl_add_u64 v[96:97], v[82:83], 0, s[8:9]
	s_mov_b64 s[8:9], 0xf510080
	v_mov_b32_e32 v184, v96
	v_mov_b32_e32 v185, v97
	v_lshl_add_u64 v[96:97], v[82:83], 0, s[8:9]
	s_mov_b64 s[8:9], 0xf520080
	v_mov_b32_e32 v186, v96
	v_mov_b32_e32 v187, v97
	v_lshl_add_u64 v[96:97], v[82:83], 0, s[8:9]
	s_mov_b64 s[8:9], 0xf530080
	v_mov_b32_e32 v188, v96
	v_mov_b32_e32 v189, v97
	v_lshl_add_u64 v[82:83], v[82:83], 0, s[8:9]
	s_mov_b64 s[8:9], 0x3040080
	v_mov_b32_e32 v190, v82
	v_mov_b32_e32 v191, v83
	v_lshl_add_u64 v[82:83], v[80:81], 0, s[20:21]
	v_lshl_add_u64 v[96:97], v[82:83], 0, s[8:9]
	s_mov_b64 s[8:9], 0x3050080
	v_mov_b32_e32 v192, v96
	v_mov_b32_e32 v193, v97
	v_lshl_add_u64 v[96:97], v[82:83], 0, s[8:9]
	s_mov_b64 s[8:9], 0x3060080
	v_mov_b32_e32 v194, v96
	v_mov_b32_e32 v195, v97
	v_lshl_add_u64 v[96:97], v[82:83], 0, s[8:9]
	s_mov_b64 s[8:9], 0x3070080
	v_lshl_add_u64 v[82:83], v[82:83], 0, s[8:9]
	v_mov_b32_e32 v196, v96
	v_mov_b32_e32 v197, v97
	v_mov_b32_e32 v198, v82
	v_mov_b32_e32 v199, v83
	v_readfirstlane_b32 s100, v84
	s_mov_b64 vcc, 0x80
	s_waitcnt vmcnt(0) lgkmcnt(0)
	s_barrier

.LBB0_648:
	s_and_b32 s0, s10, 7
	s_mulk_i32 s0, 0x210
	s_ashr_i32 s1, s10, 3
	s_add_i32 s11, s0, s1
	s_mul_hi_i32 s0, s11, 0x3e0f83e1
	s_lshr_b32 s1, s0, 31
	s_ashr_i32 s0, s0, 8
	s_add_i32 s20, s0, s1
	s_mul_i32 s0, s20, 0x420
	s_sub_i32 s1, s11, s0
	s_lshl_b32 s0, s1, 4
	s_and_b32 s0, s0, 0xffffff80
	s_lshl_b32 s1, s1, 7
	s_and_b32 s18, s1, 0x380
	s_ashr_i32 s1, s0, 31
	s_lshl_b64 s[8:9], s[0:1], 9
	v_readlane_b32 s12, v182, 27
	v_readlane_b32 s13, v182, 28
	s_add_u32 s1, s12, s8
	s_addc_u32 s12, s13, s9
	s_lshl_b32 s8, s20, 6
	s_ashr_i32 s9, s8, 31
	s_lshl_b64 s[8:9], s[8:9], 1
	s_add_u32 s8, s1, s8
	s_addc_u32 s9, s12, s9
	s_ashr_i32 s21, s20, 31
	s_lshl_b64 s[12:13], s[20:21], 17
	v_readlane_b32 s1, v183, 55
	s_add_u32 s1, s1, s12
	v_readlane_b32 s12, v183, 56
	s_addc_u32 s13, s12, s13
	s_lshl_b32 s12, s18, 7
	s_add_u32 s12, s1, s12
	v_lshl_add_u64 v[0:1], s[8:9], 0, v[72:73]
	v_readfirstlane_b32 s1, v92
	v_add_u32_e32 v6, 0x1000, v92
	v_lshl_add_u64 v[0:1], v[0:1], 0, v[68:69]
	s_mov_b32 m0, s1
	s_mov_b64 s[8:9], 0x4000
	v_readfirstlane_b32 s1, v6
	v_add_u32_e32 v6, 0x2000, v92
	s_setprio 3
	global_load_lds_dwordx4 v[0:1], off
	v_lshl_add_u64 v[4:5], v[0:1], 0, s[8:9]
	s_mov_b32 m0, s1
	s_mov_b64 s[8:9], 0x8000
	v_readfirstlane_b32 s1, v6
	global_load_lds_dwordx4 v[4:5], off
	v_lshl_add_u64 v[4:5], v[0:1], 0, s[8:9]
	s_mov_b32 m0, s1
	s_mov_b64 s[8:9], 0xc000
	global_load_lds_dwordx4 v[4:5], off
	v_add_u32_e32 v4, 0x3000, v92
	v_lshl_add_u64 v[0:1], v[0:1], 0, s[8:9]
	v_readfirstlane_b32 s1, v4
	s_mov_b32 m0, s1
	s_addc_u32 s13, s13, 0
	global_load_lds_dwordx4 v[0:1], off
	v_add_u32_e32 v0, 0x8000, v92
	v_lshl_add_u64 v[2:3], s[12:13], 0, v[74:75]
	v_readfirstlane_b32 s1, v0
	v_add_u32_e32 v4, 0x9000, v92
	v_lshl_add_u64 v[2:3], v[2:3], 0, v[68:69]
	s_mov_b32 m0, s1
	s_mov_b64 s[8:9], 0x1000
	v_readfirstlane_b32 s1, v4
	v_add_u32_e32 v4, 0xa000, v92
	global_load_lds_dwordx4 v[2:3], off
	v_lshl_add_u64 v[0:1], v[2:3], 0, s[8:9]
	s_mov_b32 m0, s1
	s_mov_b64 s[8:9], 0x2000
	v_readfirstlane_b32 s1, v4
	global_load_lds_dwordx4 v[0:1], off
	v_lshl_add_u64 v[0:1], v[2:3], 0, s[8:9]
	s_mov_b32 m0, s1
	s_mov_b64 s[8:9], 0x3000
	global_load_lds_dwordx4 v[0:1], off
	v_lshl_add_u64 v[0:1], v[2:3], 0, s[8:9]
	v_add_u32_e32 v2, 0xb000, v92
	s_nop 0
	v_readfirstlane_b32 s1, v2
	s_mov_b32 m0, s1
	s_nop 0
	global_load_lds_dwordx4 v[0:1], off
	s_setprio 0
	s_waitcnt vmcnt(0)
	s_waitcnt vmcnt(0) lgkmcnt(0)
	s_barrier
	ds_read_b128 v[0:3], v88
	ds_read_b128 v[4:7], v88 offset:2048
	ds_read_b128 v[8:11], v88 offset:4096
	ds_read_b128 v[12:15], v88 offset:6144
	ds_read_b128 v[16:19], v89 offset:32768
	ds_read_b128 v[20:23], v89 offset:34816
	ds_read_b128 v[24:27], v89 offset:36864
	ds_read_b128 v[28:31], v89 offset:38912
	s_setprio 1
	s_waitcnt lgkmcnt(3)
	v_mfma_f32_16x16x32_bf16 v[32:35], v[16:19], v[0:3], 0
	s_waitcnt lgkmcnt(2)
	v_mfma_f32_16x16x32_bf16 v[36:39], v[20:23], v[0:3], 0
	s_waitcnt lgkmcnt(1)
	v_mfma_f32_16x16x32_bf16 v[40:43], v[24:27], v[0:3], 0
	s_waitcnt lgkmcnt(0)
	v_mfma_f32_16x16x32_bf16 v[0:3], v[28:31], v[0:3], 0
	v_mfma_f32_16x16x32_bf16 v[48:51], v[16:19], v[4:7], 0
	v_mfma_f32_16x16x32_bf16 v[52:55], v[20:23], v[4:7], 0
	v_mfma_f32_16x16x32_bf16 v[56:59], v[24:27], v[4:7], 0
	v_mfma_f32_16x16x32_bf16 v[4:7], v[28:31], v[4:7], 0
	v_mfma_f32_16x16x32_bf16 v[76:79], v[16:19], v[8:11], 0
	v_mfma_f32_16x16x32_bf16 v[80:83], v[20:23], v[8:11], 0
	v_mfma_f32_16x16x32_bf16 v[16:19], v[16:19], v[12:15], 0
	v_mfma_f32_16x16x32_bf16 v[94:97], v[24:27], v[8:11], 0
	v_mfma_f32_16x16x32_bf16 v[98:101], v[28:31], v[8:11], 0
	v_mfma_f32_16x16x32_bf16 v[120:123], v[20:23], v[12:15], 0
	v_mfma_f32_16x16x32_bf16 v[124:127], v[24:27], v[12:15], 0
	v_mfma_f32_16x16x32_bf16 v[128:131], v[28:31], v[12:15], 0
	s_setprio 0
	ds_read_b128 v[8:11], v90
	ds_read_b128 v[20:23], v90 offset:2048
	ds_read_b128 v[132:135], v90 offset:4096
	ds_read_b128 v[136:139], v90 offset:6144
	ds_read_b128 v[140:143], v91 offset:32768
	ds_read_b128 v[144:147], v91 offset:34816
	ds_read_b128 v[148:151], v91 offset:36864
	ds_read_b128 v[152:155], v91 offset:38912
	s_setprio 1
	s_waitcnt lgkmcnt(3)
	v_mfma_f32_16x16x32_bf16 v[156:159], v[140:143], v[8:11], v[32:35]
	s_waitcnt lgkmcnt(2)
	v_mfma_f32_16x16x32_bf16 v[44:47], v[144:147], v[8:11], v[36:39]
	s_waitcnt lgkmcnt(1)
	v_mfma_f32_16x16x32_bf16 v[28:31], v[148:151], v[8:11], v[40:43]
	s_waitcnt lgkmcnt(0)
	v_mfma_f32_16x16x32_bf16 v[12:15], v[152:155], v[8:11], v[0:3]
	v_mfma_f32_16x16x32_bf16 v[60:63], v[140:143], v[20:23], v[48:51]
	v_mfma_f32_16x16x32_bf16 v[40:43], v[144:147], v[20:23], v[52:55]
	v_mfma_f32_16x16x32_bf16 v[24:27], v[148:151], v[20:23], v[56:59]
	v_mfma_f32_16x16x32_bf16 v[8:11], v[152:155], v[20:23], v[4:7]
	v_mfma_f32_16x16x32_bf16 v[56:59], v[140:143], v[132:135], v[76:79]
	v_mfma_f32_16x16x32_bf16 v[36:39], v[144:147], v[132:135], v[80:83]
	v_mfma_f32_16x16x32_bf16 v[20:23], v[148:151], v[132:135], v[94:97]
	v_mfma_f32_16x16x32_bf16 v[4:7], v[152:155], v[132:135], v[98:101]
	v_mfma_f32_16x16x32_bf16 v[48:51], v[140:143], v[136:139], v[16:19]
	v_mfma_f32_16x16x32_bf16 v[32:35], v[144:147], v[136:139], v[120:123]
	v_mfma_f32_16x16x32_bf16 v[16:19], v[148:151], v[136:139], v[124:127]
	v_mfma_f32_16x16x32_bf16 v[0:3], v[152:155], v[136:139], v[128:131]
	s_setprio 0
	s_and_b32 s1, s20, 1
	s_cmpk_gt_i32 s11, 0x83f
	s_cselect_b64 s[24:25], -1, 0
	s_cmpk_lt_i32 s11, 0x840
	s_cselect_b64 s[36:37], -1, 0
	v_readlane_b32 s40, v183, 35
	s_and_b64 s[8:9], s[36:37], exec
	v_readlane_b32 s44, v183, 39
	v_readlane_b32 s45, v183, 40
	v_readlane_b32 s50, v183, 45
	v_readlane_b32 s51, v183, 46
	s_cselect_b32 s8, s45, s51
	s_cselect_b32 s9, s44, s50
	s_lshl_b32 s11, s1, 12
	s_add_u32 s20, s9, s11
	v_or_b32_e32 v79, s18, v87
	s_addc_u32 s21, s8, 0
	v_lshlrev_b32_e32 v78, 2, v79
	s_waitcnt vmcnt(0)
	s_barrier
	global_load_dwordx4 v[52:55], v78, s[20:21]
	global_load_dwordx4 v[184:187], v78, s[20:21] offset:64
	global_load_dwordx4 v[188:191], v78, s[20:21] offset:128
	global_load_dwordx4 v[192:195], v78, s[20:21] offset:192
	s_mov_b64 s[8:9], -1
	s_and_b64 vcc, exec, s[24:25]
	v_readlane_b32 s41, v183, 36
	v_readlane_b32 s42, v183, 37
	v_readlane_b32 s43, v183, 38
	v_readlane_b32 s46, v183, 41
	v_readlane_b32 s47, v183, 42
	v_readlane_b32 s48, v183, 43
	v_readlane_b32 s49, v183, 44
	v_readlane_b32 s52, v183, 47
	v_readlane_b32 s53, v183, 48
	v_readlane_b32 s54, v183, 49
	v_readlane_b32 s55, v183, 50
	s_waitcnt vmcnt(0)
	v_add_f32_e32 v76, v156, v52
	v_mul_f32_e32 v76, 0xbfb8aa3b, v76
	v_exp_f32_e32 v76, v76
	v_add_f32_e32 v77, v157, v53
	v_add_f32_e32 v80, v158, v54
	v_add_f32_e32 v81, v159, v55
	v_mul_f32_e32 v77, 0xbfb8aa3b, v77
	v_mul_f32_e32 v80, 0xbfb8aa3b, v80
	v_mul_f32_e32 v83, 0xbfb8aa3b, v81
	v_add_f32_e32 v76, 1.0, v76
	v_exp_f32_e32 v82, v77
	v_exp_f32_e32 v81, v80
	v_rcp_f32_e32 v76, v76
	v_exp_f32_e32 v80, v83
	s_cbranch_vccz .LBB0_650
	v_add_f32_e32 v77, 1.0, v82
	v_rcp_f32_e32 v84, v77
	v_add_f32_e32 v77, 1.0, v81
	v_rcp_f32_e32 v85, v77
	v_add_f32_e32 v77, 1.0, v80
	v_rcp_f32_e32 v77, v77
	s_mov_b64 s[8:9], 0

.LBB0_881:
	s_and_b32 s0, s12, 7
	v_readlane_b32 s8, v180, 8
	s_mul_i32 s0, s0, s8
	s_ashr_i32 s1, s12, 3
	s_add_i32 s0, s0, s1
	s_ashr_i32 s1, s0, 31
	s_lshr_b32 s1, s1, 26
	s_add_i32 s1, s0, s1
	s_ashr_i32 s6, s1, 6
	s_lshl_b32 s6, s6, 3
	s_sub_i32 s8, s8, s6
	s_min_i32 s8, s8, 8
	s_abs_i32 s9, s8
	v_cvt_f32_u32_e32 v0, s9
	s_sub_i32 s11, 0, s9
	s_andn2_b32 s1, s1, 63
	s_sub_i32 s0, s0, s1
	v_rcp_iflag_f32_e32 v0, v0
	s_abs_i32 s1, s0
	s_xor_b32 s10, s0, s8
	s_ashr_i32 s10, s10, 31
	v_mul_f32_e32 v0, 0x4f7ffffe, v0
	v_cvt_u32_f32_e32 v0, v0
	v_add_u32_e32 v6, 0x1000, v68
	s_mov_b64 s[22:23], 0x10000
	s_mov_b64 s[36:37], 0x30000
	v_readfirstlane_b32 s13, v0
	s_mul_i32 s11, s11, s13
	s_mul_hi_u32 s11, s13, s11
	s_add_i32 s13, s13, s11
	s_mul_hi_u32 s11, s1, s13
	s_mul_i32 s13, s11, s9
	s_sub_i32 s1, s1, s13
	s_add_i32 s18, s11, 1
	s_sub_i32 s13, s1, s9
	s_cmp_ge_u32 s1, s9
	s_cselect_b32 s11, s18, s11
	s_cselect_b32 s1, s13, s1
	s_add_i32 s13, s11, 1
	s_cmp_ge_u32 s1, s9
	s_cselect_b32 s1, s13, s11
	s_xor_b32 s1, s1, s10
	s_sub_i32 s9, s1, s10
	s_mul_i32 s1, s9, s8
	s_sub_i32 s0, s0, s1
	s_add_i32 s1, s6, s0
	s_lshl_b32 s24, s1, 7
	s_ashr_i32 s25, s24, 31
	s_lshl_b32 s20, s9, 7
	s_lshl_b64 s[8:9], s[24:25], 11
	v_readfirstlane_b32 s0, v68
	v_lshl_add_u64 v[0:1], v[72:73], 0, s[8:9]
	s_mov_b32 m0, s0
	v_readfirstlane_b32 s0, v6
	v_add_u32_e32 v6, 0x2000, v68
	s_setprio 3
	global_load_lds_dwordx4 v[0:1], off
	v_lshl_add_u64 v[4:5], v[0:1], 0, s[22:23]
	s_mov_b32 m0, s0
	v_readfirstlane_b32 s0, v6
	global_load_lds_dwordx4 v[4:5], off
	v_lshl_add_u64 v[4:5], v[0:1], 0, s[28:29]
	s_mov_b32 m0, s0
	v_lshl_add_u64 v[0:1], v[0:1], 0, s[36:37]
	global_load_lds_dwordx4 v[4:5], off
	v_add_u32_e32 v4, 0x3000, v68
	s_ashr_i32 s21, s20, 31
	v_readfirstlane_b32 s0, v4
	s_mov_b32 m0, s0
	s_lshl_b64 s[10:11], s[20:21], 11
	global_load_lds_dwordx4 v[0:1], off
	v_add_u32_e32 v0, 0x8000, v68
	v_add_u32_e32 v4, 0x9000, v68
	v_readfirstlane_b32 s0, v0
	v_lshl_add_u64 v[2:3], v[74:75], 0, s[10:11]
	s_mov_b32 m0, s0
	v_readfirstlane_b32 s0, v4
	v_add_u32_e32 v4, 0xa000, v68
	global_load_lds_dwordx4 v[2:3], off
	v_lshl_add_u64 v[0:1], v[2:3], 0, s[22:23]
	s_mov_b32 m0, s0
	v_readfirstlane_b32 s0, v4
	global_load_lds_dwordx4 v[0:1], off
	v_lshl_add_u64 v[0:1], v[2:3], 0, s[28:29]
	s_mov_b32 m0, s0
	v_lshl_add_u64 v[86:87], v[84:85], 0, s[8:9]
	global_load_lds_dwordx4 v[0:1], off
	v_lshl_add_u64 v[0:1], v[2:3], 0, s[36:37]
	v_add_u32_e32 v2, 0xb000, v68
	v_lshl_add_u64 v[88:89], v[84:85], 0, s[10:11]
	v_readfirstlane_b32 s0, v2
	s_mov_b32 m0, s0
	s_mov_b32 s0, 0
	global_load_lds_dwordx4 v[0:1], off
	s_setprio 0
	s_waitcnt vmcnt(0)
	v_mov_b32_e32 v0, 0
	s_mov_b64 s[36:37], 0
	v_mov_b32_e32 v1, v0
	v_mov_b32_e32 v2, v0
	v_mov_b32_e32 v3, v0
	v_mov_b32_e32 v4, v0
	v_mov_b32_e32 v5, v0
	v_mov_b32_e32 v6, v0
	v_mov_b32_e32 v7, v0
	v_mov_b32_e32 v8, v0
	v_mov_b32_e32 v9, v0
	v_mov_b32_e32 v10, v0
	v_mov_b32_e32 v11, v0
	v_mov_b32_e32 v12, v0
	v_mov_b32_e32 v13, v0
	v_mov_b32_e32 v14, v0
	v_mov_b32_e32 v15, v0
	v_mov_b32_e32 v16, v0
	v_mov_b32_e32 v17, v0
	v_mov_b32_e32 v18, v0
	v_mov_b32_e32 v19, v0
	v_mov_b32_e32 v20, v0
	v_mov_b32_e32 v21, v0
	v_mov_b32_e32 v22, v0
	v_mov_b32_e32 v23, v0
	v_mov_b32_e32 v24, v0
	v_mov_b32_e32 v25, v0
	v_mov_b32_e32 v26, v0
	v_mov_b32_e32 v27, v0
	v_mov_b32_e32 v28, v0
	v_mov_b32_e32 v29, v0
	v_mov_b32_e32 v30, v0
	v_mov_b32_e32 v31, v0
	v_mov_b32_e32 v32, v0
	v_mov_b32_e32 v33, v0
	v_mov_b32_e32 v34, v0
	v_mov_b32_e32 v35, v0
	v_mov_b32_e32 v36, v0
	v_mov_b32_e32 v37, v0
	v_mov_b32_e32 v38, v0
	v_mov_b32_e32 v39, v0
	v_mov_b32_e32 v40, v0
	v_mov_b32_e32 v41, v0
	v_mov_b32_e32 v42, v0
	v_mov_b32_e32 v43, v0
	v_mov_b32_e32 v44, v0
	v_mov_b32_e32 v45, v0
	v_mov_b32_e32 v46, v0
	v_mov_b32_e32 v47, v0
	v_mov_b32_e32 v48, v0
	v_mov_b32_e32 v49, v0
	v_mov_b32_e32 v50, v0
	v_mov_b32_e32 v51, v0
	v_mov_b32_e32 v52, v0
	v_mov_b32_e32 v53, v0
	v_mov_b32_e32 v54, v0
	v_mov_b32_e32 v55, v0
	v_mov_b32_e32 v56, v0
	v_mov_b32_e32 v57, v0
	v_mov_b32_e32 v58, v0
	v_mov_b32_e32 v59, v0
	v_mov_b32_e32 v60, v0
	v_mov_b32_e32 v61, v0
	v_mov_b32_e32 v62, v0
	v_mov_b32_e32 v63, v0
	v_lshl_add_u64 v[98:99], v[86:87], 0, s[36:37]
	s_mov_b64 s[8:9], 0x1bb00080
	v_lshl_add_u64 v[100:101], v[98:99], 0, s[8:9]
	s_mov_b64 s[8:9], 0x1bb10080
	v_mov_b32_e32 v184, v100
	v_mov_b32_e32 v185, v101
	v_lshl_add_u64 v[100:101], v[98:99], 0, s[8:9]
	s_mov_b64 s[8:9], 0x1bb20080
	v_mov_b32_e32 v186, v100
	v_mov_b32_e32 v187, v101
	v_lshl_add_u64 v[100:101], v[98:99], 0, s[8:9]
	s_mov_b64 s[8:9], 0x1bb30080
	v_mov_b32_e32 v188, v100
	v_mov_b32_e32 v189, v101
	v_lshl_add_u64 v[98:99], v[98:99], 0, s[8:9]
	s_mov_b64 s[8:9], 0x3940080
	v_mov_b32_e32 v190, v98
	v_mov_b32_e32 v191, v99
	v_lshl_add_u64 v[98:99], v[88:89], 0, s[36:37]
	v_lshl_add_u64 v[100:101], v[98:99], 0, s[8:9]
	s_mov_b64 s[8:9], 0x3950080
	v_mov_b32_e32 v192, v100
	v_mov_b32_e32 v193, v101
	v_lshl_add_u64 v[100:101], v[98:99], 0, s[8:9]
	s_mov_b64 s[8:9], 0x3960080
	v_mov_b32_e32 v194, v100
	v_mov_b32_e32 v195, v101
	v_lshl_add_u64 v[100:101], v[98:99], 0, s[8:9]
	s_mov_b64 s[8:9], 0x3970080
	v_mov_b32_e32 v196, v100
	v_mov_b32_e32 v197, v101
	v_lshl_add_u64 v[98:99], v[98:99], 0, s[8:9]
	v_mov_b32_e32 v198, v98
	v_mov_b32_e32 v199, v99
	v_readfirstlane_b32 s100, v68
	s_mov_b64 vcc, 0x80
	s_waitcnt vmcnt(0) lgkmcnt(0)
	s_barrier

.LBB0_894:
	s_and_b32 s0, s6, 7
	s_mulk_i32 s0, 0x318
	s_ashr_i32 s1, s6, 3
	s_add_i32 s0, s0, s1
	s_mul_hi_i32 s1, s0, 0x2aaaaaab
	s_lshr_b32 s8, s1, 31
	s_ashr_i32 s1, s1, 6
	s_add_i32 s1, s1, s8
	s_lshl_b32 s9, s1, 3
	s_sub_i32 s8, 0x84, s9
	s_min_u32 s10, s8, 8
	v_cvt_f32_ubyte0_e32 v0, s10
	v_rcp_iflag_f32_e32 v0, v0
	s_sub_i32 s11, 0, s10
	s_mulk_i32 s1, 0xfe80
	s_add_i32 s1, s1, s0
	v_mul_f32_e32 v0, 0x4f7ffffe, v0
	v_cvt_u32_f32_e32 v0, v0
	s_abs_i32 s8, s1
	s_ashr_i32 s0, s1, 31
	v_add_u32_e32 v4, 0x1000, v71
	v_readfirstlane_b32 s12, v0
	s_mul_i32 s11, s11, s12
	s_mul_hi_u32 s11, s12, s11
	s_add_i32 s12, s12, s11
	s_mul_hi_u32 s11, s8, s12
	s_mul_i32 s12, s11, s10
	s_sub_i32 s8, s8, s12
	s_add_i32 s12, s11, 1
	s_sub_i32 s13, s8, s10
	s_cmp_ge_u32 s8, s10
	s_cselect_b32 s11, s12, s11
	s_cselect_b32 s8, s13, s8
	s_add_i32 s12, s11, 1
	s_cmp_ge_u32 s8, s10
	s_cselect_b32 s8, s12, s11
	s_xor_b32 s8, s8, s0
	s_sub_i32 s8, s8, s0
	s_mul_i32 s0, s8, s10
	s_sub_i32 s0, s1, s0
	s_add_i32 s9, s0, s9
	s_lshl_b32 s20, s9, 7
	s_ashr_i32 s21, s20, 31
	s_lshl_b64 s[0:1], s[20:21], 11
	v_readfirstlane_b32 s10, v71
	v_lshl_add_u64 v[0:1], v[72:73], 0, s[0:1]
	s_mov_b32 m0, s10
	s_mov_b64 s[12:13], 0x10000
	v_readfirstlane_b32 s10, v4
	v_add_u32_e32 v4, 0x2000, v71
	s_setprio 3
	global_load_lds_dwordx4 v[0:1], off
	v_lshl_add_u64 v[2:3], v[0:1], 0, s[12:13]
	s_mov_b32 m0, s10
	v_readfirstlane_b32 s10, v4
	global_load_lds_dwordx4 v[2:3], off
	v_lshl_add_u64 v[2:3], v[0:1], 0, s[28:29]
	s_mov_b32 m0, s10
	s_lshl_b32 s24, s8, 7
	global_load_lds_dwordx4 v[2:3], off
	v_add_u32_e32 v2, 0x3000, v71
	s_ashr_i32 s25, s24, 31
	s_mov_b64 s[22:23], 0x30000
	v_readfirstlane_b32 s10, v2
	v_add_u32_e32 v2, 0x8000, v71
	s_lshl_b64 s[38:39], s[24:25], 11
	v_lshl_add_u64 v[0:1], v[0:1], 0, s[22:23]
	s_mov_b32 m0, s10
	v_readfirstlane_b32 s10, v2
	v_add_u32_e32 v4, 0x9000, v71
	global_load_lds_dwordx4 v[0:1], off
	v_lshl_add_u64 v[0:1], v[74:75], 0, s[38:39]
	s_mov_b32 m0, s10
	v_readfirstlane_b32 s10, v4
	v_add_u32_e32 v4, 0xa000, v71
	global_load_lds_dwordx4 v[0:1], off
	v_lshl_add_u64 v[2:3], v[0:1], 0, s[12:13]
	s_mov_b32 m0, s10
	v_readfirstlane_b32 s10, v4
	global_load_lds_dwordx4 v[2:3], off
	v_lshl_add_u64 v[2:3], v[0:1], 0, s[28:29]
	s_mov_b32 m0, s10
	v_lshl_add_u64 v[0:1], v[0:1], 0, s[22:23]
	global_load_lds_dwordx4 v[2:3], off
	v_add_u32_e32 v2, 0xb000, v71
	s_mov_b64 s[36:37], 0
	v_readfirstlane_b32 s10, v2
	s_mov_b32 m0, s10
	s_mov_b32 s10, 0
	global_load_lds_dwordx4 v[0:1], off
	s_setprio 0
	s_waitcnt vmcnt(0)
	v_mov_b32_e32 v0, 0
	v_mov_b32_e32 v1, v0
	v_mov_b32_e32 v2, v0
	v_mov_b32_e32 v3, v0
	v_mov_b32_e32 v4, v0
	v_mov_b32_e32 v5, v0
	v_mov_b32_e32 v6, v0
	v_mov_b32_e32 v7, v0
	v_mov_b32_e32 v8, v0
	v_mov_b32_e32 v9, v0
	v_mov_b32_e32 v10, v0
	v_mov_b32_e32 v11, v0
	v_mov_b32_e32 v12, v0
	v_mov_b32_e32 v13, v0
	v_mov_b32_e32 v14, v0
	v_mov_b32_e32 v15, v0
	v_mov_b32_e32 v16, v0
	v_mov_b32_e32 v17, v0
	v_mov_b32_e32 v18, v0
	v_mov_b32_e32 v19, v0
	v_mov_b32_e32 v20, v0
	v_mov_b32_e32 v21, v0
	v_mov_b32_e32 v22, v0
	v_mov_b32_e32 v23, v0
	v_mov_b32_e32 v24, v0
	v_mov_b32_e32 v25, v0
	v_mov_b32_e32 v26, v0
	v_mov_b32_e32 v27, v0
	v_mov_b32_e32 v28, v0
	v_mov_b32_e32 v29, v0
	v_mov_b32_e32 v30, v0
	v_mov_b32_e32 v31, v0
	v_mov_b32_e32 v32, v0
	v_mov_b32_e32 v33, v0
	v_mov_b32_e32 v34, v0
	v_mov_b32_e32 v35, v0
	v_mov_b32_e32 v36, v0
	v_mov_b32_e32 v37, v0
	v_mov_b32_e32 v38, v0
	v_mov_b32_e32 v39, v0
	v_mov_b32_e32 v40, v0
	v_mov_b32_e32 v41, v0
	v_mov_b32_e32 v42, v0
	v_mov_b32_e32 v43, v0
	v_mov_b32_e32 v44, v0
	v_mov_b32_e32 v45, v0
	v_mov_b32_e32 v46, v0
	v_mov_b32_e32 v47, v0
	v_mov_b32_e32 v48, v0
	v_mov_b32_e32 v49, v0
	v_mov_b32_e32 v50, v0
	v_mov_b32_e32 v51, v0
	v_mov_b32_e32 v52, v0
	v_mov_b32_e32 v53, v0
	v_mov_b32_e32 v54, v0
	v_mov_b32_e32 v55, v0
	v_mov_b32_e32 v56, v0
	v_mov_b32_e32 v57, v0
	v_mov_b32_e32 v58, v0
	v_mov_b32_e32 v59, v0
	v_mov_b32_e32 v60, v0
	v_mov_b32_e32 v61, v0
	v_mov_b32_e32 v62, v0
	v_mov_b32_e32 v63, v0
	v_lshl_add_u64 v[82:83], v[78:79], 0, s[0:1]
	v_lshl_add_u64 v[84:85], v[80:81], 0, s[38:39]
	v_lshl_add_u64 v[86:87], v[82:83], 0, s[36:37]
	v_lshl_add_u64 v[88:89], v[86:87], 0, s[76:77]
	v_mov_b32_e32 v184, v88
	v_mov_b32_e32 v185, v89
	v_lshl_add_u64 v[88:89], v[86:87], 0, s[80:81]
	v_mov_b32_e32 v186, v88
	v_mov_b32_e32 v187, v89
	v_lshl_add_u64 v[88:89], v[86:87], 0, s[78:79]
	v_lshl_add_u64 v[86:87], v[86:87], 0, s[88:89]
	v_mov_b32_e32 v188, v88
	v_mov_b32_e32 v189, v89
	v_mov_b32_e32 v190, v86
	v_mov_b32_e32 v191, v87
	v_lshl_add_u64 v[86:87], v[84:85], 0, s[36:37]
	v_lshl_add_u64 v[88:89], v[86:87], 0, s[92:93]
	v_mov_b32_e32 v192, v88
	v_mov_b32_e32 v193, v89
	v_lshl_add_u64 v[88:89], v[86:87], 0, s[96:97]
	v_mov_b32_e32 v194, v88
	v_mov_b32_e32 v195, v89
	v_lshl_add_u64 v[88:89], v[86:87], 0, s[30:31]
	v_mov_b32_e32 v196, v88
	v_mov_b32_e32 v197, v89
	v_lshl_add_u64 v[86:87], v[86:87], 0, s[14:15]
	v_mov_b32_e32 v198, v86
	v_mov_b32_e32 v199, v87
	v_readfirstlane_b32 s100, v71
	s_mov_b64 vcc, 0x80
	s_waitcnt vmcnt(0) lgkmcnt(0)
	s_barrier

.LBB0_1238:
	s_bfe_u32 s11, s9, 0x20008
	s_lshl_b32 s10, s18, 6
	s_lshl_b32 s9, s11, 9
	s_and_b32 s10, s10, 0x180
	s_or_b32 s9, s9, s10
	s_and_b32 s19, s12, 0x300
	s_mul_i32 s9, s9, 0x8400
	v_readlane_b32 s20, v181, 46
	v_readlane_b32 s21, v181, 47
	s_add_u32 s20, s20, s9
	s_addc_u32 s21, s21, 0
	s_ashr_i32 s9, s8, 31
	s_lshl_b64 s[8:9], s[8:9], 1
	s_add_u32 s20, s20, s8
	s_addc_u32 s21, s21, s9
	s_and_b64 s[0:1], s[0:1], exec
	s_cselect_b32 s23, s91, s73
	s_cselect_b32 s22, s90, s72
	s_lshl_b32 s0, s18, 7
	s_lshl_b32 s1, s11, 8
	s_and_b32 s0, s0, 0x80
	s_or_b32 s1, s1, s0
	s_mul_i32 s1, s1, 0x8400
	s_add_u32 s1, s22, s1
	s_addc_u32 s37, s23, 0
	s_add_u32 s38, s1, s8
	v_lshl_add_u64 v[0:1], s[20:21], 0, v[76:77]
	v_readfirstlane_b32 s1, v82
	v_add_u32_e32 v6, 0x1000, v82
	s_addc_u32 s39, s37, s9
	v_lshl_add_u64 v[0:1], v[0:1], 0, v[68:69]
	s_mov_b32 m0, s1
	s_mov_b64 s[20:21], 0x108000
	v_readfirstlane_b32 s1, v6
	v_add_u32_e32 v6, 0x2000, v82
	v_lshl_add_u64 v[2:3], s[38:39], 0, v[76:77]
	s_setprio 3
	global_load_lds_dwordx4 v[0:1], off
	v_lshl_add_u64 v[4:5], v[0:1], 0, s[20:21]
	s_mov_b32 m0, s1
	s_mov_b64 s[38:39], 0x210000
	v_readfirstlane_b32 s1, v6
	global_load_lds_dwordx4 v[4:5], off
	v_lshl_add_u64 v[4:5], v[0:1], 0, s[38:39]
	s_mov_b32 m0, s1
	s_mov_b64 s[40:41], 0x318000
	global_load_lds_dwordx4 v[4:5], off
	v_add_u32_e32 v4, 0x3000, v82
	v_lshl_add_u64 v[0:1], v[0:1], 0, s[40:41]
	v_readfirstlane_b32 s1, v4
	s_mov_b32 m0, s1
	v_add_u32_e32 v4, 0x9000, v82
	global_load_lds_dwordx4 v[0:1], off
	v_add_u32_e32 v0, 0x8000, v82
	v_lshl_add_u64 v[2:3], v[2:3], 0, v[68:69]
	v_readfirstlane_b32 s1, v0
	s_mov_b32 m0, s1
	v_readfirstlane_b32 s1, v4
	v_add_u32_e32 v4, 0xa000, v82
	global_load_lds_dwordx4 v[2:3], off
	v_lshl_add_u64 v[0:1], v[2:3], 0, s[20:21]
	s_mov_b32 m0, s1
	v_readfirstlane_b32 s1, v4
	global_load_lds_dwordx4 v[0:1], off
	v_lshl_add_u64 v[0:1], v[2:3], 0, s[38:39]
	s_mov_b32 m0, s1
	s_add_i32 s19, s18, s19
	global_load_lds_dwordx4 v[0:1], off
	v_lshl_add_u64 v[0:1], v[2:3], 0, s[40:41]
	v_add_u32_e32 v2, 0xb000, v82
	s_bfe_u32 s20, s19, 0x20008
	v_readfirstlane_b32 s1, v2
	s_mov_b32 m0, s1
	s_bfe_u32 s18, s18, 0x20001
	global_load_lds_dwordx4 v[0:1], off
	s_setprio 0
	s_mul_i32 s19, s20, 0x840000
	s_mul_i32 s18, s18, 0x210000
	s_lshl_b32 s1, s36, 7
	s_add_i32 s19, s19, s18
	s_add_u32 s1, s1, 0x80
	s_lshl_b32 s18, s19, 1
	s_add_u32 s18, s8, s18
	s_addc_u32 s19, s9, 0
	v_lshl_add_u64 v[78:79], v[74:75], 0, s[18:19]
	s_bfe_u32 s19, s6, 0x10003
	s_mul_i32 s18, s20, 0x420000
	s_mul_i32 s19, s19, 0x210000
	s_add_i32 s18, s18, s19
	s_lshl_b32 s18, s18, 1
	s_add_u32 s8, s8, s18
	s_waitcnt vmcnt(0)
	v_lshl_add_u64 v[0:1], s[22:23], 0, v[72:73]
	s_addc_u32 s9, s9, 0
	v_lshl_add_u64 v[80:81], v[0:1], 0, s[8:9]
	v_mov_b32_e32 v0, 0
	s_mov_b64 s[20:21], 0
	s_mov_b32 s8, 0
	v_mov_b32_e32 v1, v0
	v_mov_b32_e32 v2, v0
	v_mov_b32_e32 v3, v0
	v_mov_b32_e32 v4, v0
	v_mov_b32_e32 v5, v0
	v_mov_b32_e32 v6, v0
	v_mov_b32_e32 v7, v0
	v_mov_b32_e32 v8, v0
	v_mov_b32_e32 v9, v0
	v_mov_b32_e32 v10, v0
	v_mov_b32_e32 v11, v0
	v_mov_b32_e32 v12, v0
	v_mov_b32_e32 v13, v0
	v_mov_b32_e32 v14, v0
	v_mov_b32_e32 v15, v0
	v_mov_b32_e32 v16, v0
	v_mov_b32_e32 v17, v0
	v_mov_b32_e32 v18, v0
	v_mov_b32_e32 v19, v0
	v_mov_b32_e32 v20, v0
	v_mov_b32_e32 v21, v0
	v_mov_b32_e32 v22, v0
	v_mov_b32_e32 v23, v0
	v_mov_b32_e32 v24, v0
	v_mov_b32_e32 v25, v0
	v_mov_b32_e32 v26, v0
	v_mov_b32_e32 v27, v0
	v_mov_b32_e32 v28, v0
	v_mov_b32_e32 v29, v0
	v_mov_b32_e32 v30, v0
	v_mov_b32_e32 v31, v0
	v_mov_b32_e32 v32, v0
	v_mov_b32_e32 v33, v0
	v_mov_b32_e32 v34, v0
	v_mov_b32_e32 v35, v0
	v_mov_b32_e32 v36, v0
	v_mov_b32_e32 v37, v0
	v_mov_b32_e32 v38, v0
	v_mov_b32_e32 v39, v0
	v_mov_b32_e32 v40, v0
	v_mov_b32_e32 v41, v0
	v_mov_b32_e32 v42, v0
	v_mov_b32_e32 v43, v0
	v_mov_b32_e32 v44, v0
	v_mov_b32_e32 v45, v0
	v_mov_b32_e32 v46, v0
	v_mov_b32_e32 v47, v0
	v_mov_b32_e32 v48, v0
	v_mov_b32_e32 v49, v0
	v_mov_b32_e32 v50, v0
	v_mov_b32_e32 v51, v0
	v_mov_b32_e32 v52, v0
	v_mov_b32_e32 v53, v0
	v_mov_b32_e32 v54, v0
	v_mov_b32_e32 v55, v0
	v_mov_b32_e32 v56, v0
	v_mov_b32_e32 v57, v0
	v_mov_b32_e32 v58, v0
	v_mov_b32_e32 v59, v0
	v_mov_b32_e32 v60, v0
	v_mov_b32_e32 v61, v0
	v_mov_b32_e32 v62, v0
	v_mov_b32_e32 v63, v0
	v_lshl_add_u64 v[88:89], v[78:79], 0, s[20:21]
	s_mov_b64 s[18:19], 0xd400080
	v_lshl_add_u64 v[90:91], v[88:89], 0, s[18:19]
	s_mov_b64 s[18:19], 0xd508080
	v_mov_b32_e32 v184, v90
	v_mov_b32_e32 v185, v91
	v_lshl_add_u64 v[90:91], v[88:89], 0, s[18:19]
	s_mov_b64 s[18:19], 0xd610080
	v_mov_b32_e32 v186, v90
	v_mov_b32_e32 v187, v91
	v_lshl_add_u64 v[90:91], v[88:89], 0, s[18:19]
	s_mov_b64 s[18:19], 0xd718080
	v_mov_b32_e32 v188, v90
	v_mov_b32_e32 v189, v91
	v_lshl_add_u64 v[88:89], v[88:89], 0, s[18:19]
	v_mov_b32_e32 v190, v88
	v_mov_b32_e32 v191, v89
	v_lshl_add_u64 v[88:89], v[80:81], 0, s[20:21]
	v_lshl_add_u64 v[90:91], v[88:89], 0, s[92:93]
	s_mov_b64 s[18:19], 0x108080
	v_mov_b32_e32 v192, v90
	v_mov_b32_e32 v193, v91
	v_lshl_add_u64 v[90:91], v[88:89], 0, s[18:19]
	s_mov_b64 s[18:19], 0x210080
	v_mov_b32_e32 v194, v90
	v_mov_b32_e32 v195, v91
	v_lshl_add_u64 v[90:91], v[88:89], 0, s[18:19]
	s_mov_b64 s[18:19], 0x318080
	v_mov_b32_e32 v196, v90
	v_mov_b32_e32 v197, v91
	v_lshl_add_u64 v[88:89], v[88:89], 0, s[18:19]
	v_mov_b32_e32 v198, v88
	v_mov_b32_e32 v199, v89
	v_readfirstlane_b32 s100, v82
	s_mov_b64 vcc, 0x80
	s_waitcnt vmcnt(0) lgkmcnt(0)
	s_barrier

.LBB0_1295:
	s_lshl_b32 s1, s12, 7
	s_add_i32 s12, s18, s1
	s_and_b32 s0, s13, s11
	s_ashr_i32 s13, s12, 31
	s_and_b32 s11, s10, 3
	s_lshl_b64 s[12:13], s[12:13], 11
	s_add_u32 s12, s2, s12
	s_addc_u32 s13, s3, s13
	s_lshl_b32 s21, s11, 9
	s_add_u32 s12, s12, s21
	s_addc_u32 s13, s13, 0
	s_lshl_b32 s0, s0, 7
	s_add_i32 s18, s18, s0
	s_ashr_i32 s19, s18, 31
	s_lshl_b64 s[18:19], s[18:19], 11
	v_readlane_b32 s22, v181, 42
	v_readlane_b32 s23, v181, 43
	s_add_u32 s18, s22, s18
	s_addc_u32 s19, s23, s19
	s_add_u32 s18, s18, s21
	v_lshl_add_u64 v[0:1], s[12:13], 0, v[72:73]
	v_readfirstlane_b32 s12, v94
	v_add_u32_e32 v4, 0x1000, v94
	s_addc_u32 s19, s19, 0
	v_lshl_add_u64 v[62:63], v[0:1], 0, v[68:69]
	s_mov_b32 m0, s12
	s_mov_b64 s[22:23], 0x10000
	v_readfirstlane_b32 s13, v4
	v_add_u32_e32 v4, 0x2000, v94
	v_lshl_add_u64 v[0:1], s[18:19], 0, v[72:73]
	s_setprio 3
	global_load_lds_dwordx4 v[62:63], off
	v_lshl_add_u64 v[2:3], v[62:63], 0, s[22:23]
	s_mov_b32 m0, s13
	v_readfirstlane_b32 s18, v4
	v_add_u32_e32 v4, 0x3000, v94
	global_load_lds_dwordx4 v[2:3], off
	v_lshl_add_u64 v[2:3], v[62:63], 0, s[28:29]
	s_mov_b32 m0, s18
	s_mov_b64 s[24:25], 0x30000
	v_readfirstlane_b32 s19, v4
	global_load_lds_dwordx4 v[2:3], off
	v_lshl_add_u64 v[2:3], v[62:63], 0, s[24:25]
	s_mov_b32 m0, s19
	v_lshl_add_u64 v[0:1], v[0:1], 0, v[68:69]
	global_load_lds_dwordx4 v[2:3], off
	v_add_u32_e32 v2, 0x8000, v94
	v_add_u32_e32 v4, 0x9000, v94
	v_readfirstlane_b32 s21, v2
	s_mov_b32 m0, s21
	v_lshl_add_u64 v[2:3], v[0:1], 0, s[22:23]
	v_readfirstlane_b32 s22, v4
	v_add_u32_e32 v4, 0xa000, v94
	global_load_lds_dwordx4 v[0:1], off
	s_mov_b32 m0, s22
	v_readfirstlane_b32 s23, v4
	global_load_lds_dwordx4 v[2:3], off
	v_lshl_add_u64 v[2:3], v[0:1], 0, s[28:29]
	s_mov_b32 m0, s23
	v_add_u32_e32 v4, 0xb000, v94
	global_load_lds_dwordx4 v[2:3], off
	v_lshl_add_u64 v[2:3], v[0:1], 0, s[24:25]
	v_readfirstlane_b32 s24, v4
	v_add_u32_e32 v4, 0x4000, v94
	s_mov_b32 m0, s24
	v_readfirstlane_b32 s25, v4
	v_add_u32_e32 v4, 0x5000, v94
	global_load_lds_dwordx4 v[2:3], off
	v_lshl_add_u64 v[2:3], v[62:63], 0, s[92:93]
	s_mov_b32 m0, s25
	v_readfirstlane_b32 s36, v4
	v_add_u32_e32 v4, 0x6000, v94
	s_waitcnt vmcnt(0)
	s_waitcnt vmcnt(0) lgkmcnt(0)
	s_barrier
	global_load_lds_dwordx4 v[2:3], off
	v_lshl_add_u64 v[2:3], v[62:63], 0, s[96:97]
	s_mov_b32 m0, s36
	v_readfirstlane_b32 s37, v4
	v_add_u32_e32 v4, 0x7000, v94
	global_load_lds_dwordx4 v[2:3], off
	v_lshl_add_u64 v[2:3], v[62:63], 0, s[30:31]
	s_mov_b32 m0, s37
	v_readfirstlane_b32 s38, v4
	v_add_u32_e32 v4, 0xc000, v94
	global_load_lds_dwordx4 v[2:3], off
	v_lshl_add_u64 v[2:3], v[62:63], 0, s[14:15]
	s_mov_b32 m0, s38
	v_readfirstlane_b32 s39, v4
	v_add_u32_e32 v4, 0xd000, v94
	global_load_lds_dwordx4 v[2:3], off
	v_lshl_add_u64 v[2:3], v[0:1], 0, s[92:93]
	s_mov_b32 m0, s39
	v_readfirstlane_b32 s40, v4
	v_add_u32_e32 v4, 0xe000, v94
	global_load_lds_dwordx4 v[2:3], off
	v_lshl_add_u64 v[2:3], v[0:1], 0, s[96:97]
	s_mov_b32 m0, s40
	v_readfirstlane_b32 s41, v4
	v_add_u32_e32 v4, 0xf000, v94
	global_load_lds_dwordx4 v[2:3], off
	v_lshl_add_u64 v[2:3], v[0:1], 0, s[30:31]
	s_mov_b32 m0, s41
	v_readfirstlane_b32 s42, v4
	global_load_lds_dwordx4 v[2:3], off
	v_lshl_add_u64 v[2:3], v[0:1], 0, s[14:15]
	s_mov_b32 m0, s42
	s_nop 0
	global_load_lds_dwordx4 v[2:3], off
	s_setprio 0
	ds_read_b128 v[2:5], v90
	ds_read_b128 v[6:9], v90 offset:2048
	ds_read_b128 v[10:13], v90 offset:4096
	ds_read_b128 v[14:17], v90 offset:6144
	ds_read_b128 v[18:21], v91 offset:32768
	ds_read_b128 v[22:25], v91 offset:34816
	ds_read_b128 v[26:29], v91 offset:36864
	ds_read_b128 v[30:33], v91 offset:38912
	s_setprio 1
	s_waitcnt lgkmcnt(0)
	v_mfma_f32_16x16x32_bf16 v[34:37], v[18:21], v[2:5], 0
	v_mfma_f32_16x16x32_bf16 v[38:41], v[22:25], v[2:5], 0
	v_mfma_f32_16x16x32_bf16 v[42:45], v[26:29], v[2:5], 0
	v_mfma_f32_16x16x32_bf16 v[2:5], v[30:33], v[2:5], 0
	v_mfma_f32_16x16x32_bf16 v[46:49], v[18:21], v[6:9], 0
	v_mfma_f32_16x16x32_bf16 v[50:53], v[22:25], v[6:9], 0
	v_mfma_f32_16x16x32_bf16 v[54:57], v[26:29], v[6:9], 0
	v_mfma_f32_16x16x32_bf16 v[6:9], v[30:33], v[6:9], 0
	v_mfma_f32_16x16x32_bf16 v[58:61], v[18:21], v[10:13], 0
	v_mfma_f32_16x16x32_bf16 v[74:77], v[22:25], v[10:13], 0
	v_mfma_f32_16x16x32_bf16 v[78:81], v[26:29], v[10:13], 0
	v_mfma_f32_16x16x32_bf16 v[10:13], v[30:33], v[10:13], 0
	v_mfma_f32_16x16x32_bf16 v[18:21], v[18:21], v[14:17], 0
	v_mfma_f32_16x16x32_bf16 v[22:25], v[22:25], v[14:17], 0
	v_mfma_f32_16x16x32_bf16 v[26:29], v[26:29], v[14:17], 0
	v_mfma_f32_16x16x32_bf16 v[14:17], v[30:33], v[14:17], 0
	s_setprio 0
	ds_read_b128 v[30:33], v92
	ds_read_b128 v[82:85], v92 offset:2048
	ds_read_b128 v[96:99], v92 offset:4096
	ds_read_b128 v[100:103], v92 offset:6144
	ds_read_b128 v[120:123], v93 offset:32768
	ds_read_b128 v[124:127], v93 offset:34816
	ds_read_b128 v[128:131], v93 offset:36864
	ds_read_b128 v[132:135], v93 offset:38912
	s_setprio 1
	s_waitcnt lgkmcnt(0)
	v_mfma_f32_16x16x32_bf16 v[34:37], v[120:123], v[30:33], v[34:37]
	v_mfma_f32_16x16x32_bf16 v[38:41], v[124:127], v[30:33], v[38:41]
	v_mfma_f32_16x16x32_bf16 v[42:45], v[128:131], v[30:33], v[42:45]
	v_mfma_f32_16x16x32_bf16 v[2:5], v[132:135], v[30:33], v[2:5]
	v_mfma_f32_16x16x32_bf16 v[30:33], v[120:123], v[82:85], v[46:49]
	v_mfma_f32_16x16x32_bf16 v[46:49], v[124:127], v[82:85], v[50:53]
	v_mfma_f32_16x16x32_bf16 v[50:53], v[128:131], v[82:85], v[54:57]
	v_mfma_f32_16x16x32_bf16 v[6:9], v[132:135], v[82:85], v[6:9]
	v_mfma_f32_16x16x32_bf16 v[54:57], v[120:123], v[96:99], v[58:61]
	v_mfma_f32_16x16x32_bf16 v[58:61], v[124:127], v[96:99], v[74:77]
	v_mfma_f32_16x16x32_bf16 v[74:77], v[128:131], v[96:99], v[78:81]
	v_mfma_f32_16x16x32_bf16 v[10:13], v[132:135], v[96:99], v[10:13]
	v_mfma_f32_16x16x32_bf16 v[18:21], v[120:123], v[100:103], v[18:21]
	v_mfma_f32_16x16x32_bf16 v[22:25], v[124:127], v[100:103], v[22:25]
	v_mfma_f32_16x16x32_bf16 v[26:29], v[128:131], v[100:103], v[26:29]
	v_mfma_f32_16x16x32_bf16 v[14:17], v[132:135], v[100:103], v[14:17]
	s_setprio 0
	s_mov_b64 s[44:45], 0x100
	s_mov_b32 m0, s12
	v_lshl_add_u64 v[78:79], v[62:63], 0, s[44:45]
	s_mov_b64 s[46:47], 0x10100
	s_waitcnt vmcnt(0)
	s_waitcnt vmcnt(0)
	s_barrier
	s_setprio 3
	global_load_lds_dwordx4 v[78:79], off
	v_lshl_add_u64 v[78:79], v[62:63], 0, s[46:47]
	s_mov_b32 m0, s13
	s_mov_b64 s[12:13], 0x20100
	global_load_lds_dwordx4 v[78:79], off
	v_lshl_add_u64 v[78:79], v[62:63], 0, s[12:13]
	s_mov_b32 m0, s18
	s_mov_b64 s[48:49], 0x30100
	global_load_lds_dwordx4 v[78:79], off
	v_lshl_add_u64 v[78:79], v[62:63], 0, s[48:49]
	s_mov_b32 m0, s19
	s_nop 0
	global_load_lds_dwordx4 v[78:79], off
	v_lshl_add_u64 v[78:79], v[0:1], 0, s[44:45]
	s_mov_b32 m0, s21
	s_nop 0
	global_load_lds_dwordx4 v[78:79], off
	v_lshl_add_u64 v[78:79], v[0:1], 0, s[46:47]
	s_mov_b32 m0, s22
	s_nop 0
	global_load_lds_dwordx4 v[78:79], off
	v_lshl_add_u64 v[78:79], v[0:1], 0, s[12:13]
	s_mov_b32 m0, s23
	s_nop 0
	global_load_lds_dwordx4 v[78:79], off
	v_lshl_add_u64 v[78:79], v[0:1], 0, s[48:49]
	s_mov_b32 m0, s24
	s_nop 0
	global_load_lds_dwordx4 v[78:79], off
	s_setprio 0
	ds_read_b128 v[78:81], v90 offset:16384
	ds_read_b128 v[82:85], v90 offset:18432
	ds_read_b128 v[96:99], v90 offset:20480
	ds_read_b128 v[100:103], v90 offset:22528
	ds_read_b128 v[120:123], v91 offset:49152
	ds_read_b128 v[124:127], v91 offset:51200
	ds_read_b128 v[128:131], v91 offset:53248
	ds_read_b128 v[132:135], v91 offset:55296
	s_setprio 1
	s_waitcnt lgkmcnt(0)
	v_mfma_f32_16x16x32_bf16 v[34:37], v[120:123], v[78:81], v[34:37]
	v_mfma_f32_16x16x32_bf16 v[38:41], v[124:127], v[78:81], v[38:41]
	v_mfma_f32_16x16x32_bf16 v[42:45], v[128:131], v[78:81], v[42:45]
	v_mfma_f32_16x16x32_bf16 v[2:5], v[132:135], v[78:81], v[2:5]
	v_mfma_f32_16x16x32_bf16 v[30:33], v[120:123], v[82:85], v[30:33]
	v_mfma_f32_16x16x32_bf16 v[46:49], v[124:127], v[82:85], v[46:49]
	v_mfma_f32_16x16x32_bf16 v[50:53], v[128:131], v[82:85], v[50:53]
	v_mfma_f32_16x16x32_bf16 v[6:9], v[132:135], v[82:85], v[6:9]
	v_mfma_f32_16x16x32_bf16 v[54:57], v[120:123], v[96:99], v[54:57]
	v_mfma_f32_16x16x32_bf16 v[58:61], v[124:127], v[96:99], v[58:61]
	v_mfma_f32_16x16x32_bf16 v[74:77], v[128:131], v[96:99], v[74:77]
	v_mfma_f32_16x16x32_bf16 v[10:13], v[132:135], v[96:99], v[10:13]
	v_mfma_f32_16x16x32_bf16 v[18:21], v[120:123], v[100:103], v[18:21]
	v_mfma_f32_16x16x32_bf16 v[22:25], v[124:127], v[100:103], v[22:25]
	v_mfma_f32_16x16x32_bf16 v[26:29], v[128:131], v[100:103], v[26:29]
	v_mfma_f32_16x16x32_bf16 v[14:17], v[132:135], v[100:103], v[14:17]
	s_setprio 0
	ds_read_b128 v[78:81], v92 offset:16384
	ds_read_b128 v[82:85], v92 offset:18432
	ds_read_b128 v[96:99], v92 offset:20480
	ds_read_b128 v[100:103], v92 offset:22528
	ds_read_b128 v[120:123], v93 offset:49152
	ds_read_b128 v[124:127], v93 offset:51200
	ds_read_b128 v[128:131], v93 offset:53248
	ds_read_b128 v[132:135], v93 offset:55296
	s_setprio 1
	s_waitcnt lgkmcnt(0)
	v_mfma_f32_16x16x32_bf16 v[34:37], v[120:123], v[78:81], v[34:37]
	v_mfma_f32_16x16x32_bf16 v[38:41], v[124:127], v[78:81], v[38:41]
	v_mfma_f32_16x16x32_bf16 v[42:45], v[128:131], v[78:81], v[42:45]
	v_mfma_f32_16x16x32_bf16 v[2:5], v[132:135], v[78:81], v[2:5]
	v_mfma_f32_16x16x32_bf16 v[30:33], v[120:123], v[82:85], v[30:33]
	v_mfma_f32_16x16x32_bf16 v[46:49], v[124:127], v[82:85], v[46:49]
	v_mfma_f32_16x16x32_bf16 v[50:53], v[128:131], v[82:85], v[50:53]
	v_mfma_f32_16x16x32_bf16 v[6:9], v[132:135], v[82:85], v[6:9]
	v_mfma_f32_16x16x32_bf16 v[54:57], v[120:123], v[96:99], v[54:57]
	v_mfma_f32_16x16x32_bf16 v[58:61], v[124:127], v[96:99], v[58:61]
	v_mfma_f32_16x16x32_bf16 v[74:77], v[128:131], v[96:99], v[74:77]
	v_mfma_f32_16x16x32_bf16 v[10:13], v[132:135], v[96:99], v[10:13]
	v_mfma_f32_16x16x32_bf16 v[18:21], v[120:123], v[100:103], v[18:21]
	v_mfma_f32_16x16x32_bf16 v[22:25], v[124:127], v[100:103], v[22:25]
	v_mfma_f32_16x16x32_bf16 v[26:29], v[128:131], v[100:103], v[26:29]
	v_mfma_f32_16x16x32_bf16 v[14:17], v[132:135], v[100:103], v[14:17]
	s_setprio 0
	s_mov_b64 s[12:13], 0x180
	s_mov_b32 m0, s25
	v_lshl_add_u64 v[78:79], v[62:63], 0, s[12:13]
	s_mov_b64 s[18:19], 0x10180
	s_waitcnt vmcnt(0)
	s_waitcnt vmcnt(0)
	s_barrier
	s_setprio 3
	global_load_lds_dwordx4 v[78:79], off
	v_lshl_add_u64 v[78:79], v[62:63], 0, s[18:19]
	s_mov_b32 m0, s36
	s_mov_b64 s[22:23], 0x20180
	global_load_lds_dwordx4 v[78:79], off
	v_lshl_add_u64 v[78:79], v[62:63], 0, s[22:23]
	s_mov_b32 m0, s37
	s_mov_b64 s[24:25], 0x30180
	global_load_lds_dwordx4 v[78:79], off
	v_lshl_add_u64 v[62:63], v[62:63], 0, s[24:25]
	s_mov_b32 m0, s38
	s_nop 0
	global_load_lds_dwordx4 v[62:63], off
	v_lshl_add_u64 v[62:63], v[0:1], 0, s[12:13]
	s_mov_b32 m0, s39
	s_nop 0
	global_load_lds_dwordx4 v[62:63], off
	v_lshl_add_u64 v[62:63], v[0:1], 0, s[18:19]
	s_mov_b32 m0, s40
	s_nop 0
	global_load_lds_dwordx4 v[62:63], off
	v_lshl_add_u64 v[62:63], v[0:1], 0, s[22:23]
	s_mov_b32 m0, s41
	v_lshl_add_u64 v[0:1], v[0:1], 0, s[24:25]
	global_load_lds_dwordx4 v[62:63], off
	s_mov_b32 m0, s42
	s_nop 0
	global_load_lds_dwordx4 v[0:1], off
	s_setprio 0
	ds_read_b128 v[78:81], v90
	ds_read_b128 v[82:85], v90 offset:2048
	ds_read_b128 v[96:99], v90 offset:4096
	ds_read_b128 v[100:103], v90 offset:6144
	ds_read_b128 v[120:123], v91 offset:32768
	ds_read_b128 v[124:127], v91 offset:34816
	ds_read_b128 v[128:131], v91 offset:36864
	ds_read_b128 v[132:135], v91 offset:38912
	s_setprio 1
	s_waitcnt lgkmcnt(0)
	v_mfma_f32_16x16x32_bf16 v[34:37], v[120:123], v[78:81], v[34:37]
	v_mfma_f32_16x16x32_bf16 v[38:41], v[124:127], v[78:81], v[38:41]
	v_mfma_f32_16x16x32_bf16 v[42:45], v[128:131], v[78:81], v[42:45]
	v_mfma_f32_16x16x32_bf16 v[0:3], v[132:135], v[78:81], v[2:5]
	v_mfma_f32_16x16x32_bf16 v[30:33], v[120:123], v[82:85], v[30:33]
	v_mfma_f32_16x16x32_bf16 v[46:49], v[124:127], v[82:85], v[46:49]
	v_mfma_f32_16x16x32_bf16 v[50:53], v[128:131], v[82:85], v[50:53]
	v_mfma_f32_16x16x32_bf16 v[4:7], v[132:135], v[82:85], v[6:9]
	v_mfma_f32_16x16x32_bf16 v[54:57], v[120:123], v[96:99], v[54:57]
	v_mfma_f32_16x16x32_bf16 v[58:61], v[124:127], v[96:99], v[58:61]
	v_mfma_f32_16x16x32_bf16 v[74:77], v[128:131], v[96:99], v[74:77]
	v_mfma_f32_16x16x32_bf16 v[8:11], v[132:135], v[96:99], v[10:13]
	v_mfma_f32_16x16x32_bf16 v[18:21], v[120:123], v[100:103], v[18:21]
	v_mfma_f32_16x16x32_bf16 v[22:25], v[124:127], v[100:103], v[22:25]
	v_mfma_f32_16x16x32_bf16 v[26:29], v[128:131], v[100:103], v[26:29]
	v_mfma_f32_16x16x32_bf16 v[12:15], v[132:135], v[100:103], v[14:17]
	s_setprio 0
	ds_read_b128 v[78:81], v92
	ds_read_b128 v[82:85], v92 offset:2048
	ds_read_b128 v[96:99], v92 offset:4096
	ds_read_b128 v[100:103], v92 offset:6144
	ds_read_b128 v[120:123], v93 offset:32768
	ds_read_b128 v[124:127], v93 offset:34816
	ds_read_b128 v[128:131], v93 offset:36864
	ds_read_b128 v[132:135], v93 offset:38912
	s_setprio 1
	s_waitcnt lgkmcnt(0)
	v_mfma_f32_16x16x32_bf16 v[34:37], v[120:123], v[78:81], v[34:37]
	v_mfma_f32_16x16x32_bf16 v[38:41], v[124:127], v[78:81], v[38:41]
	v_mfma_f32_16x16x32_bf16 v[42:45], v[128:131], v[78:81], v[42:45]
	v_mfma_f32_16x16x32_bf16 v[0:3], v[132:135], v[78:81], v[0:3]
	v_mfma_f32_16x16x32_bf16 v[30:33], v[120:123], v[82:85], v[30:33]
	v_mfma_f32_16x16x32_bf16 v[46:49], v[124:127], v[82:85], v[46:49]
	v_mfma_f32_16x16x32_bf16 v[50:53], v[128:131], v[82:85], v[50:53]
	v_mfma_f32_16x16x32_bf16 v[4:7], v[132:135], v[82:85], v[4:7]
	v_mfma_f32_16x16x32_bf16 v[54:57], v[120:123], v[96:99], v[54:57]
	v_mfma_f32_16x16x32_bf16 v[58:61], v[124:127], v[96:99], v[58:61]
	v_mfma_f32_16x16x32_bf16 v[74:77], v[128:131], v[96:99], v[74:77]
	v_mfma_f32_16x16x32_bf16 v[8:11], v[132:135], v[96:99], v[8:11]
	v_mfma_f32_16x16x32_bf16 v[16:19], v[120:123], v[100:103], v[18:21]
	v_mfma_f32_16x16x32_bf16 v[20:23], v[124:127], v[100:103], v[22:25]
	v_mfma_f32_16x16x32_bf16 v[24:27], v[128:131], v[100:103], v[26:29]
	v_mfma_f32_16x16x32_bf16 v[12:15], v[132:135], v[100:103], v[12:15]
	s_setprio 0
	s_waitcnt vmcnt(0)
	s_waitcnt vmcnt(0)
	s_barrier
	ds_read_b128 v[78:81], v91 offset:55296
	ds_read_b128 v[82:85], v91 offset:53248
	ds_read_b128 v[96:99], v91 offset:51200
	ds_read_b128 v[100:103], v91 offset:49152
	ds_read_b128 v[120:123], v90 offset:22528
	ds_read_b128 v[124:127], v90 offset:20480
	ds_read_b128 v[128:131], v90 offset:18432
	ds_read_b128 v[132:135], v90 offset:16384
	s_setprio 1
	s_waitcnt lgkmcnt(0)
	v_mfma_f32_16x16x32_bf16 v[34:37], v[100:103], v[132:135], v[34:37]
	v_mfma_f32_16x16x32_bf16 v[136:139], v[96:99], v[132:135], v[38:41]
	v_mfma_f32_16x16x32_bf16 v[40:43], v[82:85], v[132:135], v[42:45]
	v_mfma_f32_16x16x32_bf16 v[0:3], v[78:81], v[132:135], v[0:3]
	v_mfma_f32_16x16x32_bf16 v[28:31], v[100:103], v[128:131], v[30:33]
	v_mfma_f32_16x16x32_bf16 v[132:135], v[96:99], v[128:131], v[46:49]
	v_mfma_f32_16x16x32_bf16 v[140:143], v[82:85], v[128:131], v[50:53]
	v_mfma_f32_16x16x32_bf16 v[4:7], v[78:81], v[128:131], v[4:7]
	v_mfma_f32_16x16x32_bf16 v[52:55], v[100:103], v[124:127], v[54:57]
	v_mfma_f32_16x16x32_bf16 v[128:131], v[96:99], v[124:127], v[58:61]
	v_mfma_f32_16x16x32_bf16 v[74:77], v[82:85], v[124:127], v[74:77]
	v_mfma_f32_16x16x32_bf16 v[124:127], v[78:81], v[124:127], v[8:11]
	v_mfma_f32_16x16x32_bf16 v[100:103], v[100:103], v[120:123], v[16:19]
	v_mfma_f32_16x16x32_bf16 v[96:99], v[96:99], v[120:123], v[20:23]
	v_mfma_f32_16x16x32_bf16 v[82:85], v[82:85], v[120:123], v[24:27]
	v_mfma_f32_16x16x32_bf16 v[78:81], v[78:81], v[120:123], v[12:15]
	s_setprio 0
	ds_read_b128 v[8:11], v92 offset:16384
	s_nop 0
	ds_read_b128 v[12:15], v92 offset:18432
	ds_read_b128 v[120:123], v92 offset:20480
	ds_read_b128 v[144:147], v92 offset:22528
	ds_read_b128 v[148:151], v93 offset:49152
	ds_read_b128 v[152:155], v93 offset:51200
	ds_read_b128 v[156:159], v93 offset:53248
	ds_read_b128 v[160:163], v93 offset:55296
	s_setprio 1
	s_waitcnt lgkmcnt(3)
	v_mfma_f32_16x16x32_bf16 v[36:39], v[148:151], v[8:11], v[34:37]
	s_waitcnt lgkmcnt(2)
	v_mfma_f32_16x16x32_bf16 v[44:47], v[152:155], v[8:11], v[136:139]
	s_waitcnt lgkmcnt(1)
	v_mfma_f32_16x16x32_bf16 v[48:51], v[156:159], v[8:11], v[40:43]
	s_waitcnt lgkmcnt(0)
	v_mfma_f32_16x16x32_bf16 v[32:35], v[160:163], v[8:11], v[0:3]
	v_mfma_f32_16x16x32_bf16 v[60:63], v[148:151], v[12:15], v[28:31]
	v_mfma_f32_16x16x32_bf16 v[24:27], v[152:155], v[12:15], v[132:135]
	v_mfma_f32_16x16x32_bf16 v[20:23], v[156:159], v[12:15], v[140:143]
	v_mfma_f32_16x16x32_bf16 v[16:19], v[160:163], v[12:15], v[4:7]
	v_mfma_f32_16x16x32_bf16 v[56:59], v[148:151], v[120:123], v[52:55]
	v_mfma_f32_16x16x32_bf16 v[12:15], v[152:155], v[120:123], v[128:131]
	v_mfma_f32_16x16x32_bf16 v[8:11], v[156:159], v[120:123], v[74:77]
	v_mfma_f32_16x16x32_bf16 v[28:31], v[160:163], v[120:123], v[124:127]
	v_mfma_f32_16x16x32_bf16 v[52:55], v[148:151], v[144:147], v[100:103]
	v_mfma_f32_16x16x32_bf16 v[40:43], v[152:155], v[144:147], v[96:99]
	v_mfma_f32_16x16x32_bf16 v[4:7], v[156:159], v[144:147], v[82:85]
	v_mfma_f32_16x16x32_bf16 v[0:3], v[160:163], v[144:147], v[78:81]
	s_setprio 0
	s_or_b32 s11, s11, s5
	s_lshl_b32 s11, s11, 2
	v_mov_b32_e32 v71, s11
	s_waitcnt vmcnt(0)
	s_barrier
	global_load_dword v74, v71, s[58:59]
	s_nop 0
	global_load_dword v71, v71, s[58:59] offset:16
	s_mov_b32 s11, 0xbfb8aa3b
	s_mov_b32 s12, 0x33800000
	v_or_b32_e32 v124, s0, v89
	v_add_u32_e32 v103, s1, v88
	v_or_b32_e32 v122, 2, v124
	v_or_b32_e32 v123, 1, v124
	s_waitcnt vmcnt(1)
	v_mul_f32_e32 v75, 0xbfb8aa3b, v74
	s_waitcnt vmcnt(0)
	v_mul_f32_e32 v76, 0xbfb8aa3b, v71
	v_fma_f32 v77, v74, s11, -v75
	v_rndne_f32_e32 v78, v75
	v_fma_f32 v79, v71, s11, -v76
	v_rndne_f32_e32 v80, v76
	v_fmac_f32_e32 v77, 0xb2a5705f, v74
	v_sub_f32_e32 v75, v75, v78
	v_fmac_f32_e32 v79, 0xb2a5705f, v71
	v_sub_f32_e32 v76, v76, v80
	v_add_f32_e32 v75, v75, v77
	v_cvt_i32_f32_e32 v78, v78
	v_add_f32_e32 v76, v76, v79
	v_exp_f32_e32 v75, v75
	v_cvt_i32_f32_e32 v80, v80
	v_exp_f32_e32 v76, v76
	s_mov_b32 s11, 0x42ce8ed0
	v_ldexp_f32 v75, v75, v78
	v_cmp_nlt_f32_e32 vcc, s11, v74
	v_ldexp_f32 v76, v76, v80
	s_nop 0
	v_cndmask_b32_e32 v75, 0, v75, vcc
	v_cmp_nlt_f32_e32 vcc, s11, v71
	s_mov_b32 s11, 0xc2b17218
	s_nop 0
	v_cndmask_b32_e32 v76, 0, v76, vcc
	v_cmp_ngt_f32_e32 vcc, s11, v74
	s_nop 1
	v_cndmask_b32_e32 v75, v112, v75, vcc
	v_cmp_ngt_f32_e32 vcc, s11, v71
	v_add_f32_e32 v71, 1.0, v75
	v_frexp_mant_f32_e32 v82, v71
	v_cndmask_b32_e32 v74, v112, v76, vcc
	v_cvt_f64_f32_e32 v[76:77], v71
	s_mov_b32 s11, 0x3f2aaaab
	v_add_f32_e32 v80, 1.0, v74
	v_add_f32_e32 v81, -1.0, v71
	v_frexp_exp_i32_f64_e32 v76, v[76:77]
	v_cmp_gt_f32_e32 vcc, s11, v82
	v_add_f32_e32 v83, -1.0, v80
	v_frexp_mant_f32_e32 v84, v80
	v_cvt_f64_f32_e32 v[78:79], v80
	v_sub_f32_e32 v85, v81, v71
	v_subbrev_co_u32_e32 v76, vcc, 0, v76, vcc
	v_sub_f32_e32 v81, v75, v81
	v_sub_f32_e32 v77, v83, v80
	v_frexp_exp_i32_f64_e32 v78, v[78:79]
	v_add_f32_e32 v79, 1.0, v85
	v_cmp_gt_f32_e32 vcc, s11, v84
	v_sub_f32_e32 v83, v74, v83
	v_add_f32_e32 v77, 1.0, v77
	v_subbrev_co_u32_e32 v100, vcc, 0, v78, vcc
	v_add_f32_e32 v78, v81, v79
	v_sub_u32_e32 v79, 0, v76
	v_add_f32_e32 v77, v83, v77
	v_sub_u32_e32 v81, 0, v100
	v_ldexp_f32 v71, v71, v79
	v_ldexp_f32 v101, v80, v81
	v_ldexp_f32 v102, v77, v81
	v_add_f32_e32 v77, -1.0, v71
	v_add_f32_e32 v80, 1.0, v71
	v_ldexp_f32 v78, v78, v79
	v_add_f32_e32 v79, 1.0, v77
	v_add_f32_e32 v81, -1.0, v80
	v_sub_f32_e32 v79, v71, v79
	v_sub_f32_e32 v71, v71, v81
	v_add_f32_e32 v71, v78, v71
	v_add_f32_e32 v84, v80, v71
	v_rcp_f32_e32 v85, v84
	v_add_f32_e32 v81, v78, v79
	v_add_f32_e32 v79, v77, v81
	v_sub_f32_e32 v78, v80, v84
	v_mul_f32_e32 v86, v79, v85
	v_mul_f32_e32 v80, v84, v86
	v_add_f32_e32 v71, v71, v78
	v_fma_f32 v82, v86, v84, -v80
	v_fmac_f32_e32 v82, v86, v71
	v_sub_f32_e32 v77, v77, v79
	v_add_f32_e32 v78, v80, v82
	v_add_f32_e32 v77, v81, v77
	v_sub_f32_e32 v81, v79, v78
	v_mov_b32_e32 v83, v78
	v_pk_add_f32 v[78:79], v[78:79], v[80:81] neg_lo:[0,1] neg_hi:[0,1]
	v_cvt_f32_i32_e32 v76, v76
	v_pk_add_f32 v[78:79], v[78:79], v[82:83] neg_lo:[0,1] neg_hi:[0,1]
	s_mov_b32 s11, 0x3f317218
	v_add_f32_e32 v77, v77, v79
	v_add_f32_e32 v77, v78, v77
	v_add_f32_e32 v79, v81, v77
	v_mul_f32_e32 v78, v85, v79
	v_mul_f32_e32 v80, v84, v78
	v_sub_f32_e32 v81, v81, v79
	v_add_f32_e32 v87, v86, v78
	v_fma_f32 v82, v78, v84, -v80
	v_add_f32_e32 v77, v77, v81
	v_sub_f32_e32 v81, v87, v86
	v_fmac_f32_e32 v82, v78, v71
	v_sub_f32_e32 v71, v78, v81
	v_add_f32_e32 v78, v80, v82
	v_sub_f32_e32 v81, v79, v78
	v_mov_b32_e32 v83, v78
	v_pk_add_f32 v[78:79], v[78:79], v[80:81] neg_lo:[0,1] neg_hi:[0,1]
	v_cmp_neq_f32_e32 vcc, s4, v75
	v_pk_add_f32 v[78:79], v[78:79], v[82:83] neg_lo:[0,1] neg_hi:[0,1]
	s_nop 0
	v_add_f32_e32 v77, v77, v79
	v_add_f32_e32 v77, v78, v77
	v_add_f32_e32 v77, v81, v77
	v_mul_f32_e32 v77, v85, v77
	v_add_f32_e32 v71, v71, v77
	v_add_f32_e32 v77, v87, v71
	v_mul_f32_e32 v78, v77, v77
	v_sub_f32_e32 v80, v77, v87
	v_fmamk_f32 v81, v78, 0x3e9b6dac, v109
	v_ldexp_f32 v79, v77, 1
	v_sub_f32_e32 v80, v71, v80
	v_mul_f32_e32 v77, v77, v78
	v_fmaak_f32 v71, v78, v81, 0x3f2aaada
	v_ldexp_f32 v83, v80, 1
	v_pk_mul_f32 v[80:81], v[76:77], v[70:71]
	s_nop 0
	v_fma_f32 v78, v76, s11, -v80
	v_fmac_f32_e32 v78, 0xb102e308, v76
	v_pk_add_f32 v[76:77], v[80:81], v[78:79]
	v_mov_b32_e32 v82, v80
	v_sub_f32_e32 v71, v77, v79
	v_sub_f32_e32 v71, v81, v71
	v_add_f32_e32 v83, v83, v71
	v_pk_add_f32 v[84:85], v[76:77], v[80:81] neg_lo:[0,1] neg_hi:[0,1]
	v_pk_add_f32 v[96:97], v[76:77], v[82:83]
	v_mov_b32_e32 v79, v76
	v_mov_b32_e32 v85, v97
	v_pk_add_f32 v[98:99], v[78:79], v[84:85] neg_lo:[0,1] neg_hi:[0,1]
	v_pk_add_f32 v[78:79], v[78:79], v[84:85]
	v_mov_b32_e32 v80, v77
	v_mov_b32_e32 v87, v76
	v_pk_add_f32 v[76:77], v[78:79], v[76:77] op_sel:[1,0] op_sel_hi:[0,1] neg_lo:[0,1] neg_hi:[0,1]
	v_mov_b32_e32 v86, v83
	v_mov_b32_e32 v82, v97
	v_mov_b32_e32 v83, v79
	v_mov_b32_e32 v81, v76
	v_pk_add_f32 v[84:85], v[96:97], v[76:77] op_sel_hi:[1,0] neg_lo:[0,1] neg_hi:[0,1]
	v_pk_add_f32 v[76:77], v[82:83], v[80:81] neg_lo:[0,1] neg_hi:[0,1]
	v_mov_b32_e32 v84, v98
	v_pk_add_f32 v[76:77], v[86:87], v[76:77] neg_lo:[0,1] neg_hi:[0,1]
	v_mov_b32_e32 v99, v79
	v_pk_add_f32 v[80:81], v[84:85], v[76:77]
	s_nop 0
	v_pk_add_f32 v[82:83], v[80:81], v[80:81] op_sel:[0,1] op_sel_hi:[1,0]
	s_nop 0
	v_pk_add_f32 v[78:79], v[78:79], v[82:83] op_sel:[1,0] op_sel_hi:[0,1]
	v_mov_b32_e32 v81, v78
	v_mov_b32_e32 v77, v82
	v_pk_add_f32 v[82:83], v[80:81], v[98:99] neg_lo:[0,1] neg_hi:[0,1]
	s_nop 0
	v_sub_f32_e32 v71, v80, v82
	v_pk_add_f32 v[76:77], v[76:77], v[82:83] neg_lo:[0,1] neg_hi:[0,1]
	v_sub_f32_e32 v71, v98, v71
	v_add_f32_e32 v71, v76, v71
	v_add_f32_e32 v71, v71, v77
	v_add_f32_e32 v71, v78, v71
	v_add_f32_e32 v76, 1.0, v101
	v_cndmask_b32_e32 v71, v112, v71, vcc
	v_cmp_lt_f32_e64 vcc, |v75|, s12
	v_add_f32_e32 v77, -1.0, v76
	v_sub_f32_e32 v77, v101, v77
	v_cndmask_b32_e32 v71, v71, v75, vcc
	v_mul_f32_e32 v95, 0xbfb8aa3b, v71
	v_add_f32_e32 v71, -1.0, v101
	v_add_f32_e32 v77, v102, v77
	v_add_f32_e32 v75, 1.0, v71
	v_add_f32_e32 v84, v76, v77
	v_sub_f32_e32 v75, v101, v75
	v_rcp_f32_e32 v86, v84
	v_add_f32_e32 v75, v102, v75
	v_sub_f32_e32 v76, v76, v84
	v_add_f32_e32 v85, v77, v76
	v_add_f32_e32 v77, v71, v75
	v_sub_f32_e32 v71, v71, v77
	v_add_f32_e32 v71, v75, v71
	v_mul_f32_e32 v75, v77, v86
	v_mul_f32_e32 v78, v84, v75
	v_fma_f32 v80, v75, v84, -v78
	v_fmac_f32_e32 v80, v75, v85
	v_add_f32_e32 v76, v78, v80
	v_sub_f32_e32 v79, v77, v76
	v_pk_add_f32 v[82:83], v[76:77], v[78:79] neg_lo:[0,1] neg_hi:[0,1]
	v_mov_b32_e32 v81, v76
	v_pk_add_f32 v[76:77], v[82:83], v[80:81] neg_lo:[0,1] neg_hi:[0,1]
	v_cmp_neq_f32_e32 vcc, s4, v74
	v_add_f32_e32 v71, v71, v77
	v_add_f32_e32 v71, v76, v71
	v_add_f32_e32 v77, v79, v71
	v_mul_f32_e32 v87, v86, v77
	v_mul_f32_e32 v78, v84, v87
	v_fma_f32 v80, v87, v84, -v78
	v_fmac_f32_e32 v80, v87, v85
	v_sub_f32_e32 v76, v79, v77
	v_add_f32_e32 v71, v71, v76
	v_add_f32_e32 v76, v78, v80
	v_sub_f32_e32 v79, v77, v76
	v_pk_add_f32 v[82:83], v[76:77], v[78:79] neg_lo:[0,1] neg_hi:[0,1]
	v_mov_b32_e32 v81, v76
	v_pk_add_f32 v[76:77], v[82:83], v[80:81] neg_lo:[0,1] neg_hi:[0,1]
	s_nop 0
	v_add_f32_e32 v71, v71, v77
	v_add_f32_e32 v71, v76, v71
	v_add_f32_e32 v77, v75, v87
	v_add_f32_e32 v71, v79, v71
	v_sub_f32_e32 v75, v77, v75
	v_mul_f32_e32 v71, v86, v71
	v_sub_f32_e32 v75, v87, v75
	v_add_f32_e32 v75, v75, v71
	v_add_f32_e32 v78, v77, v75
	v_cvt_f32_i32_e32 v76, v100
	v_mul_f32_e32 v80, v78, v78
	v_fmamk_f32 v71, v80, 0x3e9b6dac, v109
	v_sub_f32_e32 v77, v78, v77
	v_fmaak_f32 v71, v80, v71, 0x3f2aaada
	v_sub_f32_e32 v75, v75, v77
	v_mul_f32_e32 v77, v78, v80
	v_pk_mul_f32 v[80:81], v[76:77], v[70:71]
	v_ldexp_f32 v79, v78, 1
	v_fma_f32 v78, v76, s11, -v80
	v_fmac_f32_e32 v78, 0xb102e308, v76
	v_pk_add_f32 v[76:77], v[80:81], v[78:79]
	v_ldexp_f32 v75, v75, 1
	v_sub_f32_e32 v71, v77, v79
	v_sub_f32_e32 v71, v81, v71
	v_add_f32_e32 v83, v75, v71
	v_mov_b32_e32 v82, v80
	v_pk_add_f32 v[80:81], v[76:77], v[80:81] neg_lo:[0,1] neg_hi:[0,1]
	v_pk_add_f32 v[84:85], v[76:77], v[82:83]
	v_mov_b32_e32 v79, v76
	v_mov_b32_e32 v81, v85
	v_pk_add_f32 v[86:87], v[78:79], v[80:81] neg_lo:[0,1] neg_hi:[0,1]
	v_pk_add_f32 v[78:79], v[78:79], v[80:81]
	v_mov_b32_e32 v98, v77
	v_pk_add_f32 v[80:81], v[78:79], v[76:77] op_sel:[1,0] op_sel_hi:[0,1] neg_lo:[0,1] neg_hi:[0,1]
	v_pk_add_f32 v[96:97], v[84:85], v[80:81] op_sel_hi:[1,0] neg_lo:[0,1] neg_hi:[0,1]
	v_mov_b32_e32 v84, v85
	v_mov_b32_e32 v85, v79
	v_mov_b32_e32 v99, v80
	v_pk_add_f32 v[80:81], v[84:85], v[98:99] neg_lo:[0,1] neg_hi:[0,1]
	v_mov_b32_e32 v82, v83
	v_mov_b32_e32 v83, v76
	v_pk_add_f32 v[76:77], v[82:83], v[80:81] neg_lo:[0,1] neg_hi:[0,1]
	v_mov_b32_e32 v96, v86
	v_pk_add_f32 v[80:81], v[96:97], v[76:77]
	v_mov_b32_e32 v87, v79
	v_pk_add_f32 v[82:83], v[80:81], v[80:81] op_sel:[0,1] op_sel_hi:[1,0]
	v_or_b32_e32 v99, 3, v124
	v_pk_add_f32 v[78:79], v[78:79], v[82:83] op_sel:[1,0] op_sel_hi:[0,1]
	v_mov_b32_e32 v81, v78
	v_pk_add_f32 v[84:85], v[80:81], v[86:87] neg_lo:[0,1] neg_hi:[0,1]
	v_mov_b32_e32 v77, v82
	v_sub_f32_e32 v71, v80, v84
	v_pk_add_f32 v[76:77], v[76:77], v[84:85] neg_lo:[0,1] neg_hi:[0,1]
	v_sub_f32_e32 v71, v86, v71
	v_add_f32_e32 v71, v76, v71
	v_sub_u32_e32 v82, v103, v99
	v_add_f32_e32 v71, v71, v77
	v_cvt_f32_u32_e32 v83, v82
	v_sub_u32_e32 v84, 0, v82
	v_add_f32_e32 v71, v78, v71
	v_cvt_f32_u32_e32 v84, v84
	v_cndmask_b32_e32 v71, v112, v71, vcc
	v_cmp_lt_f32_e64 vcc, |v74|, s12
	v_mul_f32_e32 v83, v95, v83
	v_exp_f32_e32 v83, v83
	v_cndmask_b32_e32 v71, v71, v74, vcc
	v_mul_f32_e32 v71, 0xbfb8aa3b, v71
	v_mul_f32_e32 v84, v71, v84
	v_exp_f32_e32 v84, v84
	v_cmp_lt_i32_e32 vcc, -1, v82
	v_sub_u32_e32 v100, v103, v123
	v_sub_u32_e32 v87, 0, v100
	v_cndmask_b32_e32 v83, 0, v83, vcc
	v_cmp_gt_i32_e32 vcc, 1, v82
	v_cvt_f32_u32_e32 v86, v100
	v_cvt_f32_u32_e32 v87, v87
	v_cndmask_b32_e32 v82, 0, v84, vcc
	v_add_f32_e32 v82, v83, v82
	v_mul_f32_e32 v39, v39, v82
	v_cvt_pk_bf16_f32 v102, v39, s0
	v_sub_u32_e32 v39, v103, v122
	v_cvt_f32_u32_e32 v101, v39
	v_sub_u32_e32 v120, 0, v39
	v_cvt_f32_u32_e32 v120, v120
	v_mul_f32_e32 v86, v95, v86
	v_mul_f32_e32 v101, v95, v101
	v_exp_f32_e32 v101, v101
	v_mul_f32_e32 v87, v71, v87
	v_cmp_lt_i32_e32 vcc, -1, v39
	v_exp_f32_e32 v86, v86
	v_exp_f32_e32 v121, v87
	v_cndmask_b32_e32 v87, 0, v101, vcc
	v_mul_f32_e32 v101, v71, v120
	v_exp_f32_e32 v101, v101
	s_mul_hi_i32 s11, s10, 0x820000
	s_mul_i32 s10, s10, 0x820000
	v_readlane_b32 s12, v182, 21
	v_readlane_b32 s13, v182, 22
	s_add_u32 s12, s12, s10
	v_cmp_lt_i32_e32 vcc, -1, v100
	s_addc_u32 s13, s13, s11
	s_lshl_b64 s[10:11], s[6:7], 19
	v_cndmask_b32_e32 v86, 0, v86, vcc
	v_cmp_gt_i32_e32 vcc, 1, v39
	s_add_u32 s10, s12, s10
	s_addc_u32 s11, s13, s11
	v_cndmask_b32_e32 v101, 0, v101, vcc
	v_cmp_gt_i32_e32 vcc, 1, v100
	v_mad_i64_i32 v[74:75], s[12:13], s20, v103, 0
	s_nop 0
	v_cndmask_b32_e32 v100, 0, v121, vcc
	v_lshl_add_u64 v[80:81], v[74:75], 1, s[10:11]
	v_lshlrev_b32_e32 v84, 1, v124
	v_mov_b32_e32 v85, v69
	v_pk_add_f32 v[86:87], v[86:87], v[100:101]
	v_mov_b32_e32 v100, v37
	v_mov_b32_e32 v101, v38
	v_or_b32_e32 v98, 16, v103
	v_lshl_add_u64 v[82:83], v[80:81], 0, v[84:85]
	v_pk_mul_f32 v[38:39], v[100:101], v[86:87]
	v_sub_u32_e32 v100, v98, v123
	v_cvt_pk_bf16_f32 v37, v38, v39
	global_store_short v[82:83], v102, off offset:6
	global_store_dword v[82:83], v37, off offset:2
	v_sub_u32_e32 v102, v98, v124
	v_sub_u32_e32 v39, 0, v102
	v_cvt_f32_u32_e32 v39, v39
	v_sub_u32_e32 v87, 0, v100
	v_cvt_f32_u32_e32 v86, v100
	v_cvt_f32_u32_e32 v87, v87
	v_mul_f32_e32 v39, v71, v39
	v_sub_u32_e32 v37, v98, v122
	v_exp_f32_e32 v121, v39
	v_mul_f32_e32 v39, v95, v86
	v_mul_f32_e32 v86, v71, v87
	v_cvt_f32_u32_e32 v87, v37
	v_exp_f32_e32 v101, v86
	v_sub_u32_e32 v86, 0, v37
	v_cvt_f32_u32_e32 v38, v102
	v_sub_u32_e32 v120, v98, v99
	v_cvt_f32_u32_e32 v86, v86
	v_cvt_f32_u32_e32 v125, v120
	v_mul_f32_e32 v87, v95, v87
	v_mul_f32_e32 v38, v95, v38
	v_exp_f32_e32 v39, v39
	v_exp_f32_e32 v126, v87
	v_mul_f32_e32 v86, v71, v86
	v_sub_u32_e32 v87, 0, v120
	v_exp_f32_e32 v38, v38
	v_exp_f32_e32 v127, v86
	v_mul_f32_e32 v86, v95, v125
	v_cvt_f32_u32_e32 v125, v87
	v_exp_f32_e32 v86, v86
	v_cmp_lt_i32_e32 vcc, -1, v100
	v_or_b32_e32 v97, 32, v103
	v_mul_f32_e32 v125, v71, v125
	v_cndmask_b32_e32 v39, 0, v39, vcc
	v_cmp_lt_i32_e32 vcc, -1, v102
	v_exp_f32_e32 v125, v125
	v_or_b32_e32 v96, 48, v103
	v_cndmask_b32_e32 v38, 0, v38, vcc
	v_cmp_lt_i32_e32 vcc, -1, v120
	v_mad_i64_i32 v[74:75], s[12:13], s20, v98, 0
	s_nop 0
	v_cndmask_b32_e32 v87, 0, v86, vcc
	v_cmp_lt_i32_e32 vcc, -1, v37
	v_lshl_add_u64 v[78:79], v[74:75], 1, s[10:11]
	v_mad_i64_i32 v[74:75], s[12:13], s20, v97, 0
	v_cndmask_b32_e32 v86, 0, v126, vcc
	v_cmp_gt_i32_e32 vcc, 1, v100
	v_lshl_add_u64 v[76:77], v[74:75], 1, s[10:11]
	v_mad_i64_i32 v[74:75], s[12:13], s20, v96, 0
	v_cndmask_b32_e32 v101, 0, v101, vcc
	v_cmp_gt_i32_e32 vcc, 1, v102
	v_sub_u32_e32 v102, v97, v124
	v_lshl_add_u64 v[74:75], v[74:75], 1, s[10:11]
	v_cndmask_b32_e32 v100, 0, v121, vcc
	v_cmp_gt_i32_e32 vcc, 1, v120
	v_pk_add_f32 v[38:39], v[38:39], v[100:101]
	v_sub_u32_e32 v100, v97, v123
	v_cndmask_b32_e32 v121, 0, v125, vcc
	v_cmp_gt_i32_e32 vcc, 1, v37
	v_pk_mul_f32 v[38:39], v[60:61], v[38:39]
	v_sub_u32_e32 v37, v97, v122
	v_cndmask_b32_e32 v120, 0, v127, vcc
	v_pk_add_f32 v[86:87], v[86:87], v[120:121]
	v_sub_u32_e32 v120, v97, v99
	v_pk_mul_f32 v[60:61], v[62:63], v[86:87]
	v_sub_u32_e32 v87, 0, v100
	v_cvt_pk_bf16_f32 v61, v60, v61
	v_cvt_pk_bf16_f32 v60, v38, v39
	v_sub_u32_e32 v39, 0, v102
	v_cvt_f32_u32_e32 v39, v39
	v_cvt_f32_u32_e32 v86, v100
	v_cvt_f32_u32_e32 v87, v87
	v_cvt_f32_u32_e32 v38, v102
	v_mul_f32_e32 v39, v71, v39
	v_exp_f32_e32 v121, v39
	v_mul_f32_e32 v39, v95, v86
	v_mul_f32_e32 v86, v71, v87
	v_cvt_f32_u32_e32 v87, v37
	v_exp_f32_e32 v101, v86
	v_sub_u32_e32 v86, 0, v37
	v_cvt_f32_u32_e32 v86, v86
	v_cvt_f32_u32_e32 v125, v120
	v_mul_f32_e32 v87, v95, v87
	v_mul_f32_e32 v38, v95, v38
	v_exp_f32_e32 v39, v39
	v_exp_f32_e32 v126, v87
	v_mul_f32_e32 v86, v71, v86
	v_sub_u32_e32 v87, 0, v120
	v_exp_f32_e32 v38, v38
	v_exp_f32_e32 v127, v86
	v_mul_f32_e32 v86, v95, v125
	v_cvt_f32_u32_e32 v125, v87
	v_exp_f32_e32 v86, v86
	v_cmp_lt_i32_e32 vcc, -1, v100
	v_sub_u32_e32 v99, v96, v99
	v_mul_f32_e32 v125, v71, v125
	v_cndmask_b32_e32 v39, 0, v39, vcc
	v_cmp_lt_i32_e32 vcc, -1, v102
	v_exp_f32_e32 v125, v125
	v_lshl_add_u64 v[62:63], v[78:79], 0, v[84:85]
	v_cndmask_b32_e32 v38, 0, v38, vcc
	v_cmp_lt_i32_e32 vcc, -1, v120
	s_add_i32 s8, s8, s84
	s_nop 0
	v_cndmask_b32_e32 v87, 0, v86, vcc
	v_cmp_lt_i32_e32 vcc, -1, v37
	s_nop 1
	v_cndmask_b32_e32 v86, 0, v126, vcc
	v_cmp_gt_i32_e32 vcc, 1, v100
	s_nop 1
	v_cndmask_b32_e32 v101, 0, v101, vcc
	v_cmp_gt_i32_e32 vcc, 1, v102
	v_sub_u32_e32 v102, v96, v124
	s_nop 0
	v_cndmask_b32_e32 v100, 0, v121, vcc
	v_cmp_gt_i32_e32 vcc, 1, v120
	v_pk_add_f32 v[38:39], v[38:39], v[100:101]
	v_sub_u32_e32 v100, v96, v123
	v_cndmask_b32_e32 v121, 0, v125, vcc
	v_cmp_gt_i32_e32 vcc, 1, v37
	v_pk_mul_f32 v[38:39], v[56:57], v[38:39]
	v_sub_u32_e32 v37, v96, v122
	v_cndmask_b32_e32 v120, 0, v127, vcc
	v_pk_add_f32 v[86:87], v[86:87], v[120:121]
	v_cvt_f32_u32_e32 v121, v99
	v_pk_mul_f32 v[56:57], v[58:59], v[86:87]
	v_sub_u32_e32 v87, 0, v100
	v_cvt_pk_bf16_f32 v57, v56, v57
	v_cvt_pk_bf16_f32 v56, v38, v39
	v_sub_u32_e32 v39, 0, v102
	v_cvt_f32_u32_e32 v39, v39
	v_cvt_f32_u32_e32 v86, v100
	v_cvt_f32_u32_e32 v87, v87
	v_cvt_f32_u32_e32 v38, v102
	v_mul_f32_e32 v39, v71, v39
	v_exp_f32_e32 v120, v39
	v_mul_f32_e32 v39, v95, v86
	v_mul_f32_e32 v86, v71, v87
	v_cvt_f32_u32_e32 v87, v37
	v_exp_f32_e32 v101, v86
	v_sub_u32_e32 v86, 0, v37
	v_cvt_f32_u32_e32 v86, v86
	v_mul_f32_e32 v87, v95, v87
	v_mul_f32_e32 v38, v95, v38
	v_exp_f32_e32 v39, v39
	v_exp_f32_e32 v122, v87
	v_mul_f32_e32 v86, v71, v86
	v_sub_u32_e32 v87, 0, v99
	v_exp_f32_e32 v38, v38
	v_exp_f32_e32 v123, v86
	v_mul_f32_e32 v86, v95, v121
	v_cvt_f32_u32_e32 v121, v87
	v_exp_f32_e32 v86, v86
	v_cmp_lt_i32_e32 vcc, -1, v100
	v_lshl_add_u64 v[58:59], v[76:77], 0, v[84:85]
	v_mul_f32_e32 v121, v71, v121
	v_cndmask_b32_e32 v39, 0, v39, vcc
	v_cmp_lt_i32_e32 vcc, -1, v102
	v_exp_f32_e32 v121, v121
	s_nop 0
	v_cndmask_b32_e32 v38, 0, v38, vcc
	v_cmp_lt_i32_e32 vcc, -1, v99
	s_nop 1
	v_cndmask_b32_e32 v87, 0, v86, vcc
	v_cmp_lt_i32_e32 vcc, -1, v37
	s_nop 1
	v_cndmask_b32_e32 v86, 0, v122, vcc
	v_cmp_gt_i32_e32 vcc, 1, v100
	s_nop 1
	v_cndmask_b32_e32 v101, 0, v101, vcc
	v_cmp_gt_i32_e32 vcc, 1, v102
	v_or_b32_e32 v102, 35, v124
	s_nop 0
	v_cndmask_b32_e32 v100, 0, v120, vcc
	v_cmp_gt_i32_e32 vcc, 1, v99
	v_pk_add_f32 v[38:39], v[38:39], v[100:101]
	v_or_b32_e32 v101, 32, v124
	v_cndmask_b32_e32 v121, 0, v121, vcc
	v_cmp_gt_i32_e32 vcc, 1, v37
	v_or_b32_e32 v99, 33, v124
	v_sub_u32_e32 v122, v103, v101
	v_cndmask_b32_e32 v120, 0, v123, vcc
	v_pk_add_f32 v[86:87], v[86:87], v[120:121]
	v_pk_mul_f32 v[38:39], v[52:53], v[38:39]
	v_pk_mul_f32 v[52:53], v[54:55], v[86:87]
	v_sub_u32_e32 v87, 0, v122
	v_sub_u32_e32 v123, v103, v99
	v_cvt_f32_u32_e32 v87, v87
	v_sub_u32_e32 v121, 0, v123
	v_cvt_f32_u32_e32 v120, v123
	v_cvt_f32_u32_e32 v121, v121
	v_or_b32_e32 v100, 34, v124
	v_mul_f32_e32 v87, v71, v87
	v_sub_u32_e32 v125, v103, v100
	v_exp_f32_e32 v126, v87
	v_mul_f32_e32 v87, v95, v120
	v_mul_f32_e32 v120, v71, v121
	v_cvt_f32_u32_e32 v121, v125
	v_exp_f32_e32 v127, v120
	v_sub_u32_e32 v120, 0, v125
	v_sub_u32_e32 v37, v103, v102
	v_cvt_f32_u32_e32 v86, v122
	v_cvt_f32_u32_e32 v120, v120
	v_cvt_f32_u32_e32 v128, v37
	v_mul_f32_e32 v121, v95, v121
	v_mul_f32_e32 v86, v95, v86
	v_exp_f32_e32 v87, v87
	v_exp_f32_e32 v129, v121
	v_mul_f32_e32 v120, v71, v120
	v_sub_u32_e32 v121, 0, v37
	v_exp_f32_e32 v86, v86
	v_exp_f32_e32 v130, v120
	v_mul_f32_e32 v120, v95, v128
	v_cvt_f32_u32_e32 v128, v121
	v_exp_f32_e32 v120, v120
	v_cmp_lt_i32_e32 vcc, -1, v123
	v_cvt_pk_bf16_f32 v53, v52, v53
	v_mul_f32_e32 v128, v71, v128
	v_cndmask_b32_e32 v87, 0, v87, vcc
	v_cmp_lt_i32_e32 vcc, -1, v122
	v_exp_f32_e32 v128, v128
	v_cvt_pk_bf16_f32 v52, v38, v39
	v_cndmask_b32_e32 v86, 0, v86, vcc
	v_cmp_lt_i32_e32 vcc, -1, v37
	v_lshlrev_b32_e32 v38, 1, v101
	v_mov_b32_e32 v39, v69
	v_cndmask_b32_e32 v121, 0, v120, vcc
	v_cmp_lt_i32_e32 vcc, -1, v125
	v_lshl_add_u64 v[54:55], v[74:75], 0, v[84:85]
	v_lshl_add_u64 v[84:85], v[80:81], 0, v[38:39]
	v_cndmask_b32_e32 v120, 0, v129, vcc
	v_cmp_gt_i32_e32 vcc, 1, v123
	s_nop 1
	v_cndmask_b32_e32 v123, 0, v127, vcc
	v_cmp_gt_i32_e32 vcc, 1, v122
	s_nop 1
	v_cndmask_b32_e32 v122, 0, v126, vcc
	v_cmp_gt_i32_e32 vcc, 1, v37
	v_pk_add_f32 v[86:87], v[86:87], v[122:123]
	v_sub_u32_e32 v37, v97, v102
	v_cndmask_b32_e32 v127, 0, v128, vcc
	v_cmp_gt_i32_e32 vcc, 1, v125
	v_pk_mul_f32 v[48:49], v[48:49], v[86:87]
	v_or_b32_e32 v122, 16, v124
	v_cndmask_b32_e32 v126, 0, v130, vcc
	v_pk_add_f32 v[120:121], v[120:121], v[126:127]
	v_sub_u32_e32 v130, v103, v122
	v_pk_mul_f32 v[50:51], v[50:51], v[120:121]
	v_or_b32_e32 v120, 17, v124
	v_cvt_pk_bf16_f32 v51, v50, v51
	v_cvt_pk_bf16_f32 v50, v48, v49
	v_cvt_f32_u32_e32 v48, v37
	v_sub_u32_e32 v49, 0, v37
	v_cvt_f32_u32_e32 v49, v49
	v_sub_u32_e32 v127, 0, v130
	v_mul_f32_e32 v48, v95, v48
	v_sub_u32_e32 v131, v103, v120
	v_exp_f32_e32 v48, v48
	v_mul_f32_e32 v49, v71, v49
	v_cvt_f32_u32_e32 v127, v127
	v_sub_u32_e32 v129, 0, v131
	v_exp_f32_e32 v49, v49
	v_cvt_f32_u32_e32 v128, v131
	v_cvt_f32_u32_e32 v129, v129
	v_cmp_lt_i32_e32 vcc, -1, v37
	v_or_b32_e32 v121, 18, v124
	v_mul_f32_e32 v127, v71, v127
	v_cndmask_b32_e32 v48, 0, v48, vcc
	v_cmp_gt_i32_e32 vcc, 1, v37
	v_sub_u32_e32 v125, v103, v121
	v_exp_f32_e32 v132, v127
	v_cndmask_b32_e32 v37, 0, v49, vcc
	v_mul_f32_e32 v127, v95, v128
	v_mul_f32_e32 v128, v71, v129
	v_add_f32_e32 v37, v48, v37
	v_or_b32_e32 v123, 19, v124
	v_cvt_f32_u32_e32 v129, v125
	v_exp_f32_e32 v133, v128
	v_sub_u32_e32 v128, 0, v125
	v_mul_f32_e32 v11, v11, v37
	v_sub_u32_e32 v37, v103, v123
	v_cvt_f32_u32_e32 v126, v130
	v_cvt_f32_u32_e32 v128, v128
	v_cvt_f32_u32_e32 v134, v37
	v_mul_f32_e32 v129, v95, v129
	v_mul_f32_e32 v126, v95, v126
	v_exp_f32_e32 v127, v127
	v_exp_f32_e32 v135, v129
	v_mul_f32_e32 v128, v71, v128
	v_sub_u32_e32 v129, 0, v37
	v_exp_f32_e32 v126, v126
	v_exp_f32_e32 v136, v128
	v_mul_f32_e32 v128, v95, v134
	v_cvt_f32_u32_e32 v134, v129
	v_exp_f32_e32 v128, v128
	v_cmp_lt_i32_e32 vcc, -1, v131
	global_store_dwordx2 v[84:85], v[50:51], off
	v_mul_f32_e32 v134, v71, v134
	v_cndmask_b32_e32 v127, 0, v127, vcc
	v_cmp_lt_i32_e32 vcc, -1, v130
	v_exp_f32_e32 v134, v134
	v_lshlrev_b32_e32 v50, 1, v122
	v_cndmask_b32_e32 v126, 0, v126, vcc
	v_cmp_lt_i32_e32 vcc, -1, v37
	v_mov_b32_e32 v51, v69
	v_lshl_add_u64 v[86:87], v[80:81], 0, v[50:51]
	v_cndmask_b32_e32 v129, 0, v128, vcc
	v_cmp_lt_i32_e32 vcc, -1, v125
	v_lshl_add_u64 v[84:85], v[78:79], 0, v[38:39]
	v_cvt_pk_bf16_f32 v11, v11, s0
	v_cndmask_b32_e32 v128, 0, v135, vcc
	v_cmp_gt_i32_e32 vcc, 1, v131
	v_lshl_add_u64 v[48:49], v[76:77], 0, v[38:39]
	s_nop 0
	v_cndmask_b32_e32 v131, 0, v133, vcc
	v_cmp_gt_i32_e32 vcc, 1, v130
	s_nop 1
	v_cndmask_b32_e32 v130, 0, v132, vcc
	v_cmp_gt_i32_e32 vcc, 1, v37
	v_pk_add_f32 v[126:127], v[126:127], v[130:131]
	v_sub_u32_e32 v37, v98, v123
	v_cndmask_b32_e32 v133, 0, v134, vcc
	v_cmp_gt_i32_e32 vcc, 1, v125
	v_pk_mul_f32 v[44:45], v[44:45], v[126:127]
	v_sub_u32_e32 v125, v96, v121
	v_cndmask_b32_e32 v132, 0, v136, vcc
	v_pk_add_f32 v[128:129], v[128:129], v[132:133]
	v_cmp_lt_i32_e32 vcc, -1, v37
	v_pk_mul_f32 v[46:47], v[46:47], v[128:129]
	v_sub_u32_e32 v128, v96, v122
	v_cvt_pk_bf16_f32 v47, v46, v47
	v_cvt_pk_bf16_f32 v46, v44, v45
	v_cvt_f32_u32_e32 v44, v37
	v_sub_u32_e32 v45, 0, v37
	v_cvt_f32_u32_e32 v45, v45
	global_store_dwordx2 v[86:87], v[46:47], off
	v_mul_f32_e32 v44, v95, v44
	v_sub_u32_e32 v47, 0, v128
	v_sub_u32_e32 v129, v96, v120
	v_exp_f32_e32 v44, v44
	v_mul_f32_e32 v45, v71, v45
	v_cvt_f32_u32_e32 v47, v47
	v_sub_u32_e32 v127, 0, v129
	v_exp_f32_e32 v45, v45
	v_cvt_f32_u32_e32 v126, v129
	v_cvt_f32_u32_e32 v127, v127
	v_cndmask_b32_e32 v44, 0, v44, vcc
	v_cmp_gt_i32_e32 vcc, 1, v37
	v_mul_f32_e32 v47, v71, v47
	v_exp_f32_e32 v130, v47
	v_cndmask_b32_e32 v37, 0, v45, vcc
	v_mul_f32_e32 v47, v95, v126
	v_mul_f32_e32 v126, v71, v127
	v_add_f32_e32 v37, v44, v37
	v_cvt_f32_u32_e32 v127, v125
	v_exp_f32_e32 v131, v126
	v_sub_u32_e32 v126, 0, v125
	v_mul_f32_e32 v27, v27, v37
	v_sub_u32_e32 v37, v96, v123
	v_cvt_f32_u32_e32 v46, v128
	v_cvt_f32_u32_e32 v126, v126
	v_cvt_f32_u32_e32 v132, v37
	v_mul_f32_e32 v127, v95, v127
	v_mul_f32_e32 v46, v95, v46
	v_exp_f32_e32 v47, v47
	v_exp_f32_e32 v133, v127
	v_mul_f32_e32 v126, v71, v126
	v_sub_u32_e32 v127, 0, v37
	v_exp_f32_e32 v46, v46
	v_exp_f32_e32 v134, v126
	v_mul_f32_e32 v126, v95, v132
	v_cvt_f32_u32_e32 v132, v127
	v_exp_f32_e32 v126, v126
	v_cmp_lt_i32_e32 vcc, -1, v129
	v_lshl_add_u64 v[86:87], v[78:79], 0, v[50:51]
	v_mul_f32_e32 v132, v71, v132
	v_cndmask_b32_e32 v47, 0, v47, vcc
	v_cmp_lt_i32_e32 vcc, -1, v128
	v_exp_f32_e32 v132, v132
	v_cvt_pk_bf16_f32 v27, v27, s0
	v_cndmask_b32_e32 v46, 0, v46, vcc
	v_cmp_lt_i32_e32 vcc, -1, v37
	v_lshl_add_u64 v[44:45], v[76:77], 0, v[50:51]
	v_lshl_add_u64 v[50:51], v[74:75], 0, v[50:51]
	v_cndmask_b32_e32 v127, 0, v126, vcc
	v_cmp_lt_i32_e32 vcc, -1, v125
	s_nop 1
	v_cndmask_b32_e32 v126, 0, v133, vcc
	v_cmp_gt_i32_e32 vcc, 1, v129
	v_or_b32_e32 v133, 51, v124
	s_nop 0
	v_cndmask_b32_e32 v129, 0, v131, vcc
	v_cmp_gt_i32_e32 vcc, 1, v128
	s_nop 1
	v_cndmask_b32_e32 v128, 0, v130, vcc
	v_cmp_gt_i32_e32 vcc, 1, v37
	v_pk_add_f32 v[46:47], v[46:47], v[128:129]
	v_sub_u32_e32 v37, v96, v133
	v_cndmask_b32_e32 v131, 0, v132, vcc
	v_cmp_gt_i32_e32 vcc, 1, v125
	v_pk_mul_f32 v[40:41], v[40:41], v[46:47]
	v_or_b32_e32 v132, 50, v124
	v_cndmask_b32_e32 v130, 0, v134, vcc
	v_pk_add_f32 v[126:127], v[126:127], v[130:131]
	v_or_b32_e32 v130, 48, v124
	v_or_b32_e32 v131, 49, v124
	v_sub_u32_e32 v124, v103, v124
	v_pk_mul_f32 v[42:43], v[42:43], v[126:127]
	v_cvt_pk_bf16_f32 v46, v40, v41
	v_sub_u32_e32 v41, 0, v124
	v_sub_u32_e32 v125, v96, v131
	v_cvt_pk_bf16_f32 v47, v42, v43
	v_cvt_f32_u32_e32 v41, v41
	v_sub_u32_e32 v43, 0, v125
	v_cvt_f32_u32_e32 v42, v125
	v_cvt_f32_u32_e32 v43, v43
	v_cvt_f32_u32_e32 v40, v124
	v_mul_f32_e32 v41, v71, v41
	v_sub_u32_e32 v126, v96, v132
	v_exp_f32_e32 v127, v41
	v_mul_f32_e32 v41, v95, v42
	v_mul_f32_e32 v42, v71, v43
	v_exp_f32_e32 v128, v42
	v_sub_u32_e32 v42, 0, v126
	v_cvt_f32_u32_e32 v43, v126
	v_cvt_f32_u32_e32 v42, v42
	v_mul_f32_e32 v40, v95, v40
	v_exp_f32_e32 v41, v41
	v_cvt_f32_u32_e32 v129, v37
	v_exp_f32_e32 v40, v40
	v_mul_f32_e32 v43, v95, v43
	v_mul_f32_e32 v42, v71, v42
	v_cmp_lt_i32_e32 vcc, -1, v125
	v_exp_f32_e32 v134, v43
	v_exp_f32_e32 v135, v42
	v_mul_f32_e32 v42, v95, v129
	v_cndmask_b32_e32 v43, 0, v41, vcc
	v_cmp_lt_i32_e32 vcc, -1, v124
	v_exp_f32_e32 v129, v42
	s_nop 0
	v_cndmask_b32_e32 v42, 0, v40, vcc
	v_sub_u32_e32 v40, 0, v37
	v_cvt_f32_u32_e32 v136, v40
	v_cmp_lt_i32_e32 vcc, -1, v37
	s_nop 1
	v_cndmask_b32_e32 v41, 0, v129, vcc
	v_mul_f32_e32 v129, v71, v136
	v_cmp_lt_i32_e32 vcc, -1, v126
	v_exp_f32_e32 v129, v129
	s_nop 0
	v_cndmask_b32_e32 v40, 0, v134, vcc
	v_cmp_gt_i32_e32 vcc, 1, v125
	v_sub_u32_e32 v134, v103, v132
	s_nop 0
	v_cndmask_b32_e32 v125, 0, v128, vcc
	v_cmp_gt_i32_e32 vcc, 1, v124
	v_sub_u32_e32 v128, v103, v133
	s_nop 0
	v_cndmask_b32_e32 v124, 0, v127, vcc
	v_cmp_gt_i32_e32 vcc, 1, v37
	v_pk_add_f32 v[42:43], v[42:43], v[124:125]
	v_mov_b32_e32 v37, v69
	v_cndmask_b32_e32 v127, 0, v129, vcc
	v_cmp_gt_i32_e32 vcc, 1, v126
	v_mul_f32_e32 v36, v36, v42
	v_cvt_pk_bf16_f32 v36, v36, s0
	v_cndmask_b32_e32 v126, 0, v135, vcc
	v_pk_add_f32 v[40:41], v[40:41], v[126:127]
	v_sub_u32_e32 v126, v103, v130
	global_store_short v[82:83], v36, off
	v_sub_u32_e32 v83, 0, v126
	v_sub_u32_e32 v103, v103, v131
	v_cvt_f32_u32_e32 v83, v83
	v_sub_u32_e32 v125, 0, v103
	v_cvt_f32_u32_e32 v124, v103
	v_cvt_f32_u32_e32 v125, v125
	v_mul_f32_e32 v83, v71, v83
	v_exp_f32_e32 v129, v83
	v_mul_f32_e32 v83, v95, v124
	v_mul_f32_e32 v124, v71, v125
	v_cvt_f32_u32_e32 v125, v134
	v_exp_f32_e32 v127, v124
	v_sub_u32_e32 v124, 0, v134
	v_cvt_f32_u32_e32 v82, v126
	v_cvt_f32_u32_e32 v124, v124
	v_cvt_f32_u32_e32 v135, v128
	v_mul_f32_e32 v125, v95, v125
	v_mul_f32_e32 v82, v95, v82
	v_exp_f32_e32 v83, v83
	v_exp_f32_e32 v136, v125
	v_mul_f32_e32 v124, v71, v124
	v_sub_u32_e32 v125, 0, v128
	v_exp_f32_e32 v82, v82
	v_exp_f32_e32 v137, v124
	v_mul_f32_e32 v124, v95, v135
	v_cvt_f32_u32_e32 v135, v125
	v_exp_f32_e32 v124, v124
	v_cmp_lt_i32_e32 vcc, -1, v103
	v_lshlrev_b32_e32 v36, 1, v130
	v_mul_f32_e32 v135, v71, v135
	v_cndmask_b32_e32 v83, 0, v83, vcc
	v_cmp_lt_i32_e32 vcc, -1, v126
	v_exp_f32_e32 v135, v135
	v_lshl_add_u64 v[80:81], v[80:81], 0, v[36:37]
	v_cndmask_b32_e32 v82, 0, v82, vcc
	v_cmp_lt_i32_e32 vcc, -1, v128
	v_mul_f32_e32 v24, v24, v42
	v_mul_f32_e32 v8, v8, v42
	v_cndmask_b32_e32 v125, 0, v124, vcc
	v_cmp_lt_i32_e32 vcc, -1, v134
	v_pk_mul_f32 v[0:1], v[0:1], v[42:43]
	v_pk_mul_f32 v[2:3], v[2:3], v[40:41]
	v_cndmask_b32_e32 v124, 0, v136, vcc
	v_cmp_gt_i32_e32 vcc, 1, v103
	v_cvt_pk_bf16_f32 v103, v24, s0
	v_sub_u32_e32 v24, v97, v132
	v_cndmask_b32_e32 v127, 0, v127, vcc
	v_cmp_gt_i32_e32 vcc, 1, v126
	v_cvt_pk_bf16_f32 v3, v2, v3
	v_cvt_pk_bf16_f32 v2, v0, v1
	v_cndmask_b32_e32 v126, 0, v129, vcc
	v_cmp_gt_i32_e32 vcc, 1, v128
	v_pk_add_f32 v[82:83], v[82:83], v[126:127]
	v_lshl_add_u64 v[0:1], v[74:75], 0, v[36:37]
	v_cndmask_b32_e32 v129, 0, v135, vcc
	v_cmp_gt_i32_e32 vcc, 1, v134
	v_pk_mul_f32 v[32:33], v[32:33], v[82:83]
	s_nop 0
	v_cndmask_b32_e32 v128, 0, v137, vcc
	v_pk_add_f32 v[124:125], v[124:125], v[128:129]
	s_nop 0
	v_pk_mul_f32 v[34:35], v[34:35], v[124:125]
	v_cvt_pk_bf16_f32 v124, v8, s0
	v_cvt_pk_bf16_f32 v35, v34, v35
	v_cvt_pk_bf16_f32 v34, v32, v33
	global_store_dwordx2 v[80:81], v[34:35], off
	v_sub_u32_e32 v80, v97, v130
	v_sub_u32_e32 v35, 0, v80
	v_sub_u32_e32 v81, v97, v131
	v_lshl_add_u64 v[32:33], v[78:79], 0, v[36:37]
	v_cvt_f32_u32_e32 v35, v35
	v_sub_u32_e32 v79, 0, v81
	v_cvt_f32_u32_e32 v78, v81
	v_cvt_f32_u32_e32 v79, v79
	v_mul_f32_e32 v35, v71, v35
	v_exp_f32_e32 v82, v35
	v_mul_f32_e32 v35, v95, v78
	v_mul_f32_e32 v78, v71, v79
	v_cvt_f32_u32_e32 v79, v24
	v_exp_f32_e32 v83, v78
	v_sub_u32_e32 v78, 0, v24
	v_sub_u32_e32 v8, v97, v133
	v_cvt_f32_u32_e32 v34, v80
	v_cvt_f32_u32_e32 v78, v78
	v_cvt_f32_u32_e32 v125, v8
	v_mul_f32_e32 v79, v95, v79
	v_mul_f32_e32 v34, v95, v34
	v_exp_f32_e32 v35, v35
	v_exp_f32_e32 v126, v79
	v_mul_f32_e32 v78, v71, v78
	v_sub_u32_e32 v79, 0, v8
	v_exp_f32_e32 v34, v34
	v_exp_f32_e32 v127, v78
	v_mul_f32_e32 v78, v95, v125
	v_cvt_f32_u32_e32 v125, v79
	v_exp_f32_e32 v78, v78
	v_cmp_lt_i32_e32 vcc, -1, v81
	global_store_dwordx2 v[62:63], v[60:61], off
	v_mul_f32_e32 v125, v71, v125
	v_cndmask_b32_e32 v35, 0, v35, vcc
	v_cmp_lt_i32_e32 vcc, -1, v80
	v_exp_f32_e32 v125, v125
	s_mov_b32 s0, 0x5040100
	v_cndmask_b32_e32 v34, 0, v34, vcc
	v_cmp_lt_i32_e32 vcc, -1, v8
	s_nop 1
	v_cndmask_b32_e32 v79, 0, v78, vcc
	v_cmp_lt_i32_e32 vcc, -1, v24
	s_nop 1
	v_cndmask_b32_e32 v78, 0, v126, vcc
	v_cmp_gt_i32_e32 vcc, 1, v81
	s_nop 1
	v_cndmask_b32_e32 v81, 0, v83, vcc
	v_cmp_gt_i32_e32 vcc, 1, v80
	s_nop 1
	v_cndmask_b32_e32 v80, 0, v82, vcc
	v_cmp_gt_i32_e32 vcc, 1, v8
	v_sub_u32_e32 v8, v98, v121
	v_cvt_f32_u32_e32 v60, v8
	v_cndmask_b32_e32 v83, 0, v125, vcc
	v_cmp_gt_i32_e32 vcc, 1, v24
	v_pk_add_f32 v[34:35], v[34:35], v[80:81]
	v_sub_u32_e32 v24, v98, v120
	v_cndmask_b32_e32 v82, 0, v127, vcc
	v_pk_add_f32 v[78:79], v[78:79], v[82:83]
	v_pk_mul_f32 v[34:35], v[28:29], v[34:35]
	v_pk_mul_f32 v[28:29], v[30:31], v[78:79]
	v_mul_f32_e32 v60, v95, v60
	v_cvt_pk_bf16_f32 v29, v28, v29
	v_cvt_pk_bf16_f32 v28, v34, v35
	v_sub_u32_e32 v35, 0, v24
	v_cvt_f32_u32_e32 v34, v24
	v_cvt_f32_u32_e32 v35, v35
	v_sub_u32_e32 v61, 0, v8
	v_exp_f32_e32 v60, v60
	v_cvt_f32_u32_e32 v61, v61
	v_mul_f32_e32 v34, v95, v34
	v_mul_f32_e32 v35, v71, v35
	v_cmp_lt_i32_e32 vcc, -1, v8
	v_exp_f32_e32 v34, v34
	v_exp_f32_e32 v62, v35
	v_cndmask_b32_e32 v35, 0, v60, vcc
	v_mul_f32_e32 v60, v71, v61
	v_exp_f32_e32 v60, v60
	v_cmp_lt_i32_e32 vcc, -1, v24
	v_lshl_add_u64 v[30:31], v[76:77], 0, v[36:37]
	s_nop 0
	v_cndmask_b32_e32 v34, 0, v34, vcc
	v_cmp_gt_i32_e32 vcc, 1, v8
	s_nop 1
	v_cndmask_b32_e32 v61, 0, v60, vcc
	v_cmp_gt_i32_e32 vcc, 1, v24
	v_mov_b32_e32 v24, v25
	v_mov_b32_e32 v25, v26
	v_cndmask_b32_e32 v60, 0, v62, vcc
	v_pk_add_f32 v[34:35], v[34:35], v[60:61]
	v_sub_u32_e32 v60, v98, v100
	v_pk_mul_f32 v[24:25], v[24:25], v[34:35]
	v_sub_u32_e32 v34, v98, v101
	v_cvt_pk_bf16_f32 v8, v24, v25
	v_perm_b32 v24, v8, v103, s0
	v_alignbit_b32 v25, v27, v8, 16
	global_store_dwordx2 v[86:87], v[24:25], off
	v_sub_u32_e32 v25, 0, v34
	v_sub_u32_e32 v35, v98, v99
	v_cvt_f32_u32_e32 v25, v25
	v_sub_u32_e32 v27, 0, v35
	v_cvt_f32_u32_e32 v26, v35
	v_cvt_f32_u32_e32 v27, v27
	v_mul_f32_e32 v25, v71, v25
	v_exp_f32_e32 v61, v25
	v_mul_f32_e32 v25, v95, v26
	v_mul_f32_e32 v26, v71, v27
	v_cvt_f32_u32_e32 v27, v60
	v_exp_f32_e32 v62, v26
	v_sub_u32_e32 v26, 0, v60
	v_sub_u32_e32 v8, v98, v102
	v_cvt_f32_u32_e32 v24, v34
	v_cvt_f32_u32_e32 v26, v26
	v_cvt_f32_u32_e32 v63, v8
	v_mul_f32_e32 v27, v95, v27
	v_mul_f32_e32 v24, v95, v24
	v_exp_f32_e32 v25, v25
	v_exp_f32_e32 v76, v27
	v_mul_f32_e32 v26, v71, v26
	v_sub_u32_e32 v27, 0, v8
	v_exp_f32_e32 v24, v24
	v_exp_f32_e32 v77, v26
	v_mul_f32_e32 v26, v95, v63
	v_cvt_f32_u32_e32 v63, v27
	v_exp_f32_e32 v26, v26
	v_cmp_lt_i32_e32 vcc, -1, v35
	v_mul_f32_e32 v63, v71, v63
	s_nop 0
	v_cndmask_b32_e32 v25, 0, v25, vcc
	v_cmp_lt_i32_e32 vcc, -1, v34
	v_exp_f32_e32 v63, v63
	s_nop 0
	v_cndmask_b32_e32 v24, 0, v24, vcc
	v_cmp_lt_i32_e32 vcc, -1, v8
	s_nop 1
	v_cndmask_b32_e32 v27, 0, v26, vcc
	v_cmp_lt_i32_e32 vcc, -1, v60
	s_nop 1
	v_cndmask_b32_e32 v26, 0, v76, vcc
	v_cmp_gt_i32_e32 vcc, 1, v35
	s_nop 1
	v_cndmask_b32_e32 v35, 0, v62, vcc
	v_cmp_gt_i32_e32 vcc, 1, v34
	s_nop 1
	v_cndmask_b32_e32 v34, 0, v61, vcc
	v_cmp_gt_i32_e32 vcc, 1, v8
	v_pk_add_f32 v[24:25], v[24:25], v[34:35]
	v_sub_u32_e32 v8, v98, v133
	v_cndmask_b32_e32 v61, 0, v63, vcc
	v_cmp_gt_i32_e32 vcc, 1, v60
	v_pk_mul_f32 v[20:21], v[20:21], v[24:25]
	v_sub_u32_e32 v24, v98, v130
	v_cndmask_b32_e32 v60, 0, v77, vcc
	v_pk_add_f32 v[26:27], v[26:27], v[60:61]
	v_sub_u32_e32 v25, v98, v131
	v_pk_mul_f32 v[22:23], v[22:23], v[26:27]
	v_sub_u32_e32 v26, v98, v132
	v_cvt_pk_bf16_f32 v23, v22, v23
	v_cvt_pk_bf16_f32 v22, v20, v21
	v_sub_u32_e32 v21, 0, v24
	global_store_dwordx2 v[84:85], v[22:23], off
	v_cvt_f32_u32_e32 v21, v21
	v_sub_u32_e32 v23, 0, v25
	v_cvt_f32_u32_e32 v22, v25
	v_cvt_f32_u32_e32 v23, v23
	v_mul_f32_e32 v21, v71, v21
	v_exp_f32_e32 v27, v21
	v_mul_f32_e32 v21, v95, v22
	v_mul_f32_e32 v22, v71, v23
	v_cvt_f32_u32_e32 v23, v26
	v_exp_f32_e32 v34, v22
	v_sub_u32_e32 v22, 0, v26
	v_cvt_f32_u32_e32 v20, v24
	v_cvt_f32_u32_e32 v22, v22
	v_cvt_f32_u32_e32 v35, v8
	v_mul_f32_e32 v23, v95, v23
	v_mul_f32_e32 v20, v95, v20
	v_exp_f32_e32 v21, v21
	v_exp_f32_e32 v60, v23
	v_mul_f32_e32 v22, v71, v22
	v_sub_u32_e32 v23, 0, v8
	v_exp_f32_e32 v20, v20
	v_exp_f32_e32 v61, v22
	v_mul_f32_e32 v22, v95, v35
	v_cvt_f32_u32_e32 v35, v23
	v_exp_f32_e32 v22, v22
	v_cmp_lt_i32_e32 vcc, -1, v25
	v_mul_f32_e32 v35, v71, v35
	s_nop 0
	v_cndmask_b32_e32 v21, 0, v21, vcc
	v_cmp_lt_i32_e32 vcc, -1, v24
	v_exp_f32_e32 v35, v35
	s_nop 0
	v_cndmask_b32_e32 v20, 0, v20, vcc
	v_cmp_lt_i32_e32 vcc, -1, v8
	s_nop 1
	v_cndmask_b32_e32 v23, 0, v22, vcc
	v_cmp_lt_i32_e32 vcc, -1, v26
	s_nop 1
	v_cndmask_b32_e32 v22, 0, v60, vcc
	v_cmp_gt_i32_e32 vcc, 1, v25
	s_nop 1
	v_cndmask_b32_e32 v25, 0, v34, vcc
	v_cmp_gt_i32_e32 vcc, 1, v24
	s_nop 1
	v_cndmask_b32_e32 v24, 0, v27, vcc
	v_cmp_gt_i32_e32 vcc, 1, v8
	v_pk_add_f32 v[20:21], v[20:21], v[24:25]
	v_sub_u32_e32 v8, v97, v123
	v_cndmask_b32_e32 v27, 0, v35, vcc
	v_cmp_gt_i32_e32 vcc, 1, v26
	v_pk_mul_f32 v[16:17], v[16:17], v[20:21]
	v_sub_u32_e32 v20, v97, v122
	v_cndmask_b32_e32 v26, 0, v61, vcc
	v_pk_add_f32 v[22:23], v[22:23], v[26:27]
	v_sub_u32_e32 v21, v97, v120
	v_pk_mul_f32 v[18:19], v[18:19], v[22:23]
	v_sub_u32_e32 v22, v97, v121
	v_cvt_pk_bf16_f32 v19, v18, v19
	v_cvt_pk_bf16_f32 v18, v16, v17
	v_sub_u32_e32 v17, 0, v20
	global_store_dwordx2 v[32:33], v[18:19], off
	global_store_dwordx2 v[58:59], v[56:57], off
	v_cvt_f32_u32_e32 v17, v17
	v_sub_u32_e32 v19, 0, v21
	v_cvt_f32_u32_e32 v18, v21
	v_cvt_f32_u32_e32 v19, v19
	v_mul_f32_e32 v17, v71, v17
	v_exp_f32_e32 v23, v17
	v_mul_f32_e32 v17, v95, v18
	v_mul_f32_e32 v18, v71, v19
	v_cvt_f32_u32_e32 v19, v22
	v_exp_f32_e32 v24, v18
	v_sub_u32_e32 v18, 0, v22
	v_cvt_f32_u32_e32 v16, v20
	v_cvt_f32_u32_e32 v18, v18
	v_cvt_f32_u32_e32 v25, v8
	v_mul_f32_e32 v19, v95, v19
	v_mul_f32_e32 v16, v95, v16
	v_exp_f32_e32 v17, v17
	v_exp_f32_e32 v26, v19
	v_mul_f32_e32 v18, v71, v18
	v_sub_u32_e32 v19, 0, v8
	v_exp_f32_e32 v16, v16
	v_exp_f32_e32 v27, v18
	v_mul_f32_e32 v18, v95, v25
	v_cvt_f32_u32_e32 v25, v19
	v_exp_f32_e32 v18, v18
	v_cmp_lt_i32_e32 vcc, -1, v21
	v_mul_f32_e32 v25, v71, v25
	s_nop 0
	v_cndmask_b32_e32 v17, 0, v17, vcc
	v_cmp_lt_i32_e32 vcc, -1, v20
	v_exp_f32_e32 v25, v25
	s_nop 0
	v_cndmask_b32_e32 v16, 0, v16, vcc
	v_cmp_lt_i32_e32 vcc, -1, v8
	s_nop 1
	v_cndmask_b32_e32 v19, 0, v18, vcc
	v_cmp_lt_i32_e32 vcc, -1, v22
	s_nop 1
	v_cndmask_b32_e32 v18, 0, v26, vcc
	v_cmp_gt_i32_e32 vcc, 1, v21
	s_nop 1
	v_cndmask_b32_e32 v21, 0, v24, vcc
	v_cmp_gt_i32_e32 vcc, 1, v20
	s_nop 1
	v_cndmask_b32_e32 v20, 0, v23, vcc
	v_cmp_gt_i32_e32 vcc, 1, v8
	v_pk_add_f32 v[16:17], v[16:17], v[20:21]
	v_sub_u32_e32 v8, v97, v100
	v_cndmask_b32_e32 v23, 0, v25, vcc
	v_cmp_gt_i32_e32 vcc, 1, v22
	v_pk_mul_f32 v[12:13], v[12:13], v[16:17]
	v_sub_u32_e32 v16, 0, v8
	v_cndmask_b32_e32 v22, 0, v27, vcc
	v_pk_add_f32 v[18:19], v[18:19], v[22:23]
	v_cvt_f32_u32_e32 v16, v16
	v_pk_mul_f32 v[14:15], v[14:15], v[18:19]
	v_cmp_lt_i32_e32 vcc, -1, v8
	v_cvt_pk_bf16_f32 v15, v14, v15
	v_cvt_pk_bf16_f32 v14, v12, v13
	global_store_dwordx2 v[44:45], v[14:15], off
	v_cvt_f32_u32_e32 v15, v8
	v_sub_u32_e32 v14, v97, v99
	v_sub_u32_e32 v13, 0, v14
	v_cvt_f32_u32_e32 v12, v14
	v_cvt_f32_u32_e32 v13, v13
	v_mul_f32_e32 v15, v95, v15
	v_exp_f32_e32 v15, v15
	v_mul_f32_e32 v12, v95, v12
	v_mul_f32_e32 v13, v71, v13
	v_exp_f32_e32 v12, v12
	v_exp_f32_e32 v17, v13
	v_cndmask_b32_e32 v13, 0, v15, vcc
	v_mul_f32_e32 v15, v71, v16
	v_exp_f32_e32 v15, v15
	v_cmp_lt_i32_e32 vcc, -1, v14
	v_sub_u32_e32 v16, v96, v100
	s_nop 0
	v_cndmask_b32_e32 v12, 0, v12, vcc
	v_cmp_gt_i32_e32 vcc, 1, v8
	v_mov_b32_e32 v8, v9
	v_mov_b32_e32 v9, v10
	v_cndmask_b32_e32 v15, 0, v15, vcc
	v_cmp_gt_i32_e32 vcc, 1, v14
	s_nop 1
	v_cndmask_b32_e32 v14, 0, v17, vcc
	v_pk_add_f32 v[12:13], v[12:13], v[14:15]
	v_sub_u32_e32 v14, v96, v102
	v_pk_mul_f32 v[8:9], v[8:9], v[12:13]
	v_sub_u32_e32 v12, v96, v101
	v_cvt_pk_bf16_f32 v9, v8, v9
	v_perm_b32 v8, v9, v124, s0
	v_alignbit_b32 v9, v11, v9, 16
	global_store_dwordx2 v[48:49], v[8:9], off
	global_store_dwordx2 v[30:31], v[28:29], off
	global_store_dwordx2 v[54:55], v[52:53], off
	global_store_dwordx2 v[50:51], v[46:47], off
	v_sub_u32_e32 v9, 0, v12
	v_sub_u32_e32 v13, v96, v99
	v_cvt_f32_u32_e32 v9, v9
	v_sub_u32_e32 v11, 0, v13
	v_cvt_f32_u32_e32 v10, v13
	v_cvt_f32_u32_e32 v11, v11
	v_mul_f32_e32 v9, v71, v9
	v_exp_f32_e32 v15, v9
	v_mul_f32_e32 v9, v95, v10
	v_mul_f32_e32 v10, v71, v11
	v_cvt_f32_u32_e32 v11, v16
	v_exp_f32_e32 v17, v10
	v_sub_u32_e32 v10, 0, v16
	v_cvt_f32_u32_e32 v8, v12
	v_cvt_f32_u32_e32 v10, v10
	v_cvt_f32_u32_e32 v18, v14
	v_mul_f32_e32 v11, v95, v11
	v_mul_f32_e32 v8, v95, v8
	v_exp_f32_e32 v9, v9
	v_exp_f32_e32 v19, v11
	v_mul_f32_e32 v10, v71, v10
	v_sub_u32_e32 v11, 0, v14
	v_exp_f32_e32 v8, v8
	v_exp_f32_e32 v20, v10
	v_mul_f32_e32 v10, v95, v18
	v_cvt_f32_u32_e32 v18, v11
	v_exp_f32_e32 v10, v10
	v_cmp_lt_i32_e32 vcc, -1, v13
	v_readlane_b32 s0, v181, 50
	v_mul_f32_e32 v18, v71, v18
	v_cndmask_b32_e32 v9, 0, v9, vcc
	v_cmp_lt_i32_e32 vcc, -1, v12
	v_exp_f32_e32 v18, v18
	s_add_i32 s9, s9, s0
	v_cndmask_b32_e32 v8, 0, v8, vcc
	v_cmp_lt_i32_e32 vcc, -1, v14
	s_cmpk_lt_i32 s8, 0x820
	s_nop 0
	v_cndmask_b32_e32 v11, 0, v10, vcc
	v_cmp_lt_i32_e32 vcc, -1, v16
	s_nop 1
	v_cndmask_b32_e32 v10, 0, v19, vcc
	v_cmp_gt_i32_e32 vcc, 1, v13
	s_nop 1
	v_cndmask_b32_e32 v13, 0, v17, vcc
	v_cmp_gt_i32_e32 vcc, 1, v12
	s_nop 1
	v_cndmask_b32_e32 v12, 0, v15, vcc
	v_cmp_gt_i32_e32 vcc, 1, v14
	v_pk_add_f32 v[8:9], v[8:9], v[12:13]
	s_nop 0
	v_cndmask_b32_e32 v15, 0, v18, vcc
	v_cmp_gt_i32_e32 vcc, 1, v16
	v_pk_mul_f32 v[4:5], v[4:5], v[8:9]
	s_nop 0
	v_cndmask_b32_e32 v14, 0, v20, vcc
	v_pk_add_f32 v[10:11], v[10:11], v[14:15]
	s_nop 0
	v_pk_mul_f32 v[6:7], v[6:7], v[10:11]
	s_nop 0
	v_cvt_pk_bf16_f32 v7, v6, v7
	v_cvt_pk_bf16_f32 v6, v4, v5
	v_lshl_add_u64 v[4:5], v[74:75], 0, v[38:39]
	global_store_dwordx2 v[4:5], v[6:7], off
	global_store_dwordx2 v[0:1], v[2:3], off
	s_cbranch_scc0 .LBB0_1308

.LBB0_1374:
	s_cmp_lg_u32 s47, 2
	s_cselect_b64 s[0:1], -1, 0
	s_cmp_eq_u32 s47, 0
	s_cselect_b64 s[36:37], -1, 0
	s_and_b64 s[8:9], s[36:37], exec
	s_cselect_b32 s6, s43, s42
	s_add_i32 s8, s6, s13
	s_ashr_i32 s9, s8, 31
	s_lshl_b64 s[8:9], s[8:9], 18
	s_add_u32 s6, s44, s8
	s_addc_u32 s18, s45, s9
	s_cmp_eq_u32 s47, 2
	s_cselect_b32 s26, s11, 0x400
	s_cselect_b32 s9, s25, s41
	s_cselect_b32 s8, s24, s40
	v_mad_i64_i32 v[84:85], vcc, s26, v72, 0
	s_cselect_b32 s22, s21, s6
	v_lshl_add_u64 v[84:85], v[84:85], 1, s[8:9]
	v_readfirstlane_b32 s6, v100
	v_add_u32_e32 v88, 0x1000, v100
	s_cselect_b32 s19, 0x4200, s16
	s_cselect_b32 s23, s39, s18
	s_cselect_b32 s18, s46, 4
	v_lshl_add_u64 v[84:85], v[84:85], 0, v[68:69]
	s_mov_b32 m0, s6
	s_lshl_b32 s6, s26, 6
	v_readfirstlane_b32 s27, v88
	v_add_u32_e32 v88, 0x2000, v100
	s_setprio 3
	global_load_lds_dwordx4 v[84:85], off
	v_lshl_add_u64 v[84:85], v[84:85], 0, s[6:7]
	s_mov_b32 m0, s27
	v_readfirstlane_b32 s27, v88
	global_load_lds_dwordx4 v[84:85], off
	v_lshl_add_u64 v[84:85], v[84:85], 0, s[6:7]
	s_mov_b32 m0, s27
	v_add_u32_e32 v88, 0x3000, v100
	global_load_lds_dwordx4 v[84:85], off
	v_lshl_add_u64 v[84:85], v[84:85], 0, s[6:7]
	v_readfirstlane_b32 s6, v88
	s_mov_b32 m0, s6
	v_mad_i64_i32 v[86:87], vcc, s19, v72, 0
	global_load_lds_dwordx4 v[84:85], off
	v_add_u32_e32 v84, 0x8000, v100
	v_lshl_add_u64 v[86:87], v[86:87], 1, s[22:23]
	v_readfirstlane_b32 s6, v84
	v_lshl_add_u64 v[86:87], v[86:87], 0, v[68:69]
	s_mov_b32 m0, s6
	s_lshl_b32 s6, s19, 6
	global_load_lds_dwordx4 v[86:87], off
	v_lshl_add_u64 v[84:85], v[86:87], 0, s[6:7]
	v_add_u32_e32 v86, 0x9000, v100
	s_add_u32 s8, s8, 0x80
	v_readfirstlane_b32 s27, v86
	v_add_u32_e32 v86, 0xa000, v100
	s_mov_b32 m0, s27
	v_readfirstlane_b32 s27, v86
	global_load_lds_dwordx4 v[84:85], off
	v_lshl_add_u64 v[84:85], v[84:85], 0, s[6:7]
	s_mov_b32 m0, s27
	v_add_u32_e32 v86, 0xb000, v100
	global_load_lds_dwordx4 v[84:85], off
	v_lshl_add_u64 v[84:85], v[84:85], 0, s[6:7]
	v_readfirstlane_b32 s6, v86
	s_mov_b32 m0, s6
	s_addc_u32 s9, s9, 0
	global_load_lds_dwordx4 v[84:85], off
	s_setprio 0
	v_mov_b64_e32 v[90:91], s[8:9]
	v_mad_i64_i32 v[84:85], s[8:9], v76, s26, v[90:91]
	v_mad_i64_i32 v[86:87], s[8:9], v78, s26, v[90:91]
	v_mad_i64_i32 v[88:89], s[8:9], v80, s26, v[90:91]
	v_mad_i64_i32 v[90:91], s[8:9], v82, s26, v[90:91]
	s_add_u32 s8, s22, 0x80
	s_waitcnt vmcnt(0)
	s_addc_u32 s9, s23, 0
	v_mov_b64_e32 v[98:99], s[8:9]
	s_mov_b32 s6, 0
	v_mad_i64_i32 v[92:93], s[8:9], v76, s19, v[98:99]
	v_mad_i64_i32 v[94:95], s[8:9], v78, s19, v[98:99]
	v_mad_i64_i32 v[96:97], s[8:9], v80, s19, v[98:99]
	v_mad_i64_i32 v[98:99], s[8:9], v82, s19, v[98:99]
	s_mov_b64 s[26:27], s[48:49]
	s_mov_b32 s48, s5
	s_waitcnt vmcnt(0) lgkmcnt(0)
	s_barrier
	s_branch .LBB0_1376

.LBB0_1378:
	s_andn2_b64 vcc, exec, s[8:9]
	s_cbranch_vccnz .LBB0_1375
	s_lshl_b32 s8, s19, 14
	s_xor_b32 s8, s8, 0x4000
	v_add_u32_e32 v128, s8, v100
	v_add_u32_e32 v129, 0x1000, v128
	v_readfirstlane_b32 s8, v128
	v_lshl_add_u64 v[126:127], v[84:85], 0, v[74:75]
	s_mov_b32 m0, s8
	v_readfirstlane_b32 s8, v129
	v_add_u32_e32 v129, 0x2000, v128
	s_setprio 3
	global_load_lds_dwordx4 v[126:127], off
	v_lshl_add_u64 v[126:127], v[90:91], 0, v[74:75]
	s_mov_b32 m0, s8
	v_readfirstlane_b32 s8, v129
	v_add_u32_e32 v129, 0x3000, v128
	global_load_lds_dwordx4 v[126:127], off
	v_lshl_add_u64 v[126:127], v[86:87], 0, v[74:75]
	s_mov_b32 m0, s8
	v_readfirstlane_b32 s8, v129
	v_add_u32_e32 v129, 0x8000, v128
	global_load_lds_dwordx4 v[126:127], off
	v_lshl_add_u64 v[126:127], v[88:89], 0, v[74:75]
	s_mov_b32 m0, s8
	v_readfirstlane_b32 s8, v129
	v_add_u32_e32 v129, 0x9000, v128
	global_load_lds_dwordx4 v[126:127], off
	v_lshl_add_u64 v[126:127], v[92:93], 0, v[74:75]
	s_mov_b32 m0, s8
	v_readfirstlane_b32 s8, v129
	v_add_u32_e32 v129, 0xa000, v128
	global_load_lds_dwordx4 v[126:127], off
	v_lshl_add_u64 v[126:127], v[98:99], 0, v[74:75]
	s_mov_b32 m0, s8
	v_readfirstlane_b32 s8, v129
	v_add_u32_e32 v128, 0xb000, v128
	global_load_lds_dwordx4 v[126:127], off
	v_lshl_add_u64 v[126:127], v[94:95], 0, v[74:75]
	s_mov_b32 m0, s8
	v_readfirstlane_b32 s8, v128
	global_load_lds_dwordx4 v[126:127], off
	v_lshl_add_u64 v[126:127], v[96:97], 0, v[74:75]
	s_mov_b32 m0, s8
	s_lshl_b32 s22, s19, 13
	global_load_lds_dwordx4 v[126:127], off
	s_setprio 0
	s_branch .LBB0_1375

.LBB0_1486:
	s_and_b32 s0, s12, 7
	v_readlane_b32 s8, v180, 8
	s_mul_i32 s0, s0, s8
	s_ashr_i32 s1, s12, 3
	s_add_i32 s0, s0, s1
	s_ashr_i32 s1, s0, 31
	s_lshr_b32 s1, s1, 26
	s_add_i32 s1, s0, s1
	s_ashr_i32 s6, s1, 6
	s_lshl_b32 s6, s6, 3
	s_sub_i32 s8, s8, s6
	s_min_i32 s8, s8, 8
	s_abs_i32 s9, s8
	v_cvt_f32_u32_e32 v0, s9
	s_sub_i32 s11, 0, s9
	s_andn2_b32 s1, s1, 63
	s_sub_i32 s0, s0, s1
	v_rcp_iflag_f32_e32 v0, v0
	s_abs_i32 s1, s0
	s_xor_b32 s10, s0, s8
	s_ashr_i32 s10, s10, 31
	v_mul_f32_e32 v0, 0x4f7ffffe, v0
	v_cvt_u32_f32_e32 v0, v0
	v_add_u32_e32 v6, 0x1000, v68
	s_mov_b64 s[22:23], 0x40000
	s_mov_b64 s[36:37], 0x60000
	v_readfirstlane_b32 s13, v0
	s_mul_i32 s11, s11, s13
	s_mul_hi_u32 s11, s13, s11
	s_add_i32 s13, s13, s11
	s_mul_hi_u32 s11, s1, s13
	s_mul_i32 s13, s11, s9
	s_sub_i32 s1, s1, s13
	s_add_i32 s18, s11, 1
	s_sub_i32 s13, s1, s9
	s_cmp_ge_u32 s1, s9
	s_cselect_b32 s11, s18, s11
	s_cselect_b32 s1, s13, s1
	s_add_i32 s13, s11, 1
	s_cmp_ge_u32 s1, s9
	s_cselect_b32 s1, s13, s11
	s_xor_b32 s1, s1, s10
	s_sub_i32 s9, s1, s10
	s_mul_i32 s1, s9, s8
	s_sub_i32 s0, s0, s1
	s_add_i32 s1, s6, s0
	s_lshl_b32 s24, s1, 7
	s_ashr_i32 s25, s24, 31
	s_lshl_b32 s20, s9, 7
	s_lshl_b64 s[8:9], s[24:25], 12
	v_readfirstlane_b32 s0, v68
	v_lshl_add_u64 v[0:1], v[72:73], 0, s[8:9]
	s_mov_b32 m0, s0
	v_readfirstlane_b32 s0, v6
	v_add_u32_e32 v6, 0x2000, v68
	s_setprio 3
	global_load_lds_dwordx4 v[0:1], off
	v_lshl_add_u64 v[4:5], v[0:1], 0, s[28:29]
	s_mov_b32 m0, s0
	v_readfirstlane_b32 s0, v6
	global_load_lds_dwordx4 v[4:5], off
	v_lshl_add_u64 v[4:5], v[0:1], 0, s[22:23]
	s_mov_b32 m0, s0
	v_lshl_add_u64 v[0:1], v[0:1], 0, s[36:37]
	global_load_lds_dwordx4 v[4:5], off
	v_add_u32_e32 v4, 0x3000, v68
	s_ashr_i32 s21, s20, 31
	v_readfirstlane_b32 s0, v4
	s_mov_b32 m0, s0
	s_lshl_b64 s[10:11], s[20:21], 12
	global_load_lds_dwordx4 v[0:1], off
	v_add_u32_e32 v0, 0x8000, v68
	v_add_u32_e32 v4, 0x9000, v68
	v_readfirstlane_b32 s0, v0
	v_lshl_add_u64 v[2:3], v[74:75], 0, s[10:11]
	s_mov_b32 m0, s0
	v_readfirstlane_b32 s0, v4
	v_add_u32_e32 v4, 0xa000, v68
	global_load_lds_dwordx4 v[2:3], off
	v_lshl_add_u64 v[0:1], v[2:3], 0, s[28:29]
	s_mov_b32 m0, s0
	v_readfirstlane_b32 s0, v4
	global_load_lds_dwordx4 v[0:1], off
	v_lshl_add_u64 v[0:1], v[2:3], 0, s[22:23]
	s_mov_b32 m0, s0
	v_lshl_add_u64 v[88:89], v[84:85], 0, s[8:9]
	global_load_lds_dwordx4 v[0:1], off
	v_lshl_add_u64 v[0:1], v[2:3], 0, s[36:37]
	v_add_u32_e32 v2, 0xb000, v68
	v_lshl_add_u64 v[90:91], v[86:87], 0, s[10:11]
	v_readfirstlane_b32 s0, v2
	s_mov_b32 m0, s0
	s_mov_b32 s0, 0
	global_load_lds_dwordx4 v[0:1], off
	s_setprio 0
	s_waitcnt vmcnt(0)
	v_mov_b32_e32 v0, 0
	s_mov_b64 s[36:37], 0
	v_mov_b32_e32 v1, v0
	v_mov_b32_e32 v2, v0
	v_mov_b32_e32 v3, v0
	v_mov_b32_e32 v4, v0
	v_mov_b32_e32 v5, v0
	v_mov_b32_e32 v6, v0
	v_mov_b32_e32 v7, v0
	v_mov_b32_e32 v8, v0
	v_mov_b32_e32 v9, v0
	v_mov_b32_e32 v10, v0
	v_mov_b32_e32 v11, v0
	v_mov_b32_e32 v12, v0
	v_mov_b32_e32 v13, v0
	v_mov_b32_e32 v14, v0
	v_mov_b32_e32 v15, v0
	v_mov_b32_e32 v16, v0
	v_mov_b32_e32 v17, v0
	v_mov_b32_e32 v18, v0
	v_mov_b32_e32 v19, v0
	v_mov_b32_e32 v20, v0
	v_mov_b32_e32 v21, v0
	v_mov_b32_e32 v22, v0
	v_mov_b32_e32 v23, v0
	v_mov_b32_e32 v24, v0
	v_mov_b32_e32 v25, v0
	v_mov_b32_e32 v26, v0
	v_mov_b32_e32 v27, v0
	v_mov_b32_e32 v28, v0
	v_mov_b32_e32 v29, v0
	v_mov_b32_e32 v30, v0
	v_mov_b32_e32 v31, v0
	v_mov_b32_e32 v32, v0
	v_mov_b32_e32 v33, v0
	v_mov_b32_e32 v34, v0
	v_mov_b32_e32 v35, v0
	v_mov_b32_e32 v36, v0
	v_mov_b32_e32 v37, v0
	v_mov_b32_e32 v38, v0
	v_mov_b32_e32 v39, v0
	v_mov_b32_e32 v40, v0
	v_mov_b32_e32 v41, v0
	v_mov_b32_e32 v42, v0
	v_mov_b32_e32 v43, v0
	v_mov_b32_e32 v44, v0
	v_mov_b32_e32 v45, v0
	v_mov_b32_e32 v46, v0
	v_mov_b32_e32 v47, v0
	v_mov_b32_e32 v48, v0
	v_mov_b32_e32 v49, v0
	v_mov_b32_e32 v50, v0
	v_mov_b32_e32 v51, v0
	v_mov_b32_e32 v52, v0
	v_mov_b32_e32 v53, v0
	v_mov_b32_e32 v54, v0
	v_mov_b32_e32 v55, v0
	v_mov_b32_e32 v56, v0
	v_mov_b32_e32 v57, v0
	v_mov_b32_e32 v58, v0
	v_mov_b32_e32 v59, v0
	v_mov_b32_e32 v60, v0
	v_mov_b32_e32 v61, v0
	v_mov_b32_e32 v62, v0
	v_mov_b32_e32 v63, v0
	v_lshl_add_u64 v[100:101], v[88:89], 0, s[36:37]
	s_mov_b64 s[8:9], 0x15800080
	v_lshl_add_u64 v[102:103], v[100:101], 0, s[8:9]
	s_mov_b64 s[8:9], 0x15820080
	v_mov_b32_e32 v184, v102
	v_mov_b32_e32 v185, v103
	v_lshl_add_u64 v[102:103], v[100:101], 0, s[8:9]
	s_mov_b64 s[8:9], 0x15840080
	v_mov_b32_e32 v186, v102
	v_mov_b32_e32 v187, v103
	v_lshl_add_u64 v[102:103], v[100:101], 0, s[8:9]
	s_mov_b64 s[8:9], 0x15860080
	v_mov_b32_e32 v188, v102
	v_mov_b32_e32 v189, v103
	v_lshl_add_u64 v[100:101], v[100:101], 0, s[8:9]
	s_mov_b64 s[8:9], 0x1800080
	v_mov_b32_e32 v190, v100
	v_mov_b32_e32 v191, v101
	v_lshl_add_u64 v[100:101], v[90:91], 0, s[36:37]
	v_lshl_add_u64 v[102:103], v[100:101], 0, s[8:9]
	s_mov_b64 s[8:9], 0x1820080
	v_mov_b32_e32 v192, v102
	v_mov_b32_e32 v193, v103
	v_lshl_add_u64 v[102:103], v[100:101], 0, s[8:9]
	s_mov_b64 s[8:9], 0x1840080
	v_mov_b32_e32 v194, v102
	v_mov_b32_e32 v195, v103
	v_lshl_add_u64 v[102:103], v[100:101], 0, s[8:9]
	s_mov_b64 s[8:9], 0x1860080
	v_mov_b32_e32 v196, v102
	v_mov_b32_e32 v197, v103
	v_lshl_add_u64 v[100:101], v[100:101], 0, s[8:9]
	v_mov_b32_e32 v198, v100
	v_mov_b32_e32 v199, v101
	v_readfirstlane_b32 s100, v68
	s_mov_b64 vcc, 0x80
	s_waitcnt vmcnt(0) lgkmcnt(0)
	s_barrier

.LBB0_1497:
	s_and_b32 s1, s0, 7
	s_mulk_i32 s1, 0x318
	s_ashr_i32 s6, s0, 3
	s_add_i32 s1, s1, s6
	s_mul_hi_i32 s6, s1, 0x2aaaaaab
	s_lshr_b32 s8, s6, 31
	s_ashr_i32 s6, s6, 6
	s_add_i32 s6, s6, s8
	s_lshl_b32 s8, s6, 3
	s_sub_i32 s9, 0x84, s8
	s_min_u32 s9, s9, 8
	v_cvt_f32_ubyte0_e32 v0, s9
	v_rcp_iflag_f32_e32 v0, v0
	s_sub_i32 s11, 0, s9
	s_mulk_i32 s6, 0xfe80
	s_add_i32 s6, s6, s1
	v_mul_f32_e32 v0, 0x4f7ffffe, v0
	v_cvt_u32_f32_e32 v0, v0
	s_abs_i32 s10, s6
	s_ashr_i32 s1, s6, 31
	v_add_u32_e32 v6, 0x1000, v82
	v_readfirstlane_b32 s12, v0
	s_mul_i32 s11, s11, s12
	s_mul_hi_u32 s11, s12, s11
	s_add_i32 s12, s12, s11
	s_mul_hi_u32 s11, s10, s12
	s_mul_i32 s12, s11, s9
	s_sub_i32 s10, s10, s12
	s_add_i32 s12, s11, 1
	s_sub_i32 s13, s10, s9
	s_cmp_ge_u32 s10, s9
	s_cselect_b32 s11, s12, s11
	s_cselect_b32 s10, s13, s10
	s_add_i32 s12, s11, 1
	s_cmp_ge_u32 s10, s9
	s_cselect_b32 s10, s12, s11
	s_xor_b32 s10, s10, s1
	s_sub_i32 s1, s10, s1
	s_mul_i32 s9, s1, s9
	s_sub_i32 s6, s6, s9
	s_add_i32 s8, s8, s6
	s_lshl_b32 s20, s8, 7
	s_ashr_i32 s21, s20, 31
	s_lshl_b64 s[8:9], s[20:21], 11
	v_readfirstlane_b32 s6, v82
	v_lshl_add_u64 v[0:1], v[72:73], 0, s[8:9]
	s_mov_b32 m0, s6
	s_mov_b64 s[12:13], 0x10000
	v_readfirstlane_b32 s6, v6
	v_add_u32_e32 v6, 0x2000, v82
	s_setprio 3
	global_load_lds_dwordx4 v[0:1], off
	v_lshl_add_u64 v[4:5], v[0:1], 0, s[12:13]
	s_mov_b32 m0, s6
	v_readfirstlane_b32 s6, v6
	global_load_lds_dwordx4 v[4:5], off
	v_lshl_add_u64 v[4:5], v[0:1], 0, s[28:29]
	s_mov_b32 m0, s6
	s_mov_b64 s[36:37], 0x30000
	global_load_lds_dwordx4 v[4:5], off
	v_add_u32_e32 v4, 0x3000, v82
	s_lshl_b32 s24, s1, 7
	v_readfirstlane_b32 s6, v4
	v_lshl_add_u64 v[0:1], v[0:1], 0, s[36:37]
	s_mov_b32 m0, s6
	s_ashr_i32 s25, s24, 31
	global_load_lds_dwordx4 v[0:1], off
	v_add_u32_e32 v0, 0x8000, v82
	s_lshl_b64 s[10:11], s[24:25], 11
	v_readfirstlane_b32 s6, v0
	v_add_u32_e32 v4, 0x9000, v82
	v_lshl_add_u64 v[2:3], v[74:75], 0, s[10:11]
	s_mov_b32 m0, s6
	v_readfirstlane_b32 s6, v4
	v_add_u32_e32 v4, 0xa000, v82
	global_load_lds_dwordx4 v[2:3], off
	v_lshl_add_u64 v[0:1], v[2:3], 0, s[12:13]
	s_mov_b32 m0, s6
	v_readfirstlane_b32 s6, v4
	global_load_lds_dwordx4 v[0:1], off
	v_lshl_add_u64 v[0:1], v[2:3], 0, s[28:29]
	s_mov_b32 m0, s6
	v_lshl_add_u64 v[78:79], v[76:77], 0, s[8:9]
	global_load_lds_dwordx4 v[0:1], off
	v_lshl_add_u64 v[0:1], v[2:3], 0, s[36:37]
	v_add_u32_e32 v2, 0xb000, v82
	v_lshl_add_u64 v[80:81], v[76:77], 0, s[10:11]
	v_readfirstlane_b32 s6, v2
	s_mov_b32 m0, s6
	s_mov_b32 s6, 0
	global_load_lds_dwordx4 v[0:1], off
	s_setprio 0
	s_waitcnt vmcnt(0)
	v_mov_b32_e32 v0, 0
	s_mov_b64 s[36:37], 0
	v_mov_b32_e32 v1, v0
	v_mov_b32_e32 v2, v0
	v_mov_b32_e32 v3, v0
	v_mov_b32_e32 v4, v0
	v_mov_b32_e32 v5, v0
	v_mov_b32_e32 v6, v0
	v_mov_b32_e32 v7, v0
	v_mov_b32_e32 v8, v0
	v_mov_b32_e32 v9, v0
	v_mov_b32_e32 v10, v0
	v_mov_b32_e32 v11, v0
	v_mov_b32_e32 v12, v0
	v_mov_b32_e32 v13, v0
	v_mov_b32_e32 v14, v0
	v_mov_b32_e32 v15, v0
	v_mov_b32_e32 v16, v0
	v_mov_b32_e32 v17, v0
	v_mov_b32_e32 v18, v0
	v_mov_b32_e32 v19, v0
	v_mov_b32_e32 v20, v0
	v_mov_b32_e32 v21, v0
	v_mov_b32_e32 v22, v0
	v_mov_b32_e32 v23, v0
	v_mov_b32_e32 v24, v0
	v_mov_b32_e32 v25, v0
	v_mov_b32_e32 v26, v0
	v_mov_b32_e32 v27, v0
	v_mov_b32_e32 v28, v0
	v_mov_b32_e32 v29, v0
	v_mov_b32_e32 v30, v0
	v_mov_b32_e32 v31, v0
	v_mov_b32_e32 v32, v0
	v_mov_b32_e32 v33, v0
	v_mov_b32_e32 v34, v0
	v_mov_b32_e32 v35, v0
	v_mov_b32_e32 v36, v0
	v_mov_b32_e32 v37, v0
	v_mov_b32_e32 v38, v0
	v_mov_b32_e32 v39, v0
	v_mov_b32_e32 v40, v0
	v_mov_b32_e32 v41, v0
	v_mov_b32_e32 v42, v0
	v_mov_b32_e32 v43, v0
	v_mov_b32_e32 v44, v0
	v_mov_b32_e32 v45, v0
	v_mov_b32_e32 v46, v0
	v_mov_b32_e32 v47, v0
	v_mov_b32_e32 v48, v0
	v_mov_b32_e32 v49, v0
	v_mov_b32_e32 v50, v0
	v_mov_b32_e32 v51, v0
	v_mov_b32_e32 v52, v0
	v_mov_b32_e32 v53, v0
	v_mov_b32_e32 v54, v0
	v_mov_b32_e32 v55, v0
	v_mov_b32_e32 v56, v0
	v_mov_b32_e32 v57, v0
	v_mov_b32_e32 v58, v0
	v_mov_b32_e32 v59, v0
	v_mov_b32_e32 v60, v0
	v_mov_b32_e32 v61, v0
	v_mov_b32_e32 v62, v0
	v_mov_b32_e32 v63, v0
	v_lshl_add_u64 v[92:93], v[78:79], 0, s[36:37]
	v_lshl_add_u64 v[94:95], v[92:93], 0, s[76:77]
	v_mov_b32_e32 v184, v94
	v_mov_b32_e32 v185, v95
	v_lshl_add_u64 v[94:95], v[92:93], 0, s[80:81]
	v_mov_b32_e32 v186, v94
	v_mov_b32_e32 v187, v95
	v_lshl_add_u64 v[94:95], v[92:93], 0, s[78:79]
	v_lshl_add_u64 v[92:93], v[92:93], 0, s[88:89]
	v_mov_b32_e32 v188, v94
	v_mov_b32_e32 v189, v95
	s_mov_b64 s[8:9], 0x2000080
	v_mov_b32_e32 v190, v92
	v_mov_b32_e32 v191, v93
	v_lshl_add_u64 v[92:93], v[80:81], 0, s[36:37]
	v_lshl_add_u64 v[94:95], v[92:93], 0, s[8:9]
	s_mov_b64 s[8:9], 0x2010080
	v_mov_b32_e32 v192, v94
	v_mov_b32_e32 v193, v95
	v_lshl_add_u64 v[94:95], v[92:93], 0, s[8:9]
	s_mov_b64 s[8:9], 0x2020080
	v_mov_b32_e32 v194, v94
	v_mov_b32_e32 v195, v95
	v_lshl_add_u64 v[94:95], v[92:93], 0, s[8:9]
	s_mov_b64 s[8:9], 0x2030080
	v_lshl_add_u64 v[92:93], v[92:93], 0, s[8:9]
	v_mov_b32_e32 v196, v94
	v_mov_b32_e32 v197, v95
	v_mov_b32_e32 v198, v92
	v_mov_b32_e32 v199, v93
	v_readfirstlane_b32 s100, v82
	s_mov_b64 vcc, 0x80
	s_waitcnt vmcnt(0) lgkmcnt(0)
	s_barrier

.LBB0_1654:
	s_and_b32 s0, s8, 7
	s_mulk_i32 s0, 0x108
	s_ashr_i32 s6, s8, 3
	s_add_i32 s1, s0, s6
	s_bfe_u32 s9, s1, 0x30001
	s_lshl_b32 s6, s6, 7
	s_and_b32 s10, s6, 0x80
	s_lshl_b32 s6, s9, 15
	v_lshl_add_u64 v[0:1], v[60:61], 0, s[6:7]
	v_readfirstlane_b32 s6, v84
	v_add_u32_e32 v6, 0x1000, v84
	s_ashr_i32 s0, s1, 4
	s_mov_b32 m0, s6
	v_readfirstlane_b32 s6, v6
	v_add_u32_e32 v6, 0x2000, v84
	s_ashr_i32 s1, s0, 31
	s_setprio 3
	global_load_lds_dwordx4 v[0:1], off
	v_lshl_add_u64 v[4:5], v[0:1], 0, s[20:21]
	s_mov_b32 m0, s6
	v_readfirstlane_b32 s6, v6
	v_add_u32_e32 v6, 0x3000, v84
	s_lshl_b64 s[12:13], s[0:1], 11
	s_lshl_b32 s1, s9, 8
	global_load_lds_dwordx4 v[4:5], off
	v_lshl_add_u64 v[4:5], v[0:1], 0, s[24:25]
	s_mov_b32 m0, s6
	v_readfirstlane_b32 s6, v6
	s_or_b32 s11, s12, s1
	global_load_lds_dwordx4 v[4:5], off
	v_lshl_add_u64 v[4:5], v[0:1], 0, s[36:37]
	s_mov_b32 m0, s6
	s_or_b32 s12, s11, s10
	global_load_lds_dwordx4 v[4:5], off
	v_add_u32_e32 v4, 0x8000, v84
	s_lshl_b64 s[12:13], s[12:13], 8
	v_readfirstlane_b32 s6, v4
	v_add_u32_e32 v6, 0x9000, v84
	v_lshl_add_u64 v[2:3], v[62:63], 0, s[12:13]
	s_mov_b32 m0, s6
	v_readfirstlane_b32 s6, v6
	v_add_u32_e32 v6, 0xa000, v84
	global_load_lds_dwordx4 v[2:3], off
	v_lshl_add_u64 v[4:5], v[2:3], 0, s[20:21]
	s_mov_b32 m0, s6
	v_readfirstlane_b32 s6, v6
	v_add_u32_e32 v6, 0xb000, v84
	global_load_lds_dwordx4 v[4:5], off
	v_lshl_add_u64 v[4:5], v[2:3], 0, s[24:25]
	s_mov_b32 m0, s6
	v_readfirstlane_b32 s6, v6
	v_add_u32_e32 v16, 0x4000, v84
	global_load_lds_dwordx4 v[4:5], off
	v_lshl_add_u64 v[4:5], v[2:3], 0, s[36:37]
	s_mov_b32 m0, s6
	v_readfirstlane_b32 s6, v16
	global_load_lds_dwordx4 v[4:5], off
	v_lshl_add_u64 v[10:11], v[0:1], 0, s[38:39]
	v_lshl_add_u64 v[12:13], v[0:1], 0, s[40:41]
	v_lshl_add_u64 v[14:15], v[0:1], 0, s[42:43]
	v_lshl_add_u64 v[0:1], v[0:1], 0, s[92:93]
	s_mov_b32 m0, s6
	s_waitcnt vmcnt(0)
	s_waitcnt vmcnt(0) lgkmcnt(0)
	s_barrier
	global_load_lds_dwordx4 v[0:1], off
	v_add_u32_e32 v0, 0x5000, v84
	v_lshl_add_u64 v[4:5], v[2:3], 0, s[38:39]
	v_readfirstlane_b32 s6, v0
	v_add_u32_e32 v0, 0x6000, v84
	s_mov_b32 m0, s6
	v_readfirstlane_b32 s6, v0
	v_add_u32_e32 v0, 0x7000, v84
	global_load_lds_dwordx4 v[14:15], off
	s_mov_b32 m0, s6
	v_readfirstlane_b32 s6, v0
	v_add_u32_e32 v0, 0xc000, v84
	global_load_lds_dwordx4 v[12:13], off
	s_mov_b32 m0, s6
	v_readfirstlane_b32 s6, v0
	v_add_u32_e32 v0, 0xd000, v84
	v_lshl_add_u64 v[6:7], v[2:3], 0, s[40:41]
	v_lshl_add_u64 v[8:9], v[2:3], 0, s[42:43]
	v_lshl_add_u64 v[2:3], v[2:3], 0, s[92:93]
	global_load_lds_dwordx4 v[10:11], off
	s_mov_b32 m0, s6
	v_readfirstlane_b32 s6, v0
	v_add_u32_e32 v0, 0xe000, v84
	global_load_lds_dwordx4 v[2:3], off
	s_mov_b32 m0, s6
	v_readfirstlane_b32 s6, v0
	v_add_u32_e32 v0, 0xf000, v84
	global_load_lds_dwordx4 v[8:9], off
	s_mov_b32 m0, s6
	v_readfirstlane_b32 s6, v0
	global_load_lds_dwordx4 v[6:7], off
	s_mov_b32 m0, s6
	s_nop 0
	global_load_lds_dwordx4 v[4:5], off
	s_setprio 0
	ds_read_b128 v[0:3], v79
	ds_read_b128 v[4:7], v79 offset:2048
	ds_read_b128 v[8:11], v79 offset:4096
	ds_read_b128 v[12:15], v79 offset:6144
	ds_read_b128 v[16:19], v78 offset:32768
	ds_read_b128 v[20:23], v78 offset:34816
	ds_read_b128 v[24:27], v78 offset:36864
	ds_read_b128 v[28:31], v78 offset:38912
	s_setprio 1
	s_waitcnt lgkmcnt(0)
	v_mfma_f32_16x16x32_bf16 v[32:35], v[16:19], v[0:3], 0
	v_mfma_f32_16x16x32_bf16 v[36:39], v[20:23], v[0:3], 0
	v_mfma_f32_16x16x32_bf16 v[40:43], v[24:27], v[0:3], 0
	v_mfma_f32_16x16x32_bf16 v[0:3], v[28:31], v[0:3], 0
	v_mfma_f32_16x16x32_bf16 v[44:47], v[16:19], v[4:7], 0
	v_mfma_f32_16x16x32_bf16 v[48:51], v[20:23], v[4:7], 0
	v_mfma_f32_16x16x32_bf16 v[52:55], v[24:27], v[4:7], 0
	v_mfma_f32_16x16x32_bf16 v[4:7], v[28:31], v[4:7], 0
	v_mfma_f32_16x16x32_bf16 v[56:59], v[16:19], v[8:11], 0
	v_mfma_f32_16x16x32_bf16 v[72:75], v[20:23], v[8:11], 0
	v_mfma_f32_16x16x32_bf16 v[86:89], v[24:27], v[8:11], 0
	v_mfma_f32_16x16x32_bf16 v[8:11], v[28:31], v[8:11], 0
	v_mfma_f32_16x16x32_bf16 v[16:19], v[16:19], v[12:15], 0
	v_mfma_f32_16x16x32_bf16 v[20:23], v[20:23], v[12:15], 0
	v_mfma_f32_16x16x32_bf16 v[24:27], v[24:27], v[12:15], 0
	v_mfma_f32_16x16x32_bf16 v[12:15], v[28:31], v[12:15], 0
	s_setprio 0
	ds_read_b128 v[28:31], v80
	ds_read_b128 v[90:93], v80 offset:2048
	ds_read_b128 v[94:97], v80 offset:4096
	ds_read_b128 v[98:101], v80 offset:6144
	ds_read_b128 v[120:123], v81 offset:32768
	ds_read_b128 v[124:127], v81 offset:34816
	ds_read_b128 v[128:131], v81 offset:36864
	ds_read_b128 v[132:135], v81 offset:38912
	s_setprio 1
	s_waitcnt lgkmcnt(0)
	v_mfma_f32_16x16x32_bf16 v[32:35], v[120:123], v[28:31], v[32:35]
	v_mfma_f32_16x16x32_bf16 v[36:39], v[124:127], v[28:31], v[36:39]
	v_mfma_f32_16x16x32_bf16 v[40:43], v[128:131], v[28:31], v[40:43]
	v_mfma_f32_16x16x32_bf16 v[0:3], v[132:135], v[28:31], v[0:3]
	v_mfma_f32_16x16x32_bf16 v[28:31], v[120:123], v[90:93], v[44:47]
	v_mfma_f32_16x16x32_bf16 v[44:47], v[124:127], v[90:93], v[48:51]
	v_mfma_f32_16x16x32_bf16 v[48:51], v[128:131], v[90:93], v[52:55]
	v_mfma_f32_16x16x32_bf16 v[4:7], v[132:135], v[90:93], v[4:7]
	v_mfma_f32_16x16x32_bf16 v[52:55], v[120:123], v[94:97], v[56:59]
	v_mfma_f32_16x16x32_bf16 v[56:59], v[124:127], v[94:97], v[72:75]
	v_mfma_f32_16x16x32_bf16 v[72:75], v[128:131], v[94:97], v[86:89]
	v_mfma_f32_16x16x32_bf16 v[8:11], v[132:135], v[94:97], v[8:11]
	v_mfma_f32_16x16x32_bf16 v[16:19], v[120:123], v[98:101], v[16:19]
	v_mfma_f32_16x16x32_bf16 v[20:23], v[124:127], v[98:101], v[20:23]
	v_mfma_f32_16x16x32_bf16 v[24:27], v[128:131], v[98:101], v[24:27]
	v_mfma_f32_16x16x32_bf16 v[12:15], v[132:135], v[98:101], v[12:15]
	s_setprio 0
	s_waitcnt vmcnt(0)
	s_waitcnt vmcnt(0)
	s_barrier
	ds_read_b128 v[86:89], v78 offset:55296
	ds_read_b128 v[90:93], v78 offset:53248
	ds_read_b128 v[94:97], v78 offset:51200
	ds_read_b128 v[98:101], v78 offset:49152
	ds_read_b128 v[120:123], v79 offset:22528
	ds_read_b128 v[124:127], v79 offset:20480
	ds_read_b128 v[128:131], v79 offset:18432
	ds_read_b128 v[132:135], v79 offset:16384
	s_setprio 1
	s_waitcnt lgkmcnt(0)
	v_mfma_f32_16x16x32_bf16 v[32:35], v[98:101], v[132:135], v[32:35]
	v_mfma_f32_16x16x32_bf16 v[36:39], v[94:97], v[132:135], v[36:39]
	v_mfma_f32_16x16x32_bf16 v[40:43], v[90:93], v[132:135], v[40:43]
	v_mfma_f32_16x16x32_bf16 v[0:3], v[86:89], v[132:135], v[0:3]
	v_mfma_f32_16x16x32_bf16 v[28:31], v[98:101], v[128:131], v[28:31]
	v_mfma_f32_16x16x32_bf16 v[132:135], v[94:97], v[128:131], v[44:47]
	v_mfma_f32_16x16x32_bf16 v[136:139], v[90:93], v[128:131], v[48:51]
	v_mfma_f32_16x16x32_bf16 v[4:7], v[86:89], v[128:131], v[4:7]
	v_mfma_f32_16x16x32_bf16 v[128:131], v[98:101], v[124:127], v[52:55]
	v_mfma_f32_16x16x32_bf16 v[140:143], v[94:97], v[124:127], v[56:59]
	v_mfma_f32_16x16x32_bf16 v[72:75], v[90:93], v[124:127], v[72:75]
	v_mfma_f32_16x16x32_bf16 v[8:11], v[86:89], v[124:127], v[8:11]
	v_mfma_f32_16x16x32_bf16 v[98:101], v[98:101], v[120:123], v[16:19]
	v_mfma_f32_16x16x32_bf16 v[94:97], v[94:97], v[120:123], v[20:23]
	v_mfma_f32_16x16x32_bf16 v[90:93], v[90:93], v[120:123], v[24:27]
	v_mfma_f32_16x16x32_bf16 v[86:89], v[86:89], v[120:123], v[12:15]
	s_setprio 0
	s_nop 1
	ds_read_b128 v[12:15], v80 offset:16384
	ds_read_b128 v[16:19], v80 offset:18432
	ds_read_b128 v[120:123], v80 offset:20480
	ds_read_b128 v[124:127], v80 offset:22528
	ds_read_b128 v[144:147], v81 offset:49152
	ds_read_b128 v[148:151], v81 offset:51200
	ds_read_b128 v[152:155], v81 offset:53248
	ds_read_b128 v[156:159], v81 offset:55296
	s_setprio 1
	s_waitcnt lgkmcnt(3)
	v_mfma_f32_16x16x32_bf16 v[160:163], v[144:147], v[12:15], v[32:35]
	s_waitcnt lgkmcnt(2)
	v_mfma_f32_16x16x32_bf16 v[56:59], v[148:151], v[12:15], v[36:39]
	s_waitcnt lgkmcnt(1)
	v_mfma_f32_16x16x32_bf16 v[52:55], v[152:155], v[12:15], v[40:43]
	s_waitcnt lgkmcnt(0)
	v_mfma_f32_16x16x32_bf16 v[48:51], v[156:159], v[12:15], v[0:3]
	v_mfma_f32_16x16x32_bf16 v[44:47], v[144:147], v[16:19], v[28:31]
	v_mfma_f32_16x16x32_bf16 v[40:43], v[148:151], v[16:19], v[132:135]
	v_mfma_f32_16x16x32_bf16 v[36:39], v[152:155], v[16:19], v[136:139]
	v_mfma_f32_16x16x32_bf16 v[32:35], v[156:159], v[16:19], v[4:7]
	v_mfma_f32_16x16x32_bf16 v[28:31], v[144:147], v[120:123], v[128:131]
	v_mfma_f32_16x16x32_bf16 v[24:27], v[148:151], v[120:123], v[140:143]
	v_mfma_f32_16x16x32_bf16 v[20:23], v[152:155], v[120:123], v[72:75]
	v_mfma_f32_16x16x32_bf16 v[16:19], v[156:159], v[120:123], v[8:11]
	v_mfma_f32_16x16x32_bf16 v[12:15], v[144:147], v[124:127], v[98:101]
	v_mfma_f32_16x16x32_bf16 v[8:11], v[148:151], v[124:127], v[94:97]
	v_mfma_f32_16x16x32_bf16 v[4:7], v[152:155], v[124:127], v[90:93]
	v_mfma_f32_16x16x32_bf16 v[0:3], v[156:159], v[124:127], v[86:89]
	s_setprio 0
	s_lshl_b32 s0, s0, 7
	v_add_u32_e32 v74, s0, v71
	v_or_b32_e32 v68, s10, v76
	v_ashrrev_i32_e32 v75, 31, v74
	v_or_b32_e32 v86, s1, v68
	v_lshlrev_b64 v[74:75], 11, v[74:75]
	v_lshl_add_u32 v72, s9, 7, v71
	v_or_b32_e32 v88, v74, v86
	v_mov_b32_e32 v89, v75
	v_ashrrev_i32_e32 v73, 31, v72
	v_lshlrev_b64 v[88:89], 1, v[88:89]
	v_lshl_add_u64 v[72:73], v[72:73], 2, s[68:69]
	v_lshl_add_u64 v[90:91], s[90:91], 0, v[88:89]
	v_lshl_add_u64 v[88:89], s[86:87], 0, v[88:89]
	s_waitcnt vmcnt(0)
	s_barrier
	global_load_dword v68, v[72:73], off
	global_load_dwordx2 v[92:93], v[90:91], off
	s_nop 0
	global_load_dwordx2 v[88:89], v[88:89], off
	s_add_i32 s8, s8, s84
	s_cmpk_lt_i32 s8, 0x840
	s_waitcnt vmcnt(2)
	v_pk_add_f32 v[102:103], v[162:163], v[68:69] op_sel_hi:[1,0]
	s_waitcnt vmcnt(0)
	v_and_b32_e32 v95, 0xffff0000, v89
	v_lshlrev_b32_e32 v94, 16, v89
	v_and_b32_e32 v89, 0xffff0000, v88
	v_lshlrev_b32_e32 v88, 16, v88
	v_mul_f32_e32 v85, 0xbfb8aa3b, v88
	v_exp_f32_e32 v85, v85
	v_and_b32_e32 v101, 0xffff0000, v93
	v_lshlrev_b32_e32 v100, 16, v93
	v_and_b32_e32 v93, 0xffff0000, v92
	v_add_f32_e32 v85, 1.0, v85
	v_rcp_f32_e32 v96, v85
	v_mul_f32_e32 v85, 0xbfb8aa3b, v89
	v_exp_f32_e32 v85, v85
	v_lshlrev_b32_e32 v92, 16, v92
	v_pk_add_f32 v[120:121], v[160:161], v[68:69] op_sel_hi:[1,0]
	v_pk_mul_f32 v[100:101], v[102:103], v[100:101]
	v_add_f32_e32 v85, 1.0, v85
	v_rcp_f32_e32 v97, v85
	v_mul_f32_e32 v85, 0xbfb8aa3b, v94
	v_exp_f32_e32 v85, v85
	v_pk_mul_f32 v[92:93], v[120:121], v[92:93]
	v_pk_mul_f32 v[88:89], v[96:97], v[88:89]
	v_pk_add_f32 v[58:59], v[58:59], v[68:69] op_sel_hi:[1,0]
	v_add_f32_e32 v85, 1.0, v85
	v_rcp_f32_e32 v98, v85
	v_mul_f32_e32 v85, 0xbfb8aa3b, v95
	v_exp_f32_e32 v85, v85
	v_pk_mul_f32 v[88:89], v[92:93], v[88:89]
	v_pk_add_f32 v[56:57], v[56:57], v[68:69] op_sel_hi:[1,0]
	v_cvt_pk_bf16_f32 v88, v88, v89
	v_add_f32_e32 v85, 1.0, v85
	v_rcp_f32_e32 v99, v85
	v_or_b32_e32 v85, 16, v86
	v_pk_add_f32 v[54:55], v[54:55], v[68:69] op_sel_hi:[1,0]
	v_pk_add_f32 v[52:53], v[52:53], v[68:69] op_sel_hi:[1,0]
	v_pk_mul_f32 v[94:95], v[98:99], v[94:95]
	v_pk_add_f32 v[50:51], v[50:51], v[68:69] op_sel_hi:[1,0]
	v_pk_mul_f32 v[94:95], v[100:101], v[94:95]
	v_pk_add_f32 v[48:49], v[48:49], v[68:69] op_sel_hi:[1,0]
	v_cvt_pk_bf16_f32 v89, v94, v95
	global_store_dwordx2 v[90:91], v[88:89], off
	v_or_b32_e32 v88, v74, v85
	v_mov_b32_e32 v89, v75
	v_lshlrev_b64 v[88:89], 1, v[88:89]
	v_lshl_add_u64 v[90:91], s[90:91], 0, v[88:89]
	v_lshl_add_u64 v[88:89], s[86:87], 0, v[88:89]
	global_load_dwordx2 v[92:93], v[90:91], off
	s_nop 0
	global_load_dwordx2 v[88:89], v[88:89], off
	s_waitcnt vmcnt(1)
	v_and_b32_e32 v101, 0xffff0000, v93
	s_waitcnt vmcnt(0)
	v_and_b32_e32 v95, 0xffff0000, v89
	v_lshlrev_b32_e32 v94, 16, v89
	v_and_b32_e32 v89, 0xffff0000, v88
	v_lshlrev_b32_e32 v88, 16, v88
	v_mul_f32_e32 v87, 0xbfb8aa3b, v88
	v_exp_f32_e32 v87, v87
	v_lshlrev_b32_e32 v100, 16, v93
	v_and_b32_e32 v93, 0xffff0000, v92
	v_lshlrev_b32_e32 v92, 16, v92
	v_add_f32_e32 v87, 1.0, v87
	v_rcp_f32_e32 v96, v87
	v_mul_f32_e32 v87, 0xbfb8aa3b, v89
	v_exp_f32_e32 v87, v87
	v_pk_mul_f32 v[56:57], v[56:57], v[92:93]
	v_pk_mul_f32 v[58:59], v[58:59], v[100:101]
	v_add_f32_e32 v87, 1.0, v87
	v_rcp_f32_e32 v97, v87
	v_mul_f32_e32 v87, 0xbfb8aa3b, v94
	v_exp_f32_e32 v87, v87
	v_pk_mul_f32 v[88:89], v[96:97], v[88:89]
	s_nop 0
	v_pk_mul_f32 v[56:57], v[56:57], v[88:89]
	v_add_f32_e32 v87, 1.0, v87
	v_rcp_f32_e32 v98, v87
	v_mul_f32_e32 v87, 0xbfb8aa3b, v95
	v_exp_f32_e32 v87, v87
	v_cvt_pk_bf16_f32 v56, v56, v57
	v_add_f32_e32 v87, 1.0, v87
	v_rcp_f32_e32 v99, v87
	s_nop 0
	v_pk_mul_f32 v[92:93], v[98:99], v[94:95]
	s_nop 0
	v_pk_mul_f32 v[58:59], v[58:59], v[92:93]
	s_nop 0
	v_cvt_pk_bf16_f32 v57, v58, v59
	global_store_dwordx2 v[90:91], v[56:57], off
	v_or_b32_e32 v56, 32, v86
	v_or_b32_e32 v58, v74, v56
	v_mov_b32_e32 v59, v75
	v_lshlrev_b64 v[58:59], 1, v[58:59]
	v_lshl_add_u64 v[88:89], s[90:91], 0, v[58:59]
	v_lshl_add_u64 v[58:59], s[86:87], 0, v[58:59]
	global_load_dwordx2 v[90:91], v[88:89], off
	s_nop 0
	global_load_dwordx2 v[58:59], v[58:59], off
	s_waitcnt vmcnt(1)
	v_and_b32_e32 v99, 0xffff0000, v91
	s_waitcnt vmcnt(0)
	v_and_b32_e32 v93, 0xffff0000, v59
	v_lshlrev_b32_e32 v92, 16, v59
	v_and_b32_e32 v59, 0xffff0000, v58
	v_lshlrev_b32_e32 v58, 16, v58
	v_mul_f32_e32 v57, 0xbfb8aa3b, v58
	v_exp_f32_e32 v57, v57
	v_lshlrev_b32_e32 v98, 16, v91
	v_and_b32_e32 v91, 0xffff0000, v90
	v_lshlrev_b32_e32 v90, 16, v90
	v_add_f32_e32 v57, 1.0, v57
	v_rcp_f32_e32 v94, v57
	v_mul_f32_e32 v57, 0xbfb8aa3b, v59
	v_exp_f32_e32 v57, v57
	v_pk_mul_f32 v[52:53], v[52:53], v[90:91]
	v_pk_mul_f32 v[54:55], v[54:55], v[98:99]
	v_add_f32_e32 v57, 1.0, v57
	v_rcp_f32_e32 v95, v57
	v_mul_f32_e32 v57, 0xbfb8aa3b, v92
	v_exp_f32_e32 v57, v57
	v_pk_mul_f32 v[58:59], v[94:95], v[58:59]
	s_nop 0
	v_pk_mul_f32 v[52:53], v[52:53], v[58:59]
	v_add_f32_e32 v57, 1.0, v57
	v_rcp_f32_e32 v96, v57
	v_mul_f32_e32 v57, 0xbfb8aa3b, v93
	v_exp_f32_e32 v57, v57
	v_cvt_pk_bf16_f32 v52, v52, v53
	v_add_f32_e32 v57, 1.0, v57
	v_rcp_f32_e32 v97, v57
	s_nop 0
	v_pk_mul_f32 v[90:91], v[96:97], v[92:93]
	s_nop 0
	v_pk_mul_f32 v[54:55], v[54:55], v[90:91]
	s_nop 0
	v_cvt_pk_bf16_f32 v53, v54, v55
	global_store_dwordx2 v[88:89], v[52:53], off
	v_or_b32_e32 v52, 48, v86
	v_or_b32_e32 v74, v74, v52
	v_lshlrev_b64 v[54:55], 1, v[74:75]
	v_lshl_add_u64 v[58:59], s[90:91], 0, v[54:55]
	v_lshl_add_u64 v[54:55], s[86:87], 0, v[54:55]
	global_load_dwordx2 v[74:75], v[58:59], off
	s_nop 0
	global_load_dwordx2 v[54:55], v[54:55], off
	s_waitcnt vmcnt(1)
	v_and_b32_e32 v95, 0xffff0000, v75
	s_waitcnt vmcnt(0)
	v_and_b32_e32 v89, 0xffff0000, v55
	v_lshlrev_b32_e32 v88, 16, v55
	v_and_b32_e32 v55, 0xffff0000, v54
	v_lshlrev_b32_e32 v54, 16, v54
	v_mul_f32_e32 v53, 0xbfb8aa3b, v54
	v_exp_f32_e32 v53, v53
	v_lshlrev_b32_e32 v94, 16, v75
	v_and_b32_e32 v75, 0xffff0000, v74
	v_lshlrev_b32_e32 v74, 16, v74
	v_add_f32_e32 v53, 1.0, v53
	v_rcp_f32_e32 v90, v53
	v_mul_f32_e32 v53, 0xbfb8aa3b, v55
	v_exp_f32_e32 v53, v53
	v_pk_mul_f32 v[48:49], v[48:49], v[74:75]
	v_pk_mul_f32 v[50:51], v[50:51], v[94:95]
	v_add_f32_e32 v53, 1.0, v53
	v_rcp_f32_e32 v91, v53
	v_mul_f32_e32 v53, 0xbfb8aa3b, v88
	v_exp_f32_e32 v53, v53
	v_pk_mul_f32 v[54:55], v[90:91], v[54:55]
	s_nop 0
	v_pk_mul_f32 v[48:49], v[48:49], v[54:55]
	v_add_f32_e32 v53, 1.0, v53
	v_rcp_f32_e32 v92, v53
	v_mul_f32_e32 v53, 0xbfb8aa3b, v89
	v_exp_f32_e32 v53, v53
	v_cvt_pk_bf16_f32 v48, v48, v49
	v_add_f32_e32 v53, 1.0, v53
	v_rcp_f32_e32 v93, v53
	s_nop 0
	v_pk_mul_f32 v[74:75], v[92:93], v[88:89]
	s_nop 0
	v_pk_mul_f32 v[50:51], v[50:51], v[74:75]
	s_nop 0
	v_cvt_pk_bf16_f32 v49, v50, v51
	v_add_u32_e32 v50, s0, v82
	v_ashrrev_i32_e32 v51, 31, v50
	v_lshlrev_b64 v[50:51], 11, v[50:51]
	v_or_b32_e32 v54, v50, v86
	v_mov_b32_e32 v55, v51
	v_lshlrev_b64 v[54:55], 1, v[54:55]
	global_store_dwordx2 v[58:59], v[48:49], off
	v_lshl_add_u64 v[58:59], s[90:91], 0, v[54:55]
	v_lshl_add_u64 v[54:55], s[86:87], 0, v[54:55]
	global_load_dword v48, v[72:73], off offset:64
	global_load_dwordx2 v[74:75], v[58:59], off
	s_nop 0
	global_load_dwordx2 v[54:55], v[54:55], off
	s_waitcnt vmcnt(1)
	v_and_b32_e32 v95, 0xffff0000, v75
	s_waitcnt vmcnt(0)
	v_and_b32_e32 v89, 0xffff0000, v55
	v_lshlrev_b32_e32 v88, 16, v55
	v_and_b32_e32 v55, 0xffff0000, v54
	v_lshlrev_b32_e32 v54, 16, v54
	v_mul_f32_e32 v49, 0xbfb8aa3b, v54
	v_exp_f32_e32 v49, v49
	v_lshlrev_b32_e32 v94, 16, v75
	v_and_b32_e32 v75, 0xffff0000, v74
	v_lshlrev_b32_e32 v74, 16, v74
	v_add_f32_e32 v49, 1.0, v49
	v_rcp_f32_e32 v90, v49
	v_mul_f32_e32 v49, 0xbfb8aa3b, v55
	v_exp_f32_e32 v49, v49
	s_nop 0
	v_add_f32_e32 v49, 1.0, v49
	v_rcp_f32_e32 v91, v49
	v_mul_f32_e32 v49, 0xbfb8aa3b, v88
	v_exp_f32_e32 v49, v49
	v_pk_mul_f32 v[54:55], v[90:91], v[54:55]
	v_add_f32_e32 v49, 1.0, v49
	v_rcp_f32_e32 v92, v49
	v_pk_add_f32 v[46:47], v[46:47], v[48:49] op_sel_hi:[1,0]
	v_pk_add_f32 v[44:45], v[44:45], v[48:49] op_sel_hi:[1,0]
	v_mul_f32_e32 v49, 0xbfb8aa3b, v89
	v_exp_f32_e32 v49, v49
	v_pk_mul_f32 v[44:45], v[44:45], v[74:75]
	v_pk_mul_f32 v[46:47], v[46:47], v[94:95]
	v_pk_mul_f32 v[44:45], v[44:45], v[54:55]
	v_add_f32_e32 v49, 1.0, v49
	v_rcp_f32_e32 v93, v49
	v_cvt_pk_bf16_f32 v44, v44, v45
	v_pk_mul_f32 v[74:75], v[92:93], v[88:89]
	s_nop 0
	v_pk_mul_f32 v[46:47], v[46:47], v[74:75]
	s_nop 0
	v_cvt_pk_bf16_f32 v45, v46, v47
	global_store_dwordx2 v[58:59], v[44:45], off
	v_or_b32_e32 v44, v50, v85
	v_mov_b32_e32 v45, v51
	v_lshlrev_b64 v[44:45], 1, v[44:45]
	v_lshl_add_u64 v[46:47], s[90:91], 0, v[44:45]
	v_lshl_add_u64 v[44:45], s[86:87], 0, v[44:45]
	global_load_dwordx2 v[54:55], v[46:47], off
	s_nop 0
	global_load_dwordx2 v[44:45], v[44:45], off
	s_waitcnt vmcnt(1)
	v_and_b32_e32 v91, 0xffff0000, v55
	s_waitcnt vmcnt(0)
	v_and_b32_e32 v59, 0xffff0000, v45
	v_lshlrev_b32_e32 v58, 16, v45
	v_and_b32_e32 v45, 0xffff0000, v44
	v_lshlrev_b32_e32 v44, 16, v44
	v_mul_f32_e32 v49, 0xbfb8aa3b, v44
	v_exp_f32_e32 v49, v49
	v_lshlrev_b32_e32 v90, 16, v55
	v_and_b32_e32 v55, 0xffff0000, v54
	v_lshlrev_b32_e32 v54, 16, v54
	v_add_f32_e32 v49, 1.0, v49
	v_rcp_f32_e32 v74, v49
	v_mul_f32_e32 v49, 0xbfb8aa3b, v45
	v_exp_f32_e32 v49, v49
	s_nop 0
	v_add_f32_e32 v49, 1.0, v49
	v_rcp_f32_e32 v75, v49
	v_mul_f32_e32 v49, 0xbfb8aa3b, v58
	v_exp_f32_e32 v49, v49
	v_pk_mul_f32 v[44:45], v[74:75], v[44:45]
	v_add_f32_e32 v49, 1.0, v49
	v_rcp_f32_e32 v88, v49
	v_pk_add_f32 v[42:43], v[42:43], v[48:49] op_sel_hi:[1,0]
	v_pk_add_f32 v[40:41], v[40:41], v[48:49] op_sel_hi:[1,0]
	v_mul_f32_e32 v49, 0xbfb8aa3b, v59
	v_exp_f32_e32 v49, v49
	v_pk_mul_f32 v[40:41], v[40:41], v[54:55]
	v_pk_mul_f32 v[42:43], v[42:43], v[90:91]
	v_pk_mul_f32 v[40:41], v[40:41], v[44:45]
	v_add_f32_e32 v49, 1.0, v49
	v_rcp_f32_e32 v89, v49
	v_cvt_pk_bf16_f32 v40, v40, v41
	v_pk_mul_f32 v[54:55], v[88:89], v[58:59]
	s_nop 0
	v_pk_mul_f32 v[42:43], v[42:43], v[54:55]
	s_nop 0
	v_cvt_pk_bf16_f32 v41, v42, v43
	global_store_dwordx2 v[46:47], v[40:41], off
	v_or_b32_e32 v40, v50, v56
	v_mov_b32_e32 v41, v51
	v_lshlrev_b64 v[40:41], 1, v[40:41]
	v_lshl_add_u64 v[42:43], s[90:91], 0, v[40:41]
	v_lshl_add_u64 v[40:41], s[86:87], 0, v[40:41]
	global_load_dwordx2 v[44:45], v[42:43], off
	s_nop 0
	global_load_dwordx2 v[40:41], v[40:41], off
	v_or_b32_e32 v50, v50, v52
	s_waitcnt vmcnt(1)
	v_and_b32_e32 v75, 0xffff0000, v45
	s_waitcnt vmcnt(0)
	v_and_b32_e32 v47, 0xffff0000, v41
	v_lshlrev_b32_e32 v46, 16, v41
	v_and_b32_e32 v41, 0xffff0000, v40
	v_lshlrev_b32_e32 v40, 16, v40
	v_mul_f32_e32 v49, 0xbfb8aa3b, v40
	v_exp_f32_e32 v49, v49
	v_lshlrev_b32_e32 v74, 16, v45
	v_and_b32_e32 v45, 0xffff0000, v44
	v_lshlrev_b32_e32 v44, 16, v44
	v_add_f32_e32 v49, 1.0, v49
	v_rcp_f32_e32 v54, v49
	v_mul_f32_e32 v49, 0xbfb8aa3b, v41
	v_exp_f32_e32 v49, v49
	s_nop 0
	v_add_f32_e32 v49, 1.0, v49
	v_rcp_f32_e32 v55, v49
	v_mul_f32_e32 v49, 0xbfb8aa3b, v46
	v_exp_f32_e32 v49, v49
	v_pk_mul_f32 v[40:41], v[54:55], v[40:41]
	v_add_f32_e32 v49, 1.0, v49
	v_pk_add_f32 v[36:37], v[36:37], v[48:49] op_sel_hi:[1,0]
	v_rcp_f32_e32 v58, v49
	v_pk_mul_f32 v[36:37], v[36:37], v[44:45]
	v_mul_f32_e32 v44, 0xbfb8aa3b, v47
	v_exp_f32_e32 v44, v44
	v_pk_add_f32 v[38:39], v[38:39], v[48:49] op_sel_hi:[1,0]
	v_pk_mul_f32 v[36:37], v[36:37], v[40:41]
	v_pk_mul_f32 v[38:39], v[38:39], v[74:75]
	v_add_f32_e32 v44, 1.0, v44
	v_rcp_f32_e32 v59, v44
	v_cvt_pk_bf16_f32 v36, v36, v37
	v_pk_add_f32 v[32:33], v[32:33], v[48:49] op_sel_hi:[1,0]
	v_pk_add_f32 v[34:35], v[34:35], v[48:49] op_sel_hi:[1,0]
	v_pk_mul_f32 v[44:45], v[58:59], v[46:47]
	s_nop 0
	v_pk_mul_f32 v[38:39], v[38:39], v[44:45]
	s_nop 0
	v_cvt_pk_bf16_f32 v37, v38, v39
	global_store_dwordx2 v[42:43], v[36:37], off
	v_lshlrev_b64 v[36:37], 1, v[50:51]
	v_lshl_add_u64 v[38:39], s[90:91], 0, v[36:37]
	v_lshl_add_u64 v[36:37], s[86:87], 0, v[36:37]
	global_load_dwordx2 v[40:41], v[38:39], off
	s_nop 0
	global_load_dwordx2 v[36:37], v[36:37], off
	s_waitcnt vmcnt(1)
	v_and_b32_e32 v51, 0xffff0000, v41
	s_waitcnt vmcnt(0)
	v_and_b32_e32 v43, 0xffff0000, v37
	v_lshlrev_b32_e32 v42, 16, v37
	v_and_b32_e32 v37, 0xffff0000, v36
	v_lshlrev_b32_e32 v36, 16, v36
	v_lshlrev_b32_e32 v50, 16, v41
	v_and_b32_e32 v41, 0xffff0000, v40
	v_lshlrev_b32_e32 v40, 16, v40
	v_mul_f32_e32 v44, 0xbfb8aa3b, v36
	v_mul_f32_e32 v45, 0xbfb8aa3b, v37
	v_mul_f32_e32 v46, 0xbfb8aa3b, v42
	v_pk_mul_f32 v[32:33], v[32:33], v[40:41]
	v_mul_f32_e32 v40, 0xbfb8aa3b, v43
	v_exp_f32_e32 v44, v44
	v_exp_f32_e32 v45, v45
	v_exp_f32_e32 v46, v46
	v_exp_f32_e32 v40, v40
	v_add_f32_e32 v44, 1.0, v44
	v_add_f32_e32 v45, 1.0, v45
	v_add_f32_e32 v46, 1.0, v46
	v_add_f32_e32 v40, 1.0, v40
	v_rcp_f32_e32 v44, v44
	v_rcp_f32_e32 v45, v45
	v_rcp_f32_e32 v46, v46
	v_rcp_f32_e32 v47, v40
	v_pk_mul_f32 v[34:35], v[34:35], v[50:51]
	v_pk_mul_f32 v[36:37], v[44:45], v[36:37]
	v_pk_mul_f32 v[40:41], v[46:47], v[42:43]
	s_nop 0
	v_pk_mul_f32 v[34:35], v[34:35], v[40:41]
	v_pk_mul_f32 v[32:33], v[32:33], v[36:37]
	s_nop 0
	v_cvt_pk_bf16_f32 v32, v32, v33
	v_cvt_pk_bf16_f32 v33, v34, v35
	v_add_u32_e32 v34, s0, v83
	v_ashrrev_i32_e32 v35, 31, v34
	v_lshlrev_b64 v[34:35], 11, v[34:35]
	v_or_b32_e32 v36, v34, v86
	v_mov_b32_e32 v37, v35
	v_lshlrev_b64 v[36:37], 1, v[36:37]
	global_store_dwordx2 v[38:39], v[32:33], off
	v_lshl_add_u64 v[38:39], s[90:91], 0, v[36:37]
	v_lshl_add_u64 v[36:37], s[86:87], 0, v[36:37]
	global_load_dword v32, v[72:73], off offset:128
	global_load_dwordx2 v[40:41], v[38:39], off
	s_nop 0
	global_load_dwordx2 v[36:37], v[36:37], off
	s_waitcnt vmcnt(1)
	v_and_b32_e32 v49, 0xffff0000, v41
	s_waitcnt vmcnt(0)
	v_and_b32_e32 v43, 0xffff0000, v37
	v_lshlrev_b32_e32 v42, 16, v37
	v_and_b32_e32 v37, 0xffff0000, v36
	v_lshlrev_b32_e32 v36, 16, v36
	v_mul_f32_e32 v33, 0xbfb8aa3b, v36
	v_exp_f32_e32 v33, v33
	v_lshlrev_b32_e32 v48, 16, v41
	v_and_b32_e32 v41, 0xffff0000, v40
	v_lshlrev_b32_e32 v40, 16, v40
	v_add_f32_e32 v33, 1.0, v33
	v_rcp_f32_e32 v44, v33
	v_mul_f32_e32 v33, 0xbfb8aa3b, v37
	v_exp_f32_e32 v33, v33
	s_nop 0
	v_add_f32_e32 v33, 1.0, v33
	v_rcp_f32_e32 v45, v33
	v_mul_f32_e32 v33, 0xbfb8aa3b, v42
	v_exp_f32_e32 v33, v33
	v_pk_mul_f32 v[36:37], v[44:45], v[36:37]
	v_add_f32_e32 v33, 1.0, v33
	v_rcp_f32_e32 v46, v33
	v_pk_add_f32 v[30:31], v[30:31], v[32:33] op_sel_hi:[1,0]
	v_pk_add_f32 v[28:29], v[28:29], v[32:33] op_sel_hi:[1,0]
	v_mul_f32_e32 v33, 0xbfb8aa3b, v43
	v_exp_f32_e32 v33, v33
	v_pk_mul_f32 v[28:29], v[28:29], v[40:41]
	v_pk_mul_f32 v[30:31], v[30:31], v[48:49]
	v_pk_mul_f32 v[28:29], v[28:29], v[36:37]
	v_add_f32_e32 v33, 1.0, v33
	v_rcp_f32_e32 v47, v33
	v_cvt_pk_bf16_f32 v28, v28, v29
	v_pk_mul_f32 v[40:41], v[46:47], v[42:43]
	s_nop 0
	v_pk_mul_f32 v[30:31], v[30:31], v[40:41]
	s_nop 0
	v_cvt_pk_bf16_f32 v29, v30, v31
	global_store_dwordx2 v[38:39], v[28:29], off
	v_or_b32_e32 v28, v34, v85
	v_mov_b32_e32 v29, v35
	v_lshlrev_b64 v[28:29], 1, v[28:29]
	v_lshl_add_u64 v[30:31], s[90:91], 0, v[28:29]
	v_lshl_add_u64 v[28:29], s[86:87], 0, v[28:29]
	global_load_dwordx2 v[36:37], v[30:31], off
	s_nop 0
	global_load_dwordx2 v[28:29], v[28:29], off
	s_waitcnt vmcnt(1)
	v_and_b32_e32 v45, 0xffff0000, v37
	s_waitcnt vmcnt(0)
	v_and_b32_e32 v39, 0xffff0000, v29
	v_lshlrev_b32_e32 v38, 16, v29
	v_and_b32_e32 v29, 0xffff0000, v28
	v_lshlrev_b32_e32 v28, 16, v28
	v_mul_f32_e32 v33, 0xbfb8aa3b, v28
	v_exp_f32_e32 v33, v33
	v_lshlrev_b32_e32 v44, 16, v37
	v_and_b32_e32 v37, 0xffff0000, v36
	v_lshlrev_b32_e32 v36, 16, v36
	v_add_f32_e32 v33, 1.0, v33
	v_rcp_f32_e32 v40, v33
	v_mul_f32_e32 v33, 0xbfb8aa3b, v29
	v_exp_f32_e32 v33, v33
	s_nop 0
	v_add_f32_e32 v33, 1.0, v33
	v_rcp_f32_e32 v41, v33
	v_mul_f32_e32 v33, 0xbfb8aa3b, v38
	v_exp_f32_e32 v33, v33
	v_pk_mul_f32 v[28:29], v[40:41], v[28:29]
	v_add_f32_e32 v33, 1.0, v33
	v_rcp_f32_e32 v42, v33
	v_pk_add_f32 v[26:27], v[26:27], v[32:33] op_sel_hi:[1,0]
	v_pk_add_f32 v[24:25], v[24:25], v[32:33] op_sel_hi:[1,0]
	v_mul_f32_e32 v33, 0xbfb8aa3b, v39
	v_exp_f32_e32 v33, v33
	v_pk_mul_f32 v[24:25], v[24:25], v[36:37]
	v_pk_mul_f32 v[26:27], v[26:27], v[44:45]
	v_pk_mul_f32 v[24:25], v[24:25], v[28:29]
	v_add_f32_e32 v33, 1.0, v33
	v_rcp_f32_e32 v43, v33
	v_cvt_pk_bf16_f32 v24, v24, v25
	v_pk_mul_f32 v[36:37], v[42:43], v[38:39]
	s_nop 0
	v_pk_mul_f32 v[26:27], v[26:27], v[36:37]
	s_nop 0
	v_cvt_pk_bf16_f32 v25, v26, v27
	global_store_dwordx2 v[30:31], v[24:25], off
	v_or_b32_e32 v24, v34, v56
	v_mov_b32_e32 v25, v35
	v_lshlrev_b64 v[24:25], 1, v[24:25]
	v_lshl_add_u64 v[26:27], s[90:91], 0, v[24:25]
	v_lshl_add_u64 v[24:25], s[86:87], 0, v[24:25]
	global_load_dwordx2 v[28:29], v[26:27], off
	s_nop 0
	global_load_dwordx2 v[24:25], v[24:25], off
	v_or_b32_e32 v34, v34, v52
	s_waitcnt vmcnt(1)
	v_and_b32_e32 v41, 0xffff0000, v29
	s_waitcnt vmcnt(0)
	v_and_b32_e32 v31, 0xffff0000, v25
	v_lshlrev_b32_e32 v30, 16, v25
	v_and_b32_e32 v25, 0xffff0000, v24
	v_lshlrev_b32_e32 v24, 16, v24
	v_mul_f32_e32 v33, 0xbfb8aa3b, v24
	v_exp_f32_e32 v33, v33
	v_lshlrev_b32_e32 v40, 16, v29
	v_and_b32_e32 v29, 0xffff0000, v28
	v_lshlrev_b32_e32 v28, 16, v28
	v_add_f32_e32 v33, 1.0, v33
	v_rcp_f32_e32 v36, v33
	v_mul_f32_e32 v33, 0xbfb8aa3b, v25
	v_exp_f32_e32 v33, v33
	s_nop 0
	v_add_f32_e32 v33, 1.0, v33
	v_rcp_f32_e32 v37, v33
	v_mul_f32_e32 v33, 0xbfb8aa3b, v30
	v_exp_f32_e32 v33, v33
	v_pk_mul_f32 v[24:25], v[36:37], v[24:25]
	v_add_f32_e32 v33, 1.0, v33
	v_pk_add_f32 v[20:21], v[20:21], v[32:33] op_sel_hi:[1,0]
	v_rcp_f32_e32 v38, v33
	v_pk_mul_f32 v[20:21], v[20:21], v[28:29]
	v_mul_f32_e32 v28, 0xbfb8aa3b, v31
	v_exp_f32_e32 v28, v28
	v_pk_add_f32 v[22:23], v[22:23], v[32:33] op_sel_hi:[1,0]
	v_pk_mul_f32 v[20:21], v[20:21], v[24:25]
	v_pk_mul_f32 v[22:23], v[22:23], v[40:41]
	v_add_f32_e32 v28, 1.0, v28
	v_rcp_f32_e32 v39, v28
	v_cvt_pk_bf16_f32 v20, v20, v21
	v_pk_add_f32 v[16:17], v[16:17], v[32:33] op_sel_hi:[1,0]
	v_pk_add_f32 v[18:19], v[18:19], v[32:33] op_sel_hi:[1,0]
	v_pk_mul_f32 v[28:29], v[38:39], v[30:31]
	s_nop 0
	v_pk_mul_f32 v[22:23], v[22:23], v[28:29]
	s_nop 0
	v_cvt_pk_bf16_f32 v21, v22, v23
	global_store_dwordx2 v[26:27], v[20:21], off
	v_lshlrev_b64 v[20:21], 1, v[34:35]
	v_lshl_add_u64 v[22:23], s[90:91], 0, v[20:21]
	v_lshl_add_u64 v[20:21], s[86:87], 0, v[20:21]
	global_load_dwordx2 v[24:25], v[22:23], off
	s_nop 0
	global_load_dwordx2 v[20:21], v[20:21], off
	s_waitcnt vmcnt(1)
	v_and_b32_e32 v35, 0xffff0000, v25
	s_waitcnt vmcnt(0)
	v_and_b32_e32 v27, 0xffff0000, v21
	v_lshlrev_b32_e32 v26, 16, v21
	v_and_b32_e32 v21, 0xffff0000, v20
	v_lshlrev_b32_e32 v20, 16, v20
	v_lshlrev_b32_e32 v34, 16, v25
	v_and_b32_e32 v25, 0xffff0000, v24
	v_lshlrev_b32_e32 v24, 16, v24
	v_mul_f32_e32 v28, 0xbfb8aa3b, v20
	v_mul_f32_e32 v29, 0xbfb8aa3b, v21
	v_mul_f32_e32 v30, 0xbfb8aa3b, v26
	v_pk_mul_f32 v[16:17], v[16:17], v[24:25]
	v_mul_f32_e32 v24, 0xbfb8aa3b, v27
	v_exp_f32_e32 v28, v28
	v_exp_f32_e32 v29, v29
	v_exp_f32_e32 v30, v30
	v_exp_f32_e32 v24, v24
	v_add_f32_e32 v28, 1.0, v28
	v_add_f32_e32 v29, 1.0, v29
	v_add_f32_e32 v30, 1.0, v30
	v_add_f32_e32 v24, 1.0, v24
	v_rcp_f32_e32 v28, v28
	v_rcp_f32_e32 v29, v29
	v_rcp_f32_e32 v30, v30
	v_rcp_f32_e32 v31, v24
	v_pk_mul_f32 v[18:19], v[18:19], v[34:35]
	v_pk_mul_f32 v[20:21], v[28:29], v[20:21]
	v_pk_mul_f32 v[24:25], v[30:31], v[26:27]
	s_nop 0
	v_pk_mul_f32 v[18:19], v[18:19], v[24:25]
	v_pk_mul_f32 v[16:17], v[16:17], v[20:21]
	s_nop 0
	v_cvt_pk_bf16_f32 v16, v16, v17
	v_cvt_pk_bf16_f32 v17, v18, v19
	v_add_u32_e32 v18, s0, v77
	v_ashrrev_i32_e32 v19, 31, v18
	v_lshlrev_b64 v[18:19], 11, v[18:19]
	v_or_b32_e32 v20, v18, v86
	v_mov_b32_e32 v21, v19
	v_lshlrev_b64 v[20:21], 1, v[20:21]
	global_store_dwordx2 v[22:23], v[16:17], off
	v_lshl_add_u64 v[22:23], s[90:91], 0, v[20:21]
	v_lshl_add_u64 v[20:21], s[86:87], 0, v[20:21]
	global_load_dword v16, v[72:73], off offset:192
	global_load_dwordx2 v[24:25], v[22:23], off
	s_nop 0
	global_load_dwordx2 v[20:21], v[20:21], off
	s_waitcnt vmcnt(1)
	v_and_b32_e32 v33, 0xffff0000, v25
	s_waitcnt vmcnt(0)
	v_and_b32_e32 v27, 0xffff0000, v21
	v_lshlrev_b32_e32 v26, 16, v21
	v_and_b32_e32 v21, 0xffff0000, v20
	v_lshlrev_b32_e32 v20, 16, v20
	v_mul_f32_e32 v17, 0xbfb8aa3b, v20
	v_exp_f32_e32 v17, v17
	v_lshlrev_b32_e32 v32, 16, v25
	v_and_b32_e32 v25, 0xffff0000, v24
	v_lshlrev_b32_e32 v24, 16, v24
	v_add_f32_e32 v17, 1.0, v17
	v_rcp_f32_e32 v28, v17
	v_mul_f32_e32 v17, 0xbfb8aa3b, v21
	v_exp_f32_e32 v17, v17
	s_nop 0
	v_add_f32_e32 v17, 1.0, v17
	v_rcp_f32_e32 v29, v17
	v_mul_f32_e32 v17, 0xbfb8aa3b, v26
	v_exp_f32_e32 v17, v17
	v_pk_mul_f32 v[20:21], v[28:29], v[20:21]
	v_add_f32_e32 v17, 1.0, v17
	v_rcp_f32_e32 v30, v17
	v_pk_add_f32 v[14:15], v[14:15], v[16:17] op_sel_hi:[1,0]
	v_pk_add_f32 v[12:13], v[12:13], v[16:17] op_sel_hi:[1,0]
	v_mul_f32_e32 v17, 0xbfb8aa3b, v27
	v_exp_f32_e32 v17, v17
	v_pk_mul_f32 v[12:13], v[12:13], v[24:25]
	v_pk_mul_f32 v[14:15], v[14:15], v[32:33]
	v_pk_mul_f32 v[12:13], v[12:13], v[20:21]
	v_add_f32_e32 v17, 1.0, v17
	v_rcp_f32_e32 v31, v17
	v_cvt_pk_bf16_f32 v12, v12, v13
	v_pk_mul_f32 v[24:25], v[30:31], v[26:27]
	s_nop 0
	v_pk_mul_f32 v[14:15], v[14:15], v[24:25]
	s_nop 0
	v_cvt_pk_bf16_f32 v13, v14, v15
	global_store_dwordx2 v[22:23], v[12:13], off
	v_or_b32_e32 v12, v18, v85
	v_mov_b32_e32 v13, v19
	v_lshlrev_b64 v[12:13], 1, v[12:13]
	v_lshl_add_u64 v[14:15], s[90:91], 0, v[12:13]
	v_lshl_add_u64 v[12:13], s[86:87], 0, v[12:13]
	global_load_dwordx2 v[20:21], v[14:15], off
	s_nop 0
	global_load_dwordx2 v[12:13], v[12:13], off
	s_waitcnt vmcnt(1)
	v_and_b32_e32 v29, 0xffff0000, v21
	s_waitcnt vmcnt(0)
	v_and_b32_e32 v23, 0xffff0000, v13
	v_lshlrev_b32_e32 v22, 16, v13
	v_and_b32_e32 v13, 0xffff0000, v12
	v_lshlrev_b32_e32 v12, 16, v12
	v_mul_f32_e32 v17, 0xbfb8aa3b, v12
	v_exp_f32_e32 v17, v17
	v_lshlrev_b32_e32 v28, 16, v21
	v_and_b32_e32 v21, 0xffff0000, v20
	v_lshlrev_b32_e32 v20, 16, v20
	v_add_f32_e32 v17, 1.0, v17
	v_rcp_f32_e32 v24, v17
	v_mul_f32_e32 v17, 0xbfb8aa3b, v13
	v_exp_f32_e32 v17, v17
	s_nop 0
	v_add_f32_e32 v17, 1.0, v17
	v_rcp_f32_e32 v25, v17
	v_mul_f32_e32 v17, 0xbfb8aa3b, v22
	v_exp_f32_e32 v17, v17
	v_pk_mul_f32 v[12:13], v[24:25], v[12:13]
	v_add_f32_e32 v17, 1.0, v17
	v_rcp_f32_e32 v26, v17
	v_pk_add_f32 v[10:11], v[10:11], v[16:17] op_sel_hi:[1,0]
	v_pk_add_f32 v[8:9], v[8:9], v[16:17] op_sel_hi:[1,0]
	v_mul_f32_e32 v17, 0xbfb8aa3b, v23
	v_exp_f32_e32 v17, v17
	v_pk_mul_f32 v[8:9], v[8:9], v[20:21]
	v_pk_mul_f32 v[10:11], v[10:11], v[28:29]
	v_pk_mul_f32 v[8:9], v[8:9], v[12:13]
	v_add_f32_e32 v17, 1.0, v17
	v_rcp_f32_e32 v27, v17
	v_cvt_pk_bf16_f32 v8, v8, v9
	v_pk_mul_f32 v[20:21], v[26:27], v[22:23]
	s_nop 0
	v_pk_mul_f32 v[10:11], v[10:11], v[20:21]
	s_nop 0
	v_cvt_pk_bf16_f32 v9, v10, v11
	global_store_dwordx2 v[14:15], v[8:9], off
	v_or_b32_e32 v8, v18, v56
	v_mov_b32_e32 v9, v19
	v_lshlrev_b64 v[8:9], 1, v[8:9]
	v_lshl_add_u64 v[10:11], s[90:91], 0, v[8:9]
	v_lshl_add_u64 v[8:9], s[86:87], 0, v[8:9]
	global_load_dwordx2 v[12:13], v[10:11], off
	s_nop 0
	global_load_dwordx2 v[8:9], v[8:9], off
	v_or_b32_e32 v18, v18, v52
	s_waitcnt vmcnt(1)
	v_and_b32_e32 v25, 0xffff0000, v13
	s_waitcnt vmcnt(0)
	v_and_b32_e32 v15, 0xffff0000, v9
	v_lshlrev_b32_e32 v14, 16, v9
	v_and_b32_e32 v9, 0xffff0000, v8
	v_lshlrev_b32_e32 v8, 16, v8
	v_mul_f32_e32 v17, 0xbfb8aa3b, v8
	v_exp_f32_e32 v17, v17
	v_lshlrev_b32_e32 v24, 16, v13
	v_and_b32_e32 v13, 0xffff0000, v12
	v_lshlrev_b32_e32 v12, 16, v12
	v_add_f32_e32 v17, 1.0, v17
	v_rcp_f32_e32 v20, v17
	v_mul_f32_e32 v17, 0xbfb8aa3b, v9
	v_exp_f32_e32 v17, v17
	s_nop 0
	v_add_f32_e32 v17, 1.0, v17
	v_rcp_f32_e32 v21, v17
	v_mul_f32_e32 v17, 0xbfb8aa3b, v14
	v_exp_f32_e32 v17, v17
	v_pk_mul_f32 v[8:9], v[20:21], v[8:9]
	v_add_f32_e32 v17, 1.0, v17
	v_pk_add_f32 v[4:5], v[4:5], v[16:17] op_sel_hi:[1,0]
	v_rcp_f32_e32 v22, v17
	v_pk_mul_f32 v[4:5], v[4:5], v[12:13]
	v_mul_f32_e32 v12, 0xbfb8aa3b, v15
	v_exp_f32_e32 v12, v12
	v_pk_add_f32 v[6:7], v[6:7], v[16:17] op_sel_hi:[1,0]
	v_pk_mul_f32 v[4:5], v[4:5], v[8:9]
	v_pk_mul_f32 v[6:7], v[6:7], v[24:25]
	v_add_f32_e32 v12, 1.0, v12
	v_rcp_f32_e32 v23, v12
	v_cvt_pk_bf16_f32 v4, v4, v5
	v_pk_add_f32 v[0:1], v[0:1], v[16:17] op_sel_hi:[1,0]
	v_pk_add_f32 v[2:3], v[2:3], v[16:17] op_sel_hi:[1,0]
	v_pk_mul_f32 v[12:13], v[22:23], v[14:15]
	s_nop 0
	v_pk_mul_f32 v[6:7], v[6:7], v[12:13]
	s_nop 0
	v_cvt_pk_bf16_f32 v5, v6, v7
	global_store_dwordx2 v[10:11], v[4:5], off
	v_lshlrev_b64 v[4:5], 1, v[18:19]
	v_lshl_add_u64 v[6:7], s[90:91], 0, v[4:5]
	v_lshl_add_u64 v[4:5], s[86:87], 0, v[4:5]
	global_load_dwordx2 v[8:9], v[6:7], off
	s_nop 0
	global_load_dwordx2 v[4:5], v[4:5], off
	s_waitcnt vmcnt(1)
	v_and_b32_e32 v19, 0xffff0000, v9
	s_waitcnt vmcnt(0)
	v_and_b32_e32 v11, 0xffff0000, v5
	v_lshlrev_b32_e32 v10, 16, v5
	v_and_b32_e32 v5, 0xffff0000, v4
	v_lshlrev_b32_e32 v4, 16, v4
	v_lshlrev_b32_e32 v18, 16, v9
	v_and_b32_e32 v9, 0xffff0000, v8
	v_lshlrev_b32_e32 v8, 16, v8
	v_mul_f32_e32 v12, 0xbfb8aa3b, v4
	v_mul_f32_e32 v13, 0xbfb8aa3b, v5
	v_mul_f32_e32 v14, 0xbfb8aa3b, v10
	v_pk_mul_f32 v[0:1], v[0:1], v[8:9]
	v_mul_f32_e32 v8, 0xbfb8aa3b, v11
	v_exp_f32_e32 v12, v12
	v_exp_f32_e32 v13, v13
	v_exp_f32_e32 v14, v14
	v_exp_f32_e32 v8, v8
	v_add_f32_e32 v12, 1.0, v12
	v_add_f32_e32 v13, 1.0, v13
	v_add_f32_e32 v14, 1.0, v14
	v_add_f32_e32 v8, 1.0, v8
	v_rcp_f32_e32 v12, v12
	v_rcp_f32_e32 v13, v13
	v_rcp_f32_e32 v14, v14
	v_rcp_f32_e32 v15, v8
	v_pk_mul_f32 v[2:3], v[2:3], v[18:19]
	v_pk_mul_f32 v[4:5], v[12:13], v[4:5]
	v_pk_mul_f32 v[8:9], v[14:15], v[10:11]
	s_nop 0
	v_pk_mul_f32 v[2:3], v[2:3], v[8:9]
	v_pk_mul_f32 v[0:1], v[0:1], v[4:5]
	s_nop 0
	v_cvt_pk_bf16_f32 v0, v0, v1
	v_cvt_pk_bf16_f32 v1, v2, v3
	global_store_dwordx2 v[6:7], v[0:1], off
	s_cbranch_scc1 .LBB0_1654

.LBB0_1706:
	s_and_b32 s0, s12, 7
	v_readlane_b32 s8, v180, 8
	s_mul_i32 s0, s0, s8
	s_ashr_i32 s1, s12, 3
	s_add_i32 s0, s0, s1
	s_ashr_i32 s1, s0, 31
	s_lshr_b32 s1, s1, 26
	s_add_i32 s1, s0, s1
	s_ashr_i32 s6, s1, 6
	s_lshl_b32 s6, s6, 3
	s_sub_i32 s8, s8, s6
	s_min_i32 s8, s8, 8
	s_abs_i32 s9, s8
	v_cvt_f32_u32_e32 v0, s9
	s_sub_i32 s11, 0, s9
	s_andn2_b32 s1, s1, 63
	s_sub_i32 s0, s0, s1
	v_rcp_iflag_f32_e32 v0, v0
	s_abs_i32 s1, s0
	s_xor_b32 s10, s0, s8
	s_ashr_i32 s10, s10, 31
	v_mul_f32_e32 v0, 0x4f7ffffe, v0
	v_cvt_u32_f32_e32 v0, v0
	v_add_u32_e32 v6, 0x1000, v68
	s_mov_b64 s[22:23], 0x40000
	s_mov_b64 s[36:37], 0x60000
	v_readfirstlane_b32 s13, v0
	s_mul_i32 s11, s11, s13
	s_mul_hi_u32 s11, s13, s11
	s_add_i32 s13, s13, s11
	s_mul_hi_u32 s11, s1, s13
	s_mul_i32 s13, s11, s9
	s_sub_i32 s1, s1, s13
	s_add_i32 s18, s11, 1
	s_sub_i32 s13, s1, s9
	s_cmp_ge_u32 s1, s9
	s_cselect_b32 s11, s18, s11
	s_cselect_b32 s1, s13, s1
	s_add_i32 s13, s11, 1
	s_cmp_ge_u32 s1, s9
	s_cselect_b32 s1, s13, s11
	s_xor_b32 s1, s1, s10
	s_sub_i32 s9, s1, s10
	s_mul_i32 s1, s9, s8
	s_sub_i32 s0, s0, s1
	s_add_i32 s1, s6, s0
	s_lshl_b32 s24, s1, 7
	s_ashr_i32 s25, s24, 31
	s_lshl_b32 s20, s9, 7
	s_lshl_b64 s[8:9], s[24:25], 12
	v_readfirstlane_b32 s0, v68
	v_lshl_add_u64 v[0:1], v[72:73], 0, s[8:9]
	s_mov_b32 m0, s0
	v_readfirstlane_b32 s0, v6
	v_add_u32_e32 v6, 0x2000, v68
	s_setprio 3
	global_load_lds_dwordx4 v[0:1], off
	v_lshl_add_u64 v[4:5], v[0:1], 0, s[28:29]
	s_mov_b32 m0, s0
	v_readfirstlane_b32 s0, v6
	global_load_lds_dwordx4 v[4:5], off
	v_lshl_add_u64 v[4:5], v[0:1], 0, s[22:23]
	s_mov_b32 m0, s0
	v_lshl_add_u64 v[0:1], v[0:1], 0, s[36:37]
	global_load_lds_dwordx4 v[4:5], off
	v_add_u32_e32 v4, 0x3000, v68
	s_ashr_i32 s21, s20, 31
	v_readfirstlane_b32 s0, v4
	s_mov_b32 m0, s0
	s_lshl_b64 s[10:11], s[20:21], 12
	global_load_lds_dwordx4 v[0:1], off
	v_add_u32_e32 v0, 0x8000, v68
	v_add_u32_e32 v4, 0x9000, v68
	v_readfirstlane_b32 s0, v0
	v_lshl_add_u64 v[2:3], v[74:75], 0, s[10:11]
	s_mov_b32 m0, s0
	v_readfirstlane_b32 s0, v4
	v_add_u32_e32 v4, 0xa000, v68
	global_load_lds_dwordx4 v[2:3], off
	v_lshl_add_u64 v[0:1], v[2:3], 0, s[28:29]
	s_mov_b32 m0, s0
	v_readfirstlane_b32 s0, v4
	global_load_lds_dwordx4 v[0:1], off
	v_lshl_add_u64 v[0:1], v[2:3], 0, s[22:23]
	s_mov_b32 m0, s0
	v_lshl_add_u64 v[86:87], v[84:85], 0, s[8:9]
	global_load_lds_dwordx4 v[0:1], off
	v_lshl_add_u64 v[0:1], v[2:3], 0, s[36:37]
	v_add_u32_e32 v2, 0xb000, v68
	v_lshl_add_u64 v[88:89], v[84:85], 0, s[10:11]
	v_readfirstlane_b32 s0, v2
	s_mov_b32 m0, s0
	s_mov_b32 s0, 0
	global_load_lds_dwordx4 v[0:1], off
	s_setprio 0
	s_waitcnt vmcnt(0)
	v_mov_b32_e32 v0, 0
	s_mov_b64 s[36:37], 0
	v_mov_b32_e32 v1, v0
	v_mov_b32_e32 v2, v0
	v_mov_b32_e32 v3, v0
	v_mov_b32_e32 v4, v0
	v_mov_b32_e32 v5, v0
	v_mov_b32_e32 v6, v0
	v_mov_b32_e32 v7, v0
	v_mov_b32_e32 v8, v0
	v_mov_b32_e32 v9, v0
	v_mov_b32_e32 v10, v0
	v_mov_b32_e32 v11, v0
	v_mov_b32_e32 v12, v0
	v_mov_b32_e32 v13, v0
	v_mov_b32_e32 v14, v0
	v_mov_b32_e32 v15, v0
	v_mov_b32_e32 v16, v0
	v_mov_b32_e32 v17, v0
	v_mov_b32_e32 v18, v0
	v_mov_b32_e32 v19, v0
	v_mov_b32_e32 v20, v0
	v_mov_b32_e32 v21, v0
	v_mov_b32_e32 v22, v0
	v_mov_b32_e32 v23, v0
	v_mov_b32_e32 v24, v0
	v_mov_b32_e32 v25, v0
	v_mov_b32_e32 v26, v0
	v_mov_b32_e32 v27, v0
	v_mov_b32_e32 v28, v0
	v_mov_b32_e32 v29, v0
	v_mov_b32_e32 v30, v0
	v_mov_b32_e32 v31, v0
	v_mov_b32_e32 v32, v0
	v_mov_b32_e32 v33, v0
	v_mov_b32_e32 v34, v0
	v_mov_b32_e32 v35, v0
	v_mov_b32_e32 v36, v0
	v_mov_b32_e32 v37, v0
	v_mov_b32_e32 v38, v0
	v_mov_b32_e32 v39, v0
	v_mov_b32_e32 v40, v0
	v_mov_b32_e32 v41, v0
	v_mov_b32_e32 v42, v0
	v_mov_b32_e32 v43, v0
	v_mov_b32_e32 v44, v0
	v_mov_b32_e32 v45, v0
	v_mov_b32_e32 v46, v0
	v_mov_b32_e32 v47, v0
	v_mov_b32_e32 v48, v0
	v_mov_b32_e32 v49, v0
	v_mov_b32_e32 v50, v0
	v_mov_b32_e32 v51, v0
	v_mov_b32_e32 v52, v0
	v_mov_b32_e32 v53, v0
	v_mov_b32_e32 v54, v0
	v_mov_b32_e32 v55, v0
	v_mov_b32_e32 v56, v0
	v_mov_b32_e32 v57, v0
	v_mov_b32_e32 v58, v0
	v_mov_b32_e32 v59, v0
	v_mov_b32_e32 v60, v0
	v_mov_b32_e32 v61, v0
	v_mov_b32_e32 v62, v0
	v_mov_b32_e32 v63, v0
	v_lshl_add_u64 v[98:99], v[86:87], 0, s[36:37]
	s_mov_b64 s[8:9], 0x7100080
	v_lshl_add_u64 v[100:101], v[98:99], 0, s[8:9]
	s_mov_b64 s[8:9], 0x7120080
	v_mov_b32_e32 v184, v100
	v_mov_b32_e32 v185, v101
	v_lshl_add_u64 v[100:101], v[98:99], 0, s[8:9]
	s_mov_b64 s[8:9], 0x7140080
	v_mov_b32_e32 v186, v100
	v_mov_b32_e32 v187, v101
	v_lshl_add_u64 v[100:101], v[98:99], 0, s[8:9]
	s_mov_b64 s[8:9], 0x7160080
	v_mov_b32_e32 v188, v100
	v_mov_b32_e32 v189, v101
	v_lshl_add_u64 v[98:99], v[98:99], 0, s[8:9]
	s_mov_b64 s[8:9], 0x2c00080
	v_mov_b32_e32 v190, v98
	v_mov_b32_e32 v191, v99
	v_lshl_add_u64 v[98:99], v[88:89], 0, s[36:37]
	v_lshl_add_u64 v[100:101], v[98:99], 0, s[8:9]
	s_mov_b64 s[8:9], 0x2c20080
	v_mov_b32_e32 v192, v100
	v_mov_b32_e32 v193, v101
	v_lshl_add_u64 v[100:101], v[98:99], 0, s[8:9]
	s_mov_b64 s[8:9], 0x2c40080
	v_mov_b32_e32 v194, v100
	v_mov_b32_e32 v195, v101
	v_lshl_add_u64 v[100:101], v[98:99], 0, s[8:9]
	s_mov_b64 s[8:9], 0x2c60080
	v_mov_b32_e32 v196, v100
	v_mov_b32_e32 v197, v101
	v_lshl_add_u64 v[98:99], v[98:99], 0, s[8:9]
	v_mov_b32_e32 v198, v98
	v_mov_b32_e32 v199, v99
	v_readfirstlane_b32 s100, v68
	s_mov_b64 vcc, 0x80
	s_waitcnt vmcnt(0) lgkmcnt(0)
	s_barrier
